# v30 + hand-written pipelined state scan (LDS decay table) + band-only workgroups hand 4 of their 10 c1 items to the scan workgroups (work shift so both classes finish the scan+band phase together)
# speedup vs baseline: 1.0039x; 1.0039x over previous
; __device__ __forceinline__ void phase_scan(const Params& P, int tid) {
;     const int gt = blockIdx.x * 512 + tid, NT = gridDim.x * 512;
;     for (int idx = gt; idx < 49152 + 20480; idx += NT) {
;         if (idx < 49152) {
;             const int bh = idx >> 12, e = (idx & 4095) * 4, b = bh / 6, h = bh % 6, k = e & 127;
;             bf16_t* sp = (bf16_t*)(P.ws + WS_STA) + (size_t)(b * 256 * 6 + h) * 16384 + e;
;             const float* dp = (const float*)(P.ws + WS_DEC) + (size_t)(b * 256 * 6 + h) * 128 + k;
;             f32x4 S = (f32x4){0.f, 0.f, 0.f, 0.f};
;             for (int n0 = 0; n0 < 256; n0 += 16) {
;                 u32x2 d[16]; f32x4 dc[16];
; #pragma unroll
;                 for (int j = 0; j < 16; ++j) { d[j] = *(const u32x2*)(sp + (size_t)(n0 + j) * (6 * 16384)); dc[j] = *(const f32x4*)(dp + (size_t)(n0 + j) * 768); }
.LBB0_127:
	v_add_u32_e32 v72, s68, v150
	v_cmp_lt_i32_e32 vcc, s78, v72
	s_and_saveexec_b64 s[0:1], vcc
	s_xor_b64 s[0:1], exec, s[0:1]
	v_readlane_b32 s28, v248, 56
	v_lshlrev_b32_e32 v189, 2, v150
	s_andn2_saveexec_b64 s[12:13], s[0:1]
	s_cbranch_execz .LBB0_139
	v_lshlrev_b32_e32 v189, 2, v150
	v_lshlrev_b32_e32 v0, 3, v150
	v_mov_b32_e32 v2, 0
	v_mov_b32_e32 v3, 0
	v_mov_b32_e32 v4, 0
	v_mov_b32_e32 v5, 0
	s_cmp_lt_u32 s68, 0xc000
	s_cbranch_scc0 .Lscan_c
	s_lshr_b32 s0, s68, 12
	s_lshr_b32 s8, s68, 9
	s_add_u32 s8, s8, s0
	s_and_b32 s8, s8, 7
	s_lshl_b32 s8, s8, 12
	s_cmp_gt_u32 s0, 5
	s_cselect_b32 s1, 0x5fa, 0
	s_add_u32 s0, s0, s1
	s_mov_b32 s1, s8
	s_lshl_b32 s14, s0, 15
	s_add_u32 s14, s14, s1
	s_add_u32 s14, s14, s22
	s_addc_u32 s15, s23, 0
	s_add_u32 s14, s14, 0x2ac00000
	s_addc_u32 s15, s15, 0
	s_add_u32 s14, s14, s36
	s_addc_u32 s15, s15, s37
	s_mov_b64 s[40:41], s[14:15]
	s_lshl_b32 s18, s0, 9
	s_add_u32 s18, s18, s22
	s_addc_u32 s19, s23, 0
	s_add_u32 s18, s18, 0x33400000
	s_addc_u32 s19, s19, 0
	s_add_u32 s18, s18, s36
	s_addc_u32 s19, s19, s37
	v_lshrrev_b32_e32 v6, 6, v150
	v_and_b32_e32 v1, 31, v150
	v_bfe_u32 v7, v150, 5, 1
	v_readfirstlane_b32 s0, v6
	v_lshlrev_b32_e32 v1, 4, v1
	v_mul_u32_u24_e32 v7, 0xc00, v7
	s_lshl_b32 s1, s0, 14
	s_mul_i32 s0, s0, 0x18000
	v_add_u32_e32 v6, v7, v1
	s_add_u32 s18, s18, s0
	s_addc_u32 s19, s19, 0
	s_add_u32 m0, s1, 0x0
	s_nop 0
	global_load_lds_dwordx4 v6, s[18:19]
	s_add_u32 s18, s18, 0x1800
	s_addc_u32 s19, s19, 0
	s_add_u32 m0, s1, 0x400
	s_nop 0
	global_load_lds_dwordx4 v6, s[18:19]
	s_add_u32 s18, s18, 0x1800
	s_addc_u32 s19, s19, 0
	s_add_u32 m0, s1, 0x800
	s_nop 0
	global_load_lds_dwordx4 v6, s[18:19]
	s_add_u32 s18, s18, 0x1800
	s_addc_u32 s19, s19, 0
	s_add_u32 m0, s1, 0xc00
	s_nop 0
	global_load_lds_dwordx4 v6, s[18:19]
	s_add_u32 s18, s18, 0x1800
	s_addc_u32 s19, s19, 0
	s_add_u32 m0, s1, 0x1000
	s_nop 0
	global_load_lds_dwordx4 v6, s[18:19]
	s_add_u32 s18, s18, 0x1800
	s_addc_u32 s19, s19, 0
	s_add_u32 m0, s1, 0x1400
	s_nop 0
	global_load_lds_dwordx4 v6, s[18:19]
	s_add_u32 s18, s18, 0x1800
	s_addc_u32 s19, s19, 0
	s_add_u32 m0, s1, 0x1800
	s_nop 0
	global_load_lds_dwordx4 v6, s[18:19]
	s_add_u32 s18, s18, 0x1800
	s_addc_u32 s19, s19, 0
	s_add_u32 m0, s1, 0x1c00
	s_nop 0
	global_load_lds_dwordx4 v6, s[18:19]
	s_add_u32 s18, s18, 0x1800
	s_addc_u32 s19, s19, 0
	s_add_u32 m0, s1, 0x2000
	s_nop 0
	global_load_lds_dwordx4 v6, s[18:19]
	s_add_u32 s18, s18, 0x1800
	s_addc_u32 s19, s19, 0
	s_add_u32 m0, s1, 0x2400
	s_nop 0
	global_load_lds_dwordx4 v6, s[18:19]
	s_add_u32 s18, s18, 0x1800
	s_addc_u32 s19, s19, 0
	s_add_u32 m0, s1, 0x2800
	s_nop 0
	global_load_lds_dwordx4 v6, s[18:19]
	s_add_u32 s18, s18, 0x1800
	s_addc_u32 s19, s19, 0
	s_add_u32 m0, s1, 0x2c00
	s_nop 0
	global_load_lds_dwordx4 v6, s[18:19]
	s_add_u32 s18, s18, 0x1800
	s_addc_u32 s19, s19, 0
	s_add_u32 m0, s1, 0x3000
	s_nop 0
	global_load_lds_dwordx4 v6, s[18:19]
	s_add_u32 s18, s18, 0x1800
	s_addc_u32 s19, s19, 0
	s_add_u32 m0, s1, 0x3400
	s_nop 0
	global_load_lds_dwordx4 v6, s[18:19]
	s_add_u32 s18, s18, 0x1800
	s_addc_u32 s19, s19, 0
	s_add_u32 m0, s1, 0x3800
	s_nop 0
	global_load_lds_dwordx4 v6, s[18:19]
	s_add_u32 s18, s18, 0x1800
	s_addc_u32 s19, s19, 0
	s_add_u32 m0, s1, 0x3c00
	s_nop 0
	global_load_lds_dwordx4 v6, s[18:19]
	s_add_u32 s18, s18, 0x1800
	s_addc_u32 s19, s19, 0
	global_load_dwordx2 v[14:15], v0, s[14:15]
	s_add_u32 s14, s14, 0x30000
	s_addc_u32 s15, s15, 0
	global_load_dwordx2 v[16:17], v0, s[14:15]
	s_add_u32 s14, s14, 0x30000
	s_addc_u32 s15, s15, 0
	global_load_dwordx2 v[18:19], v0, s[14:15]
	s_add_u32 s14, s14, 0x30000
	s_addc_u32 s15, s15, 0
	global_load_dwordx2 v[20:21], v0, s[14:15]
	s_add_u32 s14, s14, 0x30000
	s_addc_u32 s15, s15, 0
	global_load_dwordx2 v[22:23], v0, s[14:15]
	s_add_u32 s14, s14, 0x30000
	s_addc_u32 s15, s15, 0
	global_load_dwordx2 v[24:25], v0, s[14:15]
	s_add_u32 s14, s14, 0x30000
	s_addc_u32 s15, s15, 0
	global_load_dwordx2 v[26:27], v0, s[14:15]
	s_add_u32 s14, s14, 0x30000
	s_addc_u32 s15, s15, 0
	global_load_dwordx2 v[28:29], v0, s[14:15]
	s_add_u32 s14, s14, 0x30000
	s_addc_u32 s15, s15, 0
	global_load_dwordx2 v[30:31], v0, s[14:15]
	s_add_u32 s14, s14, 0x30000
	s_addc_u32 s15, s15, 0
	global_load_dwordx2 v[32:33], v0, s[14:15]
	s_add_u32 s14, s14, 0x30000
	s_addc_u32 s15, s15, 0
	global_load_dwordx2 v[34:35], v0, s[14:15]
	s_add_u32 s14, s14, 0x30000
	s_addc_u32 s15, s15, 0
	global_load_dwordx2 v[36:37], v0, s[14:15]
	s_add_u32 s14, s14, 0x30000
	s_addc_u32 s15, s15, 0
	global_load_dwordx2 v[38:39], v0, s[14:15]
	s_add_u32 s14, s14, 0x30000
	s_addc_u32 s15, s15, 0
	global_load_dwordx2 v[40:41], v0, s[14:15]
	s_add_u32 s14, s14, 0x30000
	s_addc_u32 s15, s15, 0
	global_load_dwordx2 v[42:43], v0, s[14:15]
	s_add_u32 s14, s14, 0x30000
	s_addc_u32 s15, s15, 0
	global_load_dwordx2 v[44:45], v0, s[14:15]
	s_add_u32 s14, s14, 0x30000
	s_addc_u32 s15, s15, 0
	global_load_dwordx2 v[46:47], v0, s[14:15]
	s_add_u32 s14, s14, 0x30000
	s_addc_u32 s15, s15, 0
	global_load_dwordx2 v[48:49], v0, s[14:15]
	s_add_u32 s14, s14, 0x30000
	s_addc_u32 s15, s15, 0
	global_load_dwordx2 v[50:51], v0, s[14:15]
	s_add_u32 s14, s14, 0x30000
	s_addc_u32 s15, s15, 0
	global_load_dwordx2 v[52:53], v0, s[14:15]
	s_add_u32 s14, s14, 0x30000
	s_addc_u32 s15, s15, 0
	global_load_dwordx2 v[54:55], v0, s[14:15]
	s_add_u32 s14, s14, 0x30000
	s_addc_u32 s15, s15, 0
	global_load_dwordx2 v[56:57], v0, s[14:15]
	s_add_u32 s14, s14, 0x30000
	s_addc_u32 s15, s15, 0
	global_load_dwordx2 v[58:59], v0, s[14:15]
	s_add_u32 s14, s14, 0x30000
	s_addc_u32 s15, s15, 0
	global_load_dwordx2 v[60:61], v0, s[14:15]
	s_add_u32 s14, s14, 0x30000
	s_addc_u32 s15, s15, 0
	global_load_dwordx2 v[62:63], v0, s[14:15]
	s_add_u32 s14, s14, 0x30000
	s_addc_u32 s15, s15, 0
	global_load_dwordx2 v[64:65], v0, s[14:15]
	s_add_u32 s14, s14, 0x30000
	s_addc_u32 s15, s15, 0
	global_load_dwordx2 v[66:67], v0, s[14:15]
	s_add_u32 s14, s14, 0x30000
	s_addc_u32 s15, s15, 0
	global_load_dwordx2 v[68:69], v0, s[14:15]
	s_add_u32 s14, s14, 0x30000
	s_addc_u32 s15, s15, 0
	global_load_dwordx2 v[70:71], v0, s[14:15]
	s_add_u32 s14, s14, 0x30000
	s_addc_u32 s15, s15, 0
	global_load_dwordx2 v[72:73], v0, s[14:15]
	s_add_u32 s14, s14, 0x30000
	s_addc_u32 s15, s15, 0
	global_load_dwordx2 v[74:75], v0, s[14:15]
	s_add_u32 s14, s14, 0x30000
	s_addc_u32 s15, s15, 0
	global_load_dwordx2 v[76:77], v0, s[14:15]
	s_add_u32 s14, s14, 0x30000
	s_addc_u32 s15, s15, 0
	s_waitcnt vmcnt(32)
	s_barrier
; __device__ __forceinline__ unsigned cvt_pk_bf16(float lo, float hi) { const f32x2 f = {lo, hi}; const bf16x2_t v = __builtin_convertvector(f, bf16x2_t); return __builtin_bit_cast(unsigned, v); }
; __device__ __forceinline__ float bflo(unsigned u) { return __uint_as_float(u << 16); }
; __device__ __forceinline__ float bfhi(unsigned u) { return __uint_as_float(u & 0xffff0000u); }
; __device__ __forceinline__ void phase_scan(const Params& P, int tid) {
;     ...
;             for (int n0 = 0; n0 < 256; n0 += 16) {
;                 u32x2 d[16]; f32x4 dc[16];
; #pragma unroll
;                 for (int j = 0; j < 16; ++j) { d[j] = *(const u32x2*)(sp + (size_t)(n0 + j) * (6 * 16384)); dc[j] = *(const f32x4*)(dp + (size_t)(n0 + j) * 768); }
; #pragma unroll
;                 for (int j = 0; j < 16; ++j) { u32x2 o; o.x = cvt_pk_bf16(S[0], S[1]); o.y = cvt_pk_bf16(S[2], S[3]);
;                     S[0] = dc[j][0] * S[0] + bflo(d[j].x); S[1] = dc[j][1] * S[1] + bfhi(d[j].x); S[2] = dc[j][2] * S[2] + bflo(d[j].y); S[3] = dc[j][3] * S[3] + bfhi(d[j].y);
;                     *(u32x2*)(sp + (size_t)(n0 + j) * (6 * 16384)) = o; }
;             }
	ds_read_b128 v[80:83], v1 offset:0
	ds_read_b128 v[84:87], v1 offset:512
	ds_read_b128 v[88:91], v1 offset:1024
	ds_read_b128 v[92:95], v1 offset:1536
	s_waitcnt vmcnt(31) lgkmcnt(3)
	v_cvt_pk_bf16_f32 v10, v2, v3
	v_cvt_pk_bf16_f32 v11, v4, v5
	v_lshlrev_b32_e32 v6, 16, v14
	v_and_b32_e32 v7, 0xffff0000, v14
	v_lshlrev_b32_e32 v8, 16, v15
	v_and_b32_e32 v9, 0xffff0000, v15
	v_pk_fma_f32 v[2:3], v[2:3], v[80:81], v[6:7]
	v_pk_fma_f32 v[4:5], v[4:5], v[82:83], v[8:9]
	global_store_dwordx2 v0, v[10:11], s[40:41]
	ds_read_b128 v[80:83], v1 offset:2048
	s_add_u32 s40, s40, 0x30000
	s_addc_u32 s41, s41, 0
	global_load_dwordx2 v[14:15], v0, s[14:15]
	s_add_u32 s14, s14, 0x30000
	s_addc_u32 s15, s15, 0
	s_waitcnt vmcnt(32) lgkmcnt(3)
	v_cvt_pk_bf16_f32 v12, v2, v3
	v_cvt_pk_bf16_f32 v13, v4, v5
	v_lshlrev_b32_e32 v6, 16, v16
	v_and_b32_e32 v7, 0xffff0000, v16
	v_lshlrev_b32_e32 v8, 16, v17
	v_and_b32_e32 v9, 0xffff0000, v17
	v_pk_fma_f32 v[2:3], v[2:3], v[84:85], v[6:7]
	v_pk_fma_f32 v[4:5], v[4:5], v[86:87], v[8:9]
	global_store_dwordx2 v0, v[12:13], s[40:41]
	ds_read_b128 v[84:87], v1 offset:2560
	s_add_u32 s40, s40, 0x30000
	s_addc_u32 s41, s41, 0
	global_load_dwordx2 v[16:17], v0, s[14:15]
	s_add_u32 s14, s14, 0x30000
	s_addc_u32 s15, s15, 0
	s_waitcnt vmcnt(33) lgkmcnt(3)
	v_cvt_pk_bf16_f32 v10, v2, v3
	v_cvt_pk_bf16_f32 v11, v4, v5
	v_lshlrev_b32_e32 v6, 16, v18
	v_and_b32_e32 v7, 0xffff0000, v18
	v_lshlrev_b32_e32 v8, 16, v19
	v_and_b32_e32 v9, 0xffff0000, v19
	v_pk_fma_f32 v[2:3], v[2:3], v[88:89], v[6:7]
	v_pk_fma_f32 v[4:5], v[4:5], v[90:91], v[8:9]
	global_store_dwordx2 v0, v[10:11], s[40:41]
	ds_read_b128 v[88:91], v1 offset:3072
	s_add_u32 s40, s40, 0x30000
	s_addc_u32 s41, s41, 0
	global_load_dwordx2 v[18:19], v0, s[14:15]
	s_add_u32 s14, s14, 0x30000
	s_addc_u32 s15, s15, 0
	s_waitcnt vmcnt(34) lgkmcnt(3)
	v_cvt_pk_bf16_f32 v12, v2, v3
	v_cvt_pk_bf16_f32 v13, v4, v5
	v_lshlrev_b32_e32 v6, 16, v20
	v_and_b32_e32 v7, 0xffff0000, v20
	v_lshlrev_b32_e32 v8, 16, v21
	v_and_b32_e32 v9, 0xffff0000, v21
	v_pk_fma_f32 v[2:3], v[2:3], v[92:93], v[6:7]
	v_pk_fma_f32 v[4:5], v[4:5], v[94:95], v[8:9]
	global_store_dwordx2 v0, v[12:13], s[40:41]
	ds_read_b128 v[92:95], v1 offset:3584
	s_add_u32 s40, s40, 0x30000
	s_addc_u32 s41, s41, 0
	global_load_dwordx2 v[20:21], v0, s[14:15]
	s_add_u32 s14, s14, 0x30000
	s_addc_u32 s15, s15, 0
	s_waitcnt vmcnt(35) lgkmcnt(3)
	v_cvt_pk_bf16_f32 v10, v2, v3
	v_cvt_pk_bf16_f32 v11, v4, v5
	v_lshlrev_b32_e32 v6, 16, v22
	v_and_b32_e32 v7, 0xffff0000, v22
	v_lshlrev_b32_e32 v8, 16, v23
	v_and_b32_e32 v9, 0xffff0000, v23
	v_pk_fma_f32 v[2:3], v[2:3], v[80:81], v[6:7]
	v_pk_fma_f32 v[4:5], v[4:5], v[82:83], v[8:9]
	global_store_dwordx2 v0, v[10:11], s[40:41]
	ds_read_b128 v[80:83], v1 offset:4096
	s_add_u32 s40, s40, 0x30000
	s_addc_u32 s41, s41, 0
	global_load_dwordx2 v[22:23], v0, s[14:15]
	s_add_u32 s14, s14, 0x30000
	s_addc_u32 s15, s15, 0
	s_waitcnt vmcnt(36) lgkmcnt(3)
	v_cvt_pk_bf16_f32 v12, v2, v3
	v_cvt_pk_bf16_f32 v13, v4, v5
	v_lshlrev_b32_e32 v6, 16, v24
	v_and_b32_e32 v7, 0xffff0000, v24
	v_lshlrev_b32_e32 v8, 16, v25
	v_and_b32_e32 v9, 0xffff0000, v25
	v_pk_fma_f32 v[2:3], v[2:3], v[84:85], v[6:7]
	v_pk_fma_f32 v[4:5], v[4:5], v[86:87], v[8:9]
	global_store_dwordx2 v0, v[12:13], s[40:41]
	ds_read_b128 v[84:87], v1 offset:4608
	s_add_u32 s40, s40, 0x30000
	s_addc_u32 s41, s41, 0
	global_load_dwordx2 v[24:25], v0, s[14:15]
	s_add_u32 s14, s14, 0x30000
	s_addc_u32 s15, s15, 0
	s_waitcnt vmcnt(37) lgkmcnt(3)
	v_cvt_pk_bf16_f32 v10, v2, v3
	v_cvt_pk_bf16_f32 v11, v4, v5
	v_lshlrev_b32_e32 v6, 16, v26
	v_and_b32_e32 v7, 0xffff0000, v26
	v_lshlrev_b32_e32 v8, 16, v27
	v_and_b32_e32 v9, 0xffff0000, v27
	v_pk_fma_f32 v[2:3], v[2:3], v[88:89], v[6:7]
	v_pk_fma_f32 v[4:5], v[4:5], v[90:91], v[8:9]
	global_store_dwordx2 v0, v[10:11], s[40:41]
	ds_read_b128 v[88:91], v1 offset:5120
	s_add_u32 s40, s40, 0x30000
	s_addc_u32 s41, s41, 0
	global_load_dwordx2 v[26:27], v0, s[14:15]
	s_add_u32 s14, s14, 0x30000
	s_addc_u32 s15, s15, 0
	s_waitcnt vmcnt(38) lgkmcnt(3)
	v_cvt_pk_bf16_f32 v12, v2, v3
	v_cvt_pk_bf16_f32 v13, v4, v5
	v_lshlrev_b32_e32 v6, 16, v28
	v_and_b32_e32 v7, 0xffff0000, v28
	v_lshlrev_b32_e32 v8, 16, v29
	v_and_b32_e32 v9, 0xffff0000, v29
	v_pk_fma_f32 v[2:3], v[2:3], v[92:93], v[6:7]
	v_pk_fma_f32 v[4:5], v[4:5], v[94:95], v[8:9]
	global_store_dwordx2 v0, v[12:13], s[40:41]
	ds_read_b128 v[92:95], v1 offset:5632
	s_add_u32 s40, s40, 0x30000
	s_addc_u32 s41, s41, 0
	global_load_dwordx2 v[28:29], v0, s[14:15]
	s_add_u32 s14, s14, 0x30000
	s_addc_u32 s15, s15, 0
	s_waitcnt vmcnt(39) lgkmcnt(3)
	v_cvt_pk_bf16_f32 v10, v2, v3
	v_cvt_pk_bf16_f32 v11, v4, v5
	v_lshlrev_b32_e32 v6, 16, v30
	v_and_b32_e32 v7, 0xffff0000, v30
	v_lshlrev_b32_e32 v8, 16, v31
	v_and_b32_e32 v9, 0xffff0000, v31
	v_pk_fma_f32 v[2:3], v[2:3], v[80:81], v[6:7]
	v_pk_fma_f32 v[4:5], v[4:5], v[82:83], v[8:9]
	global_store_dwordx2 v0, v[10:11], s[40:41]
	ds_read_b128 v[80:83], v1 offset:6144
	s_add_u32 s40, s40, 0x30000
	s_addc_u32 s41, s41, 0
	global_load_dwordx2 v[30:31], v0, s[14:15]
	s_add_u32 s14, s14, 0x30000
	s_addc_u32 s15, s15, 0
	s_waitcnt vmcnt(40) lgkmcnt(3)
	v_cvt_pk_bf16_f32 v12, v2, v3
	v_cvt_pk_bf16_f32 v13, v4, v5
	v_lshlrev_b32_e32 v6, 16, v32
	v_and_b32_e32 v7, 0xffff0000, v32
	v_lshlrev_b32_e32 v8, 16, v33
	v_and_b32_e32 v9, 0xffff0000, v33
	v_pk_fma_f32 v[2:3], v[2:3], v[84:85], v[6:7]
	v_pk_fma_f32 v[4:5], v[4:5], v[86:87], v[8:9]
	global_store_dwordx2 v0, v[12:13], s[40:41]
	ds_read_b128 v[84:87], v1 offset:6656
	s_add_u32 s40, s40, 0x30000
	s_addc_u32 s41, s41, 0
	global_load_dwordx2 v[32:33], v0, s[14:15]
	s_add_u32 s14, s14, 0x30000
	s_addc_u32 s15, s15, 0
	s_waitcnt vmcnt(41) lgkmcnt(3)
; __device__ __forceinline__ unsigned cvt_pk_bf16(float lo, float hi) { const f32x2 f = {lo, hi}; const bf16x2_t v = __builtin_convertvector(f, bf16x2_t); return __builtin_bit_cast(unsigned, v); }
; __device__ __forceinline__ float bflo(unsigned u) { return __uint_as_float(u << 16); }
; __device__ __forceinline__ float bfhi(unsigned u) { return __uint_as_float(u & 0xffff0000u); }
; __device__ __forceinline__ void phase_scan(const Params& P, int tid) {
;     ...
;             for (int n0 = 0; n0 < 256; n0 += 16) {
;                 u32x2 d[16]; f32x4 dc[16];
; #pragma unroll
;                 for (int j = 0; j < 16; ++j) { d[j] = *(const u32x2*)(sp + (size_t)(n0 + j) * (6 * 16384)); dc[j] = *(const f32x4*)(dp + (size_t)(n0 + j) * 768); }
; #pragma unroll
;                 for (int j = 0; j < 16; ++j) { u32x2 o; o.x = cvt_pk_bf16(S[0], S[1]); o.y = cvt_pk_bf16(S[2], S[3]);
;                     S[0] = dc[j][0] * S[0] + bflo(d[j].x); S[1] = dc[j][1] * S[1] + bfhi(d[j].x); S[2] = dc[j][2] * S[2] + bflo(d[j].y); S[3] = dc[j][3] * S[3] + bfhi(d[j].y);
;                     *(u32x2*)(sp + (size_t)(n0 + j) * (6 * 16384)) = o; }
;             }
	v_cvt_pk_bf16_f32 v10, v2, v3
	v_cvt_pk_bf16_f32 v11, v4, v5
	v_lshlrev_b32_e32 v6, 16, v34
	v_and_b32_e32 v7, 0xffff0000, v34
	v_lshlrev_b32_e32 v8, 16, v35
	v_and_b32_e32 v9, 0xffff0000, v35
	v_pk_fma_f32 v[2:3], v[2:3], v[88:89], v[6:7]
	v_pk_fma_f32 v[4:5], v[4:5], v[90:91], v[8:9]
	global_store_dwordx2 v0, v[10:11], s[40:41]
	ds_read_b128 v[88:91], v1 offset:7168
	s_add_u32 s40, s40, 0x30000
	s_addc_u32 s41, s41, 0
	global_load_dwordx2 v[34:35], v0, s[14:15]
	s_add_u32 s14, s14, 0x30000
	s_addc_u32 s15, s15, 0
	s_waitcnt vmcnt(42) lgkmcnt(3)
	v_cvt_pk_bf16_f32 v12, v2, v3
	v_cvt_pk_bf16_f32 v13, v4, v5
	v_lshlrev_b32_e32 v6, 16, v36
	v_and_b32_e32 v7, 0xffff0000, v36
	v_lshlrev_b32_e32 v8, 16, v37
	v_and_b32_e32 v9, 0xffff0000, v37
	v_pk_fma_f32 v[2:3], v[2:3], v[92:93], v[6:7]
	v_pk_fma_f32 v[4:5], v[4:5], v[94:95], v[8:9]
	global_store_dwordx2 v0, v[12:13], s[40:41]
	ds_read_b128 v[92:95], v1 offset:7680
	s_add_u32 s40, s40, 0x30000
	s_addc_u32 s41, s41, 0
	global_load_dwordx2 v[36:37], v0, s[14:15]
	s_add_u32 s14, s14, 0x30000
	s_addc_u32 s15, s15, 0
	s_waitcnt vmcnt(43) lgkmcnt(3)
	v_cvt_pk_bf16_f32 v10, v2, v3
	v_cvt_pk_bf16_f32 v11, v4, v5
	v_lshlrev_b32_e32 v6, 16, v38
	v_and_b32_e32 v7, 0xffff0000, v38
	v_lshlrev_b32_e32 v8, 16, v39
	v_and_b32_e32 v9, 0xffff0000, v39
	v_pk_fma_f32 v[2:3], v[2:3], v[80:81], v[6:7]
	v_pk_fma_f32 v[4:5], v[4:5], v[82:83], v[8:9]
	global_store_dwordx2 v0, v[10:11], s[40:41]
	ds_read_b128 v[80:83], v1 offset:8192
	s_add_u32 s40, s40, 0x30000
	s_addc_u32 s41, s41, 0
	global_load_dwordx2 v[38:39], v0, s[14:15]
	s_add_u32 s14, s14, 0x30000
	s_addc_u32 s15, s15, 0
	s_waitcnt vmcnt(44) lgkmcnt(3)
	v_cvt_pk_bf16_f32 v12, v2, v3
	v_cvt_pk_bf16_f32 v13, v4, v5
	v_lshlrev_b32_e32 v6, 16, v40
	v_and_b32_e32 v7, 0xffff0000, v40
	v_lshlrev_b32_e32 v8, 16, v41
	v_and_b32_e32 v9, 0xffff0000, v41
	v_pk_fma_f32 v[2:3], v[2:3], v[84:85], v[6:7]
	v_pk_fma_f32 v[4:5], v[4:5], v[86:87], v[8:9]
	global_store_dwordx2 v0, v[12:13], s[40:41]
	ds_read_b128 v[84:87], v1 offset:8704
	s_add_u32 s40, s40, 0x30000
	s_addc_u32 s41, s41, 0
	global_load_dwordx2 v[40:41], v0, s[14:15]
	s_add_u32 s14, s14, 0x30000
	s_addc_u32 s15, s15, 0
	s_waitcnt vmcnt(45) lgkmcnt(3)
	v_cvt_pk_bf16_f32 v10, v2, v3
	v_cvt_pk_bf16_f32 v11, v4, v5
	v_lshlrev_b32_e32 v6, 16, v42
	v_and_b32_e32 v7, 0xffff0000, v42
	v_lshlrev_b32_e32 v8, 16, v43
	v_and_b32_e32 v9, 0xffff0000, v43
	v_pk_fma_f32 v[2:3], v[2:3], v[88:89], v[6:7]
	v_pk_fma_f32 v[4:5], v[4:5], v[90:91], v[8:9]
	global_store_dwordx2 v0, v[10:11], s[40:41]
	ds_read_b128 v[88:91], v1 offset:9216
	s_add_u32 s40, s40, 0x30000
	s_addc_u32 s41, s41, 0
	global_load_dwordx2 v[42:43], v0, s[14:15]
	s_add_u32 s14, s14, 0x30000
	s_addc_u32 s15, s15, 0
	s_waitcnt vmcnt(46) lgkmcnt(3)
	v_cvt_pk_bf16_f32 v12, v2, v3
	v_cvt_pk_bf16_f32 v13, v4, v5
	v_lshlrev_b32_e32 v6, 16, v44
	v_and_b32_e32 v7, 0xffff0000, v44
	v_lshlrev_b32_e32 v8, 16, v45
	v_and_b32_e32 v9, 0xffff0000, v45
	v_pk_fma_f32 v[2:3], v[2:3], v[92:93], v[6:7]
	v_pk_fma_f32 v[4:5], v[4:5], v[94:95], v[8:9]
	global_store_dwordx2 v0, v[12:13], s[40:41]
	ds_read_b128 v[92:95], v1 offset:9728
	s_add_u32 s40, s40, 0x30000
	s_addc_u32 s41, s41, 0
	global_load_dwordx2 v[44:45], v0, s[14:15]
	s_add_u32 s14, s14, 0x30000
	s_addc_u32 s15, s15, 0
	s_waitcnt vmcnt(47) lgkmcnt(3)
	v_cvt_pk_bf16_f32 v10, v2, v3
	v_cvt_pk_bf16_f32 v11, v4, v5
	v_lshlrev_b32_e32 v6, 16, v46
	v_and_b32_e32 v7, 0xffff0000, v46
	v_lshlrev_b32_e32 v8, 16, v47
	v_and_b32_e32 v9, 0xffff0000, v47
	v_pk_fma_f32 v[2:3], v[2:3], v[80:81], v[6:7]
	v_pk_fma_f32 v[4:5], v[4:5], v[82:83], v[8:9]
	global_store_dwordx2 v0, v[10:11], s[40:41]
	ds_read_b128 v[80:83], v1 offset:10240
	s_add_u32 s40, s40, 0x30000
	s_addc_u32 s41, s41, 0
	global_load_dwordx2 v[46:47], v0, s[14:15]
	s_add_u32 s14, s14, 0x30000
	s_addc_u32 s15, s15, 0
	s_waitcnt vmcnt(48) lgkmcnt(3)
	v_cvt_pk_bf16_f32 v12, v2, v3
	v_cvt_pk_bf16_f32 v13, v4, v5
	v_lshlrev_b32_e32 v6, 16, v48
	v_and_b32_e32 v7, 0xffff0000, v48
	v_lshlrev_b32_e32 v8, 16, v49
	v_and_b32_e32 v9, 0xffff0000, v49
	v_pk_fma_f32 v[2:3], v[2:3], v[84:85], v[6:7]
	v_pk_fma_f32 v[4:5], v[4:5], v[86:87], v[8:9]
	global_store_dwordx2 v0, v[12:13], s[40:41]
	ds_read_b128 v[84:87], v1 offset:10752
	s_add_u32 s40, s40, 0x30000
	s_addc_u32 s41, s41, 0
	global_load_dwordx2 v[48:49], v0, s[14:15]
	s_add_u32 s14, s14, 0x30000
	s_addc_u32 s15, s15, 0
	s_waitcnt vmcnt(49) lgkmcnt(3)
	v_cvt_pk_bf16_f32 v10, v2, v3
	v_cvt_pk_bf16_f32 v11, v4, v5
	v_lshlrev_b32_e32 v6, 16, v50
	v_and_b32_e32 v7, 0xffff0000, v50
	v_lshlrev_b32_e32 v8, 16, v51
	v_and_b32_e32 v9, 0xffff0000, v51
	v_pk_fma_f32 v[2:3], v[2:3], v[88:89], v[6:7]
	v_pk_fma_f32 v[4:5], v[4:5], v[90:91], v[8:9]
	global_store_dwordx2 v0, v[10:11], s[40:41]
	ds_read_b128 v[88:91], v1 offset:11264
	s_add_u32 s40, s40, 0x30000
	s_addc_u32 s41, s41, 0
	global_load_dwordx2 v[50:51], v0, s[14:15]
	s_add_u32 s14, s14, 0x30000
	s_addc_u32 s15, s15, 0
	s_waitcnt vmcnt(50) lgkmcnt(3)
	v_cvt_pk_bf16_f32 v12, v2, v3
	v_cvt_pk_bf16_f32 v13, v4, v5
	v_lshlrev_b32_e32 v6, 16, v52
	v_and_b32_e32 v7, 0xffff0000, v52
	v_lshlrev_b32_e32 v8, 16, v53
	v_and_b32_e32 v9, 0xffff0000, v53
	v_pk_fma_f32 v[2:3], v[2:3], v[92:93], v[6:7]
	v_pk_fma_f32 v[4:5], v[4:5], v[94:95], v[8:9]
	global_store_dwordx2 v0, v[12:13], s[40:41]
	ds_read_b128 v[92:95], v1 offset:11776
	s_add_u32 s40, s40, 0x30000
	s_addc_u32 s41, s41, 0
	global_load_dwordx2 v[52:53], v0, s[14:15]
	s_add_u32 s14, s14, 0x30000
	s_addc_u32 s15, s15, 0
	s_waitcnt vmcnt(51) lgkmcnt(3)
; __device__ __forceinline__ unsigned cvt_pk_bf16(float lo, float hi) { const f32x2 f = {lo, hi}; const bf16x2_t v = __builtin_convertvector(f, bf16x2_t); return __builtin_bit_cast(unsigned, v); }
; __device__ __forceinline__ float bflo(unsigned u) { return __uint_as_float(u << 16); }
; __device__ __forceinline__ float bfhi(unsigned u) { return __uint_as_float(u & 0xffff0000u); }
; __device__ __forceinline__ void phase_scan(const Params& P, int tid) {
;     ...
;             for (int n0 = 0; n0 < 256; n0 += 16) {
;                 u32x2 d[16]; f32x4 dc[16];
; #pragma unroll
;                 for (int j = 0; j < 16; ++j) { d[j] = *(const u32x2*)(sp + (size_t)(n0 + j) * (6 * 16384)); dc[j] = *(const f32x4*)(dp + (size_t)(n0 + j) * 768); }
; #pragma unroll
;                 for (int j = 0; j < 16; ++j) { u32x2 o; o.x = cvt_pk_bf16(S[0], S[1]); o.y = cvt_pk_bf16(S[2], S[3]);
;                     S[0] = dc[j][0] * S[0] + bflo(d[j].x); S[1] = dc[j][1] * S[1] + bfhi(d[j].x); S[2] = dc[j][2] * S[2] + bflo(d[j].y); S[3] = dc[j][3] * S[3] + bfhi(d[j].y);
;                     *(u32x2*)(sp + (size_t)(n0 + j) * (6 * 16384)) = o; }
;             }
	v_cvt_pk_bf16_f32 v10, v2, v3
	v_cvt_pk_bf16_f32 v11, v4, v5
	v_lshlrev_b32_e32 v6, 16, v54
	v_and_b32_e32 v7, 0xffff0000, v54
	v_lshlrev_b32_e32 v8, 16, v55
	v_and_b32_e32 v9, 0xffff0000, v55
	v_pk_fma_f32 v[2:3], v[2:3], v[80:81], v[6:7]
	v_pk_fma_f32 v[4:5], v[4:5], v[82:83], v[8:9]
	global_store_dwordx2 v0, v[10:11], s[40:41]
	ds_read_b128 v[80:83], v1 offset:12288
	s_add_u32 s40, s40, 0x30000
	s_addc_u32 s41, s41, 0
	global_load_dwordx2 v[54:55], v0, s[14:15]
	s_add_u32 s14, s14, 0x30000
	s_addc_u32 s15, s15, 0
	s_waitcnt vmcnt(52) lgkmcnt(3)
	v_cvt_pk_bf16_f32 v12, v2, v3
	v_cvt_pk_bf16_f32 v13, v4, v5
	v_lshlrev_b32_e32 v6, 16, v56
	v_and_b32_e32 v7, 0xffff0000, v56
	v_lshlrev_b32_e32 v8, 16, v57
	v_and_b32_e32 v9, 0xffff0000, v57
	v_pk_fma_f32 v[2:3], v[2:3], v[84:85], v[6:7]
	v_pk_fma_f32 v[4:5], v[4:5], v[86:87], v[8:9]
	global_store_dwordx2 v0, v[12:13], s[40:41]
	ds_read_b128 v[84:87], v1 offset:12800
	s_add_u32 s40, s40, 0x30000
	s_addc_u32 s41, s41, 0
	global_load_dwordx2 v[56:57], v0, s[14:15]
	s_add_u32 s14, s14, 0x30000
	s_addc_u32 s15, s15, 0
	s_waitcnt vmcnt(53) lgkmcnt(3)
	v_cvt_pk_bf16_f32 v10, v2, v3
	v_cvt_pk_bf16_f32 v11, v4, v5
	v_lshlrev_b32_e32 v6, 16, v58
	v_and_b32_e32 v7, 0xffff0000, v58
	v_lshlrev_b32_e32 v8, 16, v59
	v_and_b32_e32 v9, 0xffff0000, v59
	v_pk_fma_f32 v[2:3], v[2:3], v[88:89], v[6:7]
	v_pk_fma_f32 v[4:5], v[4:5], v[90:91], v[8:9]
	global_store_dwordx2 v0, v[10:11], s[40:41]
	ds_read_b128 v[88:91], v1 offset:13312
	s_add_u32 s40, s40, 0x30000
	s_addc_u32 s41, s41, 0
	global_load_dwordx2 v[58:59], v0, s[14:15]
	s_add_u32 s14, s14, 0x30000
	s_addc_u32 s15, s15, 0
	s_waitcnt vmcnt(54) lgkmcnt(3)
	v_cvt_pk_bf16_f32 v12, v2, v3
	v_cvt_pk_bf16_f32 v13, v4, v5
	v_lshlrev_b32_e32 v6, 16, v60
	v_and_b32_e32 v7, 0xffff0000, v60
	v_lshlrev_b32_e32 v8, 16, v61
	v_and_b32_e32 v9, 0xffff0000, v61
	v_pk_fma_f32 v[2:3], v[2:3], v[92:93], v[6:7]
	v_pk_fma_f32 v[4:5], v[4:5], v[94:95], v[8:9]
	global_store_dwordx2 v0, v[12:13], s[40:41]
	ds_read_b128 v[92:95], v1 offset:13824
	s_add_u32 s40, s40, 0x30000
	s_addc_u32 s41, s41, 0
	global_load_dwordx2 v[60:61], v0, s[14:15]
	s_add_u32 s14, s14, 0x30000
	s_addc_u32 s15, s15, 0
	s_waitcnt vmcnt(55) lgkmcnt(3)
	v_cvt_pk_bf16_f32 v10, v2, v3
	v_cvt_pk_bf16_f32 v11, v4, v5
	v_lshlrev_b32_e32 v6, 16, v62
	v_and_b32_e32 v7, 0xffff0000, v62
	v_lshlrev_b32_e32 v8, 16, v63
	v_and_b32_e32 v9, 0xffff0000, v63
	v_pk_fma_f32 v[2:3], v[2:3], v[80:81], v[6:7]
	v_pk_fma_f32 v[4:5], v[4:5], v[82:83], v[8:9]
	global_store_dwordx2 v0, v[10:11], s[40:41]
	ds_read_b128 v[80:83], v1 offset:14336
	s_add_u32 s40, s40, 0x30000
	s_addc_u32 s41, s41, 0
	global_load_dwordx2 v[62:63], v0, s[14:15]
	s_add_u32 s14, s14, 0x30000
	s_addc_u32 s15, s15, 0
	s_waitcnt vmcnt(56) lgkmcnt(3)
	v_cvt_pk_bf16_f32 v12, v2, v3
	v_cvt_pk_bf16_f32 v13, v4, v5
	v_lshlrev_b32_e32 v6, 16, v64
	v_and_b32_e32 v7, 0xffff0000, v64
	v_lshlrev_b32_e32 v8, 16, v65
	v_and_b32_e32 v9, 0xffff0000, v65
	v_pk_fma_f32 v[2:3], v[2:3], v[84:85], v[6:7]
	v_pk_fma_f32 v[4:5], v[4:5], v[86:87], v[8:9]
	global_store_dwordx2 v0, v[12:13], s[40:41]
	ds_read_b128 v[84:87], v1 offset:14848
	s_add_u32 s40, s40, 0x30000
	s_addc_u32 s41, s41, 0
	global_load_dwordx2 v[64:65], v0, s[14:15]
	s_add_u32 s14, s14, 0x30000
	s_addc_u32 s15, s15, 0
	s_waitcnt vmcnt(57) lgkmcnt(3)
	v_cvt_pk_bf16_f32 v10, v2, v3
	v_cvt_pk_bf16_f32 v11, v4, v5
	v_lshlrev_b32_e32 v6, 16, v66
	v_and_b32_e32 v7, 0xffff0000, v66
	v_lshlrev_b32_e32 v8, 16, v67
	v_and_b32_e32 v9, 0xffff0000, v67
	v_pk_fma_f32 v[2:3], v[2:3], v[88:89], v[6:7]
	v_pk_fma_f32 v[4:5], v[4:5], v[90:91], v[8:9]
	global_store_dwordx2 v0, v[10:11], s[40:41]
	ds_read_b128 v[88:91], v1 offset:15360
	s_add_u32 s40, s40, 0x30000
	s_addc_u32 s41, s41, 0
	global_load_dwordx2 v[66:67], v0, s[14:15]
	s_add_u32 s14, s14, 0x30000
	s_addc_u32 s15, s15, 0
	s_waitcnt vmcnt(58) lgkmcnt(3)
	v_cvt_pk_bf16_f32 v12, v2, v3
	v_cvt_pk_bf16_f32 v13, v4, v5
	v_lshlrev_b32_e32 v6, 16, v68
	v_and_b32_e32 v7, 0xffff0000, v68
	v_lshlrev_b32_e32 v8, 16, v69
	v_and_b32_e32 v9, 0xffff0000, v69
	v_pk_fma_f32 v[2:3], v[2:3], v[92:93], v[6:7]
	v_pk_fma_f32 v[4:5], v[4:5], v[94:95], v[8:9]
	global_store_dwordx2 v0, v[12:13], s[40:41]
	ds_read_b128 v[92:95], v1 offset:15872
	s_add_u32 s40, s40, 0x30000
	s_addc_u32 s41, s41, 0
	global_load_dwordx2 v[68:69], v0, s[14:15]
	s_add_u32 s14, s14, 0x30000
	s_addc_u32 s15, s15, 0
	s_waitcnt vmcnt(59) lgkmcnt(3)
	v_cvt_pk_bf16_f32 v10, v2, v3
	v_cvt_pk_bf16_f32 v11, v4, v5
	v_lshlrev_b32_e32 v6, 16, v70
	v_and_b32_e32 v7, 0xffff0000, v70
	v_lshlrev_b32_e32 v8, 16, v71
	v_and_b32_e32 v9, 0xffff0000, v71
	v_pk_fma_f32 v[2:3], v[2:3], v[80:81], v[6:7]
	v_pk_fma_f32 v[4:5], v[4:5], v[82:83], v[8:9]
	global_store_dwordx2 v0, v[10:11], s[40:41]
	ds_read_b128 v[80:83], v1 offset:16384
	s_add_u32 s40, s40, 0x30000
	s_addc_u32 s41, s41, 0
	global_load_dwordx2 v[70:71], v0, s[14:15]
	s_add_u32 s14, s14, 0x30000
	s_addc_u32 s15, s15, 0
	s_waitcnt vmcnt(60) lgkmcnt(3)
	v_cvt_pk_bf16_f32 v12, v2, v3
	v_cvt_pk_bf16_f32 v13, v4, v5
	v_lshlrev_b32_e32 v6, 16, v72
	v_and_b32_e32 v7, 0xffff0000, v72
	v_lshlrev_b32_e32 v8, 16, v73
	v_and_b32_e32 v9, 0xffff0000, v73
	v_pk_fma_f32 v[2:3], v[2:3], v[84:85], v[6:7]
	v_pk_fma_f32 v[4:5], v[4:5], v[86:87], v[8:9]
	global_store_dwordx2 v0, v[12:13], s[40:41]
	ds_read_b128 v[84:87], v1 offset:16896
	s_add_u32 s40, s40, 0x30000
	s_addc_u32 s41, s41, 0
	global_load_dwordx2 v[72:73], v0, s[14:15]
	s_add_u32 s14, s14, 0x30000
	s_addc_u32 s15, s15, 0
	s_waitcnt vmcnt(61) lgkmcnt(3)
	v_cvt_pk_bf16_f32 v10, v2, v3
	v_cvt_pk_bf16_f32 v11, v4, v5
	v_lshlrev_b32_e32 v6, 16, v74
	v_and_b32_e32 v7, 0xffff0000, v74
	v_lshlrev_b32_e32 v8, 16, v75
	v_and_b32_e32 v9, 0xffff0000, v75
	v_pk_fma_f32 v[2:3], v[2:3], v[88:89], v[6:7]
	v_pk_fma_f32 v[4:5], v[4:5], v[90:91], v[8:9]
	global_store_dwordx2 v0, v[10:11], s[40:41]
	ds_read_b128 v[88:91], v1 offset:17408
	s_add_u32 s40, s40, 0x30000
	s_addc_u32 s41, s41, 0
	global_load_dwordx2 v[74:75], v0, s[14:15]
	s_add_u32 s14, s14, 0x30000
	s_addc_u32 s15, s15, 0
	s_waitcnt vmcnt(62) lgkmcnt(3)
	v_cvt_pk_bf16_f32 v12, v2, v3
	v_cvt_pk_bf16_f32 v13, v4, v5
	v_lshlrev_b32_e32 v6, 16, v76
	v_and_b32_e32 v7, 0xffff0000, v76
	v_lshlrev_b32_e32 v8, 16, v77
	v_and_b32_e32 v9, 0xffff0000, v77
	v_pk_fma_f32 v[2:3], v[2:3], v[92:93], v[6:7]
	v_pk_fma_f32 v[4:5], v[4:5], v[94:95], v[8:9]
	global_store_dwordx2 v0, v[12:13], s[40:41]
	ds_read_b128 v[92:95], v1 offset:17920
	s_add_u32 s40, s40, 0x30000
	s_addc_u32 s41, s41, 0
	global_load_dwordx2 v[76:77], v0, s[14:15]
	s_add_u32 s14, s14, 0x30000
	s_addc_u32 s15, s15, 0
	v_add_u32_e32 v1, 0x4000, v1
	s_mov_b32 s8, 6
; __device__ __forceinline__ unsigned cvt_pk_bf16(float lo, float hi) { const f32x2 f = {lo, hi}; const bf16x2_t v = __builtin_convertvector(f, bf16x2_t); return __builtin_bit_cast(unsigned, v); }
; __device__ __forceinline__ float bflo(unsigned u) { return __uint_as_float(u << 16); }
; __device__ __forceinline__ float bfhi(unsigned u) { return __uint_as_float(u & 0xffff0000u); }
; __device__ __forceinline__ void phase_scan(const Params& P, int tid) {
;     ...
;             for (int n0 = 0; n0 < 256; n0 += 16) {
;                 u32x2 d[16]; f32x4 dc[16];
; #pragma unroll
;                 for (int j = 0; j < 16; ++j) { d[j] = *(const u32x2*)(sp + (size_t)(n0 + j) * (6 * 16384)); dc[j] = *(const f32x4*)(dp + (size_t)(n0 + j) * 768); }
; #pragma unroll
;                 for (int j = 0; j < 16; ++j) { u32x2 o; o.x = cvt_pk_bf16(S[0], S[1]); o.y = cvt_pk_bf16(S[2], S[3]);
;                     S[0] = dc[j][0] * S[0] + bflo(d[j].x); S[1] = dc[j][1] * S[1] + bfhi(d[j].x); S[2] = dc[j][2] * S[2] + bflo(d[j].y); S[3] = dc[j][3] * S[3] + bfhi(d[j].y);
;                     *(u32x2*)(sp + (size_t)(n0 + j) * (6 * 16384)) = o; }
;             }
.Lscan_a_loop:
	s_waitcnt vmcnt(62) lgkmcnt(3)
	v_cvt_pk_bf16_f32 v10, v2, v3
	v_cvt_pk_bf16_f32 v11, v4, v5
	v_lshlrev_b32_e32 v6, 16, v14
	v_and_b32_e32 v7, 0xffff0000, v14
	v_lshlrev_b32_e32 v8, 16, v15
	v_and_b32_e32 v9, 0xffff0000, v15
	v_pk_fma_f32 v[2:3], v[2:3], v[80:81], v[6:7]
	v_pk_fma_f32 v[4:5], v[4:5], v[82:83], v[8:9]
	global_store_dwordx2 v0, v[10:11], s[40:41]
	ds_read_b128 v[80:83], v1 offset:2048
	s_add_u32 s40, s40, 0x30000
	s_addc_u32 s41, s41, 0
	global_load_dwordx2 v[14:15], v0, s[14:15]
	s_add_u32 s14, s14, 0x30000
	s_addc_u32 s15, s15, 0
	s_waitcnt vmcnt(62) lgkmcnt(3)
	v_cvt_pk_bf16_f32 v12, v2, v3
	v_cvt_pk_bf16_f32 v13, v4, v5
	v_lshlrev_b32_e32 v6, 16, v16
	v_and_b32_e32 v7, 0xffff0000, v16
	v_lshlrev_b32_e32 v8, 16, v17
	v_and_b32_e32 v9, 0xffff0000, v17
	v_pk_fma_f32 v[2:3], v[2:3], v[84:85], v[6:7]
	v_pk_fma_f32 v[4:5], v[4:5], v[86:87], v[8:9]
	global_store_dwordx2 v0, v[12:13], s[40:41]
	ds_read_b128 v[84:87], v1 offset:2560
	s_add_u32 s40, s40, 0x30000
	s_addc_u32 s41, s41, 0
	global_load_dwordx2 v[16:17], v0, s[14:15]
	s_add_u32 s14, s14, 0x30000
	s_addc_u32 s15, s15, 0
	s_waitcnt vmcnt(62) lgkmcnt(3)
	v_cvt_pk_bf16_f32 v10, v2, v3
	v_cvt_pk_bf16_f32 v11, v4, v5
	v_lshlrev_b32_e32 v6, 16, v18
	v_and_b32_e32 v7, 0xffff0000, v18
	v_lshlrev_b32_e32 v8, 16, v19
	v_and_b32_e32 v9, 0xffff0000, v19
	v_pk_fma_f32 v[2:3], v[2:3], v[88:89], v[6:7]
	v_pk_fma_f32 v[4:5], v[4:5], v[90:91], v[8:9]
	global_store_dwordx2 v0, v[10:11], s[40:41]
	ds_read_b128 v[88:91], v1 offset:3072
	s_add_u32 s40, s40, 0x30000
	s_addc_u32 s41, s41, 0
	global_load_dwordx2 v[18:19], v0, s[14:15]
	s_add_u32 s14, s14, 0x30000
	s_addc_u32 s15, s15, 0
	s_waitcnt vmcnt(62) lgkmcnt(3)
	v_cvt_pk_bf16_f32 v12, v2, v3
	v_cvt_pk_bf16_f32 v13, v4, v5
	v_lshlrev_b32_e32 v6, 16, v20
	v_and_b32_e32 v7, 0xffff0000, v20
	v_lshlrev_b32_e32 v8, 16, v21
	v_and_b32_e32 v9, 0xffff0000, v21
	v_pk_fma_f32 v[2:3], v[2:3], v[92:93], v[6:7]
	v_pk_fma_f32 v[4:5], v[4:5], v[94:95], v[8:9]
	global_store_dwordx2 v0, v[12:13], s[40:41]
	ds_read_b128 v[92:95], v1 offset:3584
	s_add_u32 s40, s40, 0x30000
	s_addc_u32 s41, s41, 0
	global_load_dwordx2 v[20:21], v0, s[14:15]
	s_add_u32 s14, s14, 0x30000
	s_addc_u32 s15, s15, 0
	s_waitcnt vmcnt(62) lgkmcnt(3)
	v_cvt_pk_bf16_f32 v10, v2, v3
	v_cvt_pk_bf16_f32 v11, v4, v5
	v_lshlrev_b32_e32 v6, 16, v22
	v_and_b32_e32 v7, 0xffff0000, v22
	v_lshlrev_b32_e32 v8, 16, v23
	v_and_b32_e32 v9, 0xffff0000, v23
	v_pk_fma_f32 v[2:3], v[2:3], v[80:81], v[6:7]
	v_pk_fma_f32 v[4:5], v[4:5], v[82:83], v[8:9]
	global_store_dwordx2 v0, v[10:11], s[40:41]
	ds_read_b128 v[80:83], v1 offset:4096
	s_add_u32 s40, s40, 0x30000
	s_addc_u32 s41, s41, 0
	global_load_dwordx2 v[22:23], v0, s[14:15]
	s_add_u32 s14, s14, 0x30000
	s_addc_u32 s15, s15, 0
	s_waitcnt vmcnt(62) lgkmcnt(3)
	v_cvt_pk_bf16_f32 v12, v2, v3
	v_cvt_pk_bf16_f32 v13, v4, v5
	v_lshlrev_b32_e32 v6, 16, v24
	v_and_b32_e32 v7, 0xffff0000, v24
	v_lshlrev_b32_e32 v8, 16, v25
	v_and_b32_e32 v9, 0xffff0000, v25
	v_pk_fma_f32 v[2:3], v[2:3], v[84:85], v[6:7]
	v_pk_fma_f32 v[4:5], v[4:5], v[86:87], v[8:9]
	global_store_dwordx2 v0, v[12:13], s[40:41]
	ds_read_b128 v[84:87], v1 offset:4608
	s_add_u32 s40, s40, 0x30000
	s_addc_u32 s41, s41, 0
	global_load_dwordx2 v[24:25], v0, s[14:15]
	s_add_u32 s14, s14, 0x30000
	s_addc_u32 s15, s15, 0
	s_waitcnt vmcnt(62) lgkmcnt(3)
	v_cvt_pk_bf16_f32 v10, v2, v3
	v_cvt_pk_bf16_f32 v11, v4, v5
	v_lshlrev_b32_e32 v6, 16, v26
	v_and_b32_e32 v7, 0xffff0000, v26
	v_lshlrev_b32_e32 v8, 16, v27
	v_and_b32_e32 v9, 0xffff0000, v27
	v_pk_fma_f32 v[2:3], v[2:3], v[88:89], v[6:7]
	v_pk_fma_f32 v[4:5], v[4:5], v[90:91], v[8:9]
	global_store_dwordx2 v0, v[10:11], s[40:41]
	ds_read_b128 v[88:91], v1 offset:5120
	s_add_u32 s40, s40, 0x30000
	s_addc_u32 s41, s41, 0
	global_load_dwordx2 v[26:27], v0, s[14:15]
	s_add_u32 s14, s14, 0x30000
	s_addc_u32 s15, s15, 0
	s_waitcnt vmcnt(62) lgkmcnt(3)
	v_cvt_pk_bf16_f32 v12, v2, v3
	v_cvt_pk_bf16_f32 v13, v4, v5
	v_lshlrev_b32_e32 v6, 16, v28
	v_and_b32_e32 v7, 0xffff0000, v28
	v_lshlrev_b32_e32 v8, 16, v29
	v_and_b32_e32 v9, 0xffff0000, v29
	v_pk_fma_f32 v[2:3], v[2:3], v[92:93], v[6:7]
	v_pk_fma_f32 v[4:5], v[4:5], v[94:95], v[8:9]
	global_store_dwordx2 v0, v[12:13], s[40:41]
	ds_read_b128 v[92:95], v1 offset:5632
	s_add_u32 s40, s40, 0x30000
	s_addc_u32 s41, s41, 0
	global_load_dwordx2 v[28:29], v0, s[14:15]
	s_add_u32 s14, s14, 0x30000
	s_addc_u32 s15, s15, 0
	s_waitcnt vmcnt(62) lgkmcnt(3)
	v_cvt_pk_bf16_f32 v10, v2, v3
	v_cvt_pk_bf16_f32 v11, v4, v5
	v_lshlrev_b32_e32 v6, 16, v30
	v_and_b32_e32 v7, 0xffff0000, v30
	v_lshlrev_b32_e32 v8, 16, v31
	v_and_b32_e32 v9, 0xffff0000, v31
	v_pk_fma_f32 v[2:3], v[2:3], v[80:81], v[6:7]
	v_pk_fma_f32 v[4:5], v[4:5], v[82:83], v[8:9]
	global_store_dwordx2 v0, v[10:11], s[40:41]
	ds_read_b128 v[80:83], v1 offset:6144
	s_add_u32 s40, s40, 0x30000
	s_addc_u32 s41, s41, 0
	global_load_dwordx2 v[30:31], v0, s[14:15]
	s_add_u32 s14, s14, 0x30000
	s_addc_u32 s15, s15, 0
	s_waitcnt vmcnt(62) lgkmcnt(3)
	v_cvt_pk_bf16_f32 v12, v2, v3
	v_cvt_pk_bf16_f32 v13, v4, v5
	v_lshlrev_b32_e32 v6, 16, v32
	v_and_b32_e32 v7, 0xffff0000, v32
	v_lshlrev_b32_e32 v8, 16, v33
	v_and_b32_e32 v9, 0xffff0000, v33
	v_pk_fma_f32 v[2:3], v[2:3], v[84:85], v[6:7]
	v_pk_fma_f32 v[4:5], v[4:5], v[86:87], v[8:9]
	global_store_dwordx2 v0, v[12:13], s[40:41]
	ds_read_b128 v[84:87], v1 offset:6656
	s_add_u32 s40, s40, 0x30000
	s_addc_u32 s41, s41, 0
	global_load_dwordx2 v[32:33], v0, s[14:15]
	s_add_u32 s14, s14, 0x30000
	s_addc_u32 s15, s15, 0
	s_waitcnt vmcnt(62) lgkmcnt(3)
; __device__ __forceinline__ unsigned cvt_pk_bf16(float lo, float hi) { const f32x2 f = {lo, hi}; const bf16x2_t v = __builtin_convertvector(f, bf16x2_t); return __builtin_bit_cast(unsigned, v); }
; __device__ __forceinline__ float bflo(unsigned u) { return __uint_as_float(u << 16); }
; __device__ __forceinline__ float bfhi(unsigned u) { return __uint_as_float(u & 0xffff0000u); }
; __device__ __forceinline__ void phase_scan(const Params& P, int tid) {
;     ...
;             for (int n0 = 0; n0 < 256; n0 += 16) {
;                 u32x2 d[16]; f32x4 dc[16];
; #pragma unroll
;                 for (int j = 0; j < 16; ++j) { d[j] = *(const u32x2*)(sp + (size_t)(n0 + j) * (6 * 16384)); dc[j] = *(const f32x4*)(dp + (size_t)(n0 + j) * 768); }
; #pragma unroll
;                 for (int j = 0; j < 16; ++j) { u32x2 o; o.x = cvt_pk_bf16(S[0], S[1]); o.y = cvt_pk_bf16(S[2], S[3]);
;                     S[0] = dc[j][0] * S[0] + bflo(d[j].x); S[1] = dc[j][1] * S[1] + bfhi(d[j].x); S[2] = dc[j][2] * S[2] + bflo(d[j].y); S[3] = dc[j][3] * S[3] + bfhi(d[j].y);
;                     *(u32x2*)(sp + (size_t)(n0 + j) * (6 * 16384)) = o; }
;             }
	v_cvt_pk_bf16_f32 v10, v2, v3
	v_cvt_pk_bf16_f32 v11, v4, v5
	v_lshlrev_b32_e32 v6, 16, v34
	v_and_b32_e32 v7, 0xffff0000, v34
	v_lshlrev_b32_e32 v8, 16, v35
	v_and_b32_e32 v9, 0xffff0000, v35
	v_pk_fma_f32 v[2:3], v[2:3], v[88:89], v[6:7]
	v_pk_fma_f32 v[4:5], v[4:5], v[90:91], v[8:9]
	global_store_dwordx2 v0, v[10:11], s[40:41]
	ds_read_b128 v[88:91], v1 offset:7168
	s_add_u32 s40, s40, 0x30000
	s_addc_u32 s41, s41, 0
	global_load_dwordx2 v[34:35], v0, s[14:15]
	s_add_u32 s14, s14, 0x30000
	s_addc_u32 s15, s15, 0
	s_waitcnt vmcnt(62) lgkmcnt(3)
	v_cvt_pk_bf16_f32 v12, v2, v3
	v_cvt_pk_bf16_f32 v13, v4, v5
	v_lshlrev_b32_e32 v6, 16, v36
	v_and_b32_e32 v7, 0xffff0000, v36
	v_lshlrev_b32_e32 v8, 16, v37
	v_and_b32_e32 v9, 0xffff0000, v37
	v_pk_fma_f32 v[2:3], v[2:3], v[92:93], v[6:7]
	v_pk_fma_f32 v[4:5], v[4:5], v[94:95], v[8:9]
	global_store_dwordx2 v0, v[12:13], s[40:41]
	ds_read_b128 v[92:95], v1 offset:7680
	s_add_u32 s40, s40, 0x30000
	s_addc_u32 s41, s41, 0
	global_load_dwordx2 v[36:37], v0, s[14:15]
	s_add_u32 s14, s14, 0x30000
	s_addc_u32 s15, s15, 0
	s_waitcnt vmcnt(62) lgkmcnt(3)
	v_cvt_pk_bf16_f32 v10, v2, v3
	v_cvt_pk_bf16_f32 v11, v4, v5
	v_lshlrev_b32_e32 v6, 16, v38
	v_and_b32_e32 v7, 0xffff0000, v38
	v_lshlrev_b32_e32 v8, 16, v39
	v_and_b32_e32 v9, 0xffff0000, v39
	v_pk_fma_f32 v[2:3], v[2:3], v[80:81], v[6:7]
	v_pk_fma_f32 v[4:5], v[4:5], v[82:83], v[8:9]
	global_store_dwordx2 v0, v[10:11], s[40:41]
	ds_read_b128 v[80:83], v1 offset:8192
	s_add_u32 s40, s40, 0x30000
	s_addc_u32 s41, s41, 0
	global_load_dwordx2 v[38:39], v0, s[14:15]
	s_add_u32 s14, s14, 0x30000
	s_addc_u32 s15, s15, 0
	s_waitcnt vmcnt(62) lgkmcnt(3)
	v_cvt_pk_bf16_f32 v12, v2, v3
	v_cvt_pk_bf16_f32 v13, v4, v5
	v_lshlrev_b32_e32 v6, 16, v40
	v_and_b32_e32 v7, 0xffff0000, v40
	v_lshlrev_b32_e32 v8, 16, v41
	v_and_b32_e32 v9, 0xffff0000, v41
	v_pk_fma_f32 v[2:3], v[2:3], v[84:85], v[6:7]
	v_pk_fma_f32 v[4:5], v[4:5], v[86:87], v[8:9]
	global_store_dwordx2 v0, v[12:13], s[40:41]
	ds_read_b128 v[84:87], v1 offset:8704
	s_add_u32 s40, s40, 0x30000
	s_addc_u32 s41, s41, 0
	global_load_dwordx2 v[40:41], v0, s[14:15]
	s_add_u32 s14, s14, 0x30000
	s_addc_u32 s15, s15, 0
	s_waitcnt vmcnt(62) lgkmcnt(3)
	v_cvt_pk_bf16_f32 v10, v2, v3
	v_cvt_pk_bf16_f32 v11, v4, v5
	v_lshlrev_b32_e32 v6, 16, v42
	v_and_b32_e32 v7, 0xffff0000, v42
	v_lshlrev_b32_e32 v8, 16, v43
	v_and_b32_e32 v9, 0xffff0000, v43
	v_pk_fma_f32 v[2:3], v[2:3], v[88:89], v[6:7]
	v_pk_fma_f32 v[4:5], v[4:5], v[90:91], v[8:9]
	global_store_dwordx2 v0, v[10:11], s[40:41]
	ds_read_b128 v[88:91], v1 offset:9216
	s_add_u32 s40, s40, 0x30000
	s_addc_u32 s41, s41, 0
	global_load_dwordx2 v[42:43], v0, s[14:15]
	s_add_u32 s14, s14, 0x30000
	s_addc_u32 s15, s15, 0
	s_waitcnt vmcnt(62) lgkmcnt(3)
	v_cvt_pk_bf16_f32 v12, v2, v3
	v_cvt_pk_bf16_f32 v13, v4, v5
	v_lshlrev_b32_e32 v6, 16, v44
	v_and_b32_e32 v7, 0xffff0000, v44
	v_lshlrev_b32_e32 v8, 16, v45
	v_and_b32_e32 v9, 0xffff0000, v45
	v_pk_fma_f32 v[2:3], v[2:3], v[92:93], v[6:7]
	v_pk_fma_f32 v[4:5], v[4:5], v[94:95], v[8:9]
	global_store_dwordx2 v0, v[12:13], s[40:41]
	ds_read_b128 v[92:95], v1 offset:9728
	s_add_u32 s40, s40, 0x30000
	s_addc_u32 s41, s41, 0
	global_load_dwordx2 v[44:45], v0, s[14:15]
	s_add_u32 s14, s14, 0x30000
	s_addc_u32 s15, s15, 0
	s_waitcnt vmcnt(62) lgkmcnt(3)
	v_cvt_pk_bf16_f32 v10, v2, v3
	v_cvt_pk_bf16_f32 v11, v4, v5
	v_lshlrev_b32_e32 v6, 16, v46
	v_and_b32_e32 v7, 0xffff0000, v46
	v_lshlrev_b32_e32 v8, 16, v47
	v_and_b32_e32 v9, 0xffff0000, v47
	v_pk_fma_f32 v[2:3], v[2:3], v[80:81], v[6:7]
	v_pk_fma_f32 v[4:5], v[4:5], v[82:83], v[8:9]
	global_store_dwordx2 v0, v[10:11], s[40:41]
	ds_read_b128 v[80:83], v1 offset:10240
	s_add_u32 s40, s40, 0x30000
	s_addc_u32 s41, s41, 0
	global_load_dwordx2 v[46:47], v0, s[14:15]
	s_add_u32 s14, s14, 0x30000
	s_addc_u32 s15, s15, 0
	s_waitcnt vmcnt(62) lgkmcnt(3)
	v_cvt_pk_bf16_f32 v12, v2, v3
	v_cvt_pk_bf16_f32 v13, v4, v5
	v_lshlrev_b32_e32 v6, 16, v48
	v_and_b32_e32 v7, 0xffff0000, v48
	v_lshlrev_b32_e32 v8, 16, v49
	v_and_b32_e32 v9, 0xffff0000, v49
	v_pk_fma_f32 v[2:3], v[2:3], v[84:85], v[6:7]
	v_pk_fma_f32 v[4:5], v[4:5], v[86:87], v[8:9]
	global_store_dwordx2 v0, v[12:13], s[40:41]
	ds_read_b128 v[84:87], v1 offset:10752
	s_add_u32 s40, s40, 0x30000
	s_addc_u32 s41, s41, 0
	global_load_dwordx2 v[48:49], v0, s[14:15]
	s_add_u32 s14, s14, 0x30000
	s_addc_u32 s15, s15, 0
	s_waitcnt vmcnt(62) lgkmcnt(3)
	v_cvt_pk_bf16_f32 v10, v2, v3
	v_cvt_pk_bf16_f32 v11, v4, v5
	v_lshlrev_b32_e32 v6, 16, v50
	v_and_b32_e32 v7, 0xffff0000, v50
	v_lshlrev_b32_e32 v8, 16, v51
	v_and_b32_e32 v9, 0xffff0000, v51
	v_pk_fma_f32 v[2:3], v[2:3], v[88:89], v[6:7]
	v_pk_fma_f32 v[4:5], v[4:5], v[90:91], v[8:9]
	global_store_dwordx2 v0, v[10:11], s[40:41]
	ds_read_b128 v[88:91], v1 offset:11264
	s_add_u32 s40, s40, 0x30000
	s_addc_u32 s41, s41, 0
	global_load_dwordx2 v[50:51], v0, s[14:15]
	s_add_u32 s14, s14, 0x30000
	s_addc_u32 s15, s15, 0
	s_waitcnt vmcnt(62) lgkmcnt(3)
	v_cvt_pk_bf16_f32 v12, v2, v3
	v_cvt_pk_bf16_f32 v13, v4, v5
	v_lshlrev_b32_e32 v6, 16, v52
	v_and_b32_e32 v7, 0xffff0000, v52
	v_lshlrev_b32_e32 v8, 16, v53
	v_and_b32_e32 v9, 0xffff0000, v53
	v_pk_fma_f32 v[2:3], v[2:3], v[92:93], v[6:7]
	v_pk_fma_f32 v[4:5], v[4:5], v[94:95], v[8:9]
	global_store_dwordx2 v0, v[12:13], s[40:41]
	ds_read_b128 v[92:95], v1 offset:11776
	s_add_u32 s40, s40, 0x30000
	s_addc_u32 s41, s41, 0
	global_load_dwordx2 v[52:53], v0, s[14:15]
	s_add_u32 s14, s14, 0x30000
	s_addc_u32 s15, s15, 0
	s_waitcnt vmcnt(62) lgkmcnt(3)
; __device__ __forceinline__ unsigned cvt_pk_bf16(float lo, float hi) { const f32x2 f = {lo, hi}; const bf16x2_t v = __builtin_convertvector(f, bf16x2_t); return __builtin_bit_cast(unsigned, v); }
; __device__ __forceinline__ float bflo(unsigned u) { return __uint_as_float(u << 16); }
; __device__ __forceinline__ float bfhi(unsigned u) { return __uint_as_float(u & 0xffff0000u); }
; __device__ __forceinline__ void phase_scan(const Params& P, int tid) {
;     ...
;             for (int n0 = 0; n0 < 256; n0 += 16) {
;                 u32x2 d[16]; f32x4 dc[16];
; #pragma unroll
;                 for (int j = 0; j < 16; ++j) { d[j] = *(const u32x2*)(sp + (size_t)(n0 + j) * (6 * 16384)); dc[j] = *(const f32x4*)(dp + (size_t)(n0 + j) * 768); }
; #pragma unroll
;                 for (int j = 0; j < 16; ++j) { u32x2 o; o.x = cvt_pk_bf16(S[0], S[1]); o.y = cvt_pk_bf16(S[2], S[3]);
;                     S[0] = dc[j][0] * S[0] + bflo(d[j].x); S[1] = dc[j][1] * S[1] + bfhi(d[j].x); S[2] = dc[j][2] * S[2] + bflo(d[j].y); S[3] = dc[j][3] * S[3] + bfhi(d[j].y);
;                     *(u32x2*)(sp + (size_t)(n0 + j) * (6 * 16384)) = o; }
;             }
	v_cvt_pk_bf16_f32 v10, v2, v3
	v_cvt_pk_bf16_f32 v11, v4, v5
	v_lshlrev_b32_e32 v6, 16, v54
	v_and_b32_e32 v7, 0xffff0000, v54
	v_lshlrev_b32_e32 v8, 16, v55
	v_and_b32_e32 v9, 0xffff0000, v55
	v_pk_fma_f32 v[2:3], v[2:3], v[80:81], v[6:7]
	v_pk_fma_f32 v[4:5], v[4:5], v[82:83], v[8:9]
	global_store_dwordx2 v0, v[10:11], s[40:41]
	ds_read_b128 v[80:83], v1 offset:12288
	s_add_u32 s40, s40, 0x30000
	s_addc_u32 s41, s41, 0
	global_load_dwordx2 v[54:55], v0, s[14:15]
	s_add_u32 s14, s14, 0x30000
	s_addc_u32 s15, s15, 0
	s_waitcnt vmcnt(62) lgkmcnt(3)
	v_cvt_pk_bf16_f32 v12, v2, v3
	v_cvt_pk_bf16_f32 v13, v4, v5
	v_lshlrev_b32_e32 v6, 16, v56
	v_and_b32_e32 v7, 0xffff0000, v56
	v_lshlrev_b32_e32 v8, 16, v57
	v_and_b32_e32 v9, 0xffff0000, v57
	v_pk_fma_f32 v[2:3], v[2:3], v[84:85], v[6:7]
	v_pk_fma_f32 v[4:5], v[4:5], v[86:87], v[8:9]
	global_store_dwordx2 v0, v[12:13], s[40:41]
	ds_read_b128 v[84:87], v1 offset:12800
	s_add_u32 s40, s40, 0x30000
	s_addc_u32 s41, s41, 0
	global_load_dwordx2 v[56:57], v0, s[14:15]
	s_add_u32 s14, s14, 0x30000
	s_addc_u32 s15, s15, 0
	s_waitcnt vmcnt(62) lgkmcnt(3)
	v_cvt_pk_bf16_f32 v10, v2, v3
	v_cvt_pk_bf16_f32 v11, v4, v5
	v_lshlrev_b32_e32 v6, 16, v58
	v_and_b32_e32 v7, 0xffff0000, v58
	v_lshlrev_b32_e32 v8, 16, v59
	v_and_b32_e32 v9, 0xffff0000, v59
	v_pk_fma_f32 v[2:3], v[2:3], v[88:89], v[6:7]
	v_pk_fma_f32 v[4:5], v[4:5], v[90:91], v[8:9]
	global_store_dwordx2 v0, v[10:11], s[40:41]
	ds_read_b128 v[88:91], v1 offset:13312
	s_add_u32 s40, s40, 0x30000
	s_addc_u32 s41, s41, 0
	global_load_dwordx2 v[58:59], v0, s[14:15]
	s_add_u32 s14, s14, 0x30000
	s_addc_u32 s15, s15, 0
	s_waitcnt vmcnt(62) lgkmcnt(3)
	v_cvt_pk_bf16_f32 v12, v2, v3
	v_cvt_pk_bf16_f32 v13, v4, v5
	v_lshlrev_b32_e32 v6, 16, v60
	v_and_b32_e32 v7, 0xffff0000, v60
	v_lshlrev_b32_e32 v8, 16, v61
	v_and_b32_e32 v9, 0xffff0000, v61
	v_pk_fma_f32 v[2:3], v[2:3], v[92:93], v[6:7]
	v_pk_fma_f32 v[4:5], v[4:5], v[94:95], v[8:9]
	global_store_dwordx2 v0, v[12:13], s[40:41]
	ds_read_b128 v[92:95], v1 offset:13824
	s_add_u32 s40, s40, 0x30000
	s_addc_u32 s41, s41, 0
	global_load_dwordx2 v[60:61], v0, s[14:15]
	s_add_u32 s14, s14, 0x30000
	s_addc_u32 s15, s15, 0
	s_waitcnt vmcnt(62) lgkmcnt(3)
	v_cvt_pk_bf16_f32 v10, v2, v3
	v_cvt_pk_bf16_f32 v11, v4, v5
	v_lshlrev_b32_e32 v6, 16, v62
	v_and_b32_e32 v7, 0xffff0000, v62
	v_lshlrev_b32_e32 v8, 16, v63
	v_and_b32_e32 v9, 0xffff0000, v63
	v_pk_fma_f32 v[2:3], v[2:3], v[80:81], v[6:7]
	v_pk_fma_f32 v[4:5], v[4:5], v[82:83], v[8:9]
	global_store_dwordx2 v0, v[10:11], s[40:41]
	ds_read_b128 v[80:83], v1 offset:14336
	s_add_u32 s40, s40, 0x30000
	s_addc_u32 s41, s41, 0
	global_load_dwordx2 v[62:63], v0, s[14:15]
	s_add_u32 s14, s14, 0x30000
	s_addc_u32 s15, s15, 0
	s_waitcnt vmcnt(62) lgkmcnt(3)
	v_cvt_pk_bf16_f32 v12, v2, v3
	v_cvt_pk_bf16_f32 v13, v4, v5
	v_lshlrev_b32_e32 v6, 16, v64
	v_and_b32_e32 v7, 0xffff0000, v64
	v_lshlrev_b32_e32 v8, 16, v65
	v_and_b32_e32 v9, 0xffff0000, v65
	v_pk_fma_f32 v[2:3], v[2:3], v[84:85], v[6:7]
	v_pk_fma_f32 v[4:5], v[4:5], v[86:87], v[8:9]
	global_store_dwordx2 v0, v[12:13], s[40:41]
	ds_read_b128 v[84:87], v1 offset:14848
	s_add_u32 s40, s40, 0x30000
	s_addc_u32 s41, s41, 0
	global_load_dwordx2 v[64:65], v0, s[14:15]
	s_add_u32 s14, s14, 0x30000
	s_addc_u32 s15, s15, 0
	s_waitcnt vmcnt(62) lgkmcnt(3)
	v_cvt_pk_bf16_f32 v10, v2, v3
	v_cvt_pk_bf16_f32 v11, v4, v5
	v_lshlrev_b32_e32 v6, 16, v66
	v_and_b32_e32 v7, 0xffff0000, v66
	v_lshlrev_b32_e32 v8, 16, v67
	v_and_b32_e32 v9, 0xffff0000, v67
	v_pk_fma_f32 v[2:3], v[2:3], v[88:89], v[6:7]
	v_pk_fma_f32 v[4:5], v[4:5], v[90:91], v[8:9]
	global_store_dwordx2 v0, v[10:11], s[40:41]
	ds_read_b128 v[88:91], v1 offset:15360
	s_add_u32 s40, s40, 0x30000
	s_addc_u32 s41, s41, 0
	global_load_dwordx2 v[66:67], v0, s[14:15]
	s_add_u32 s14, s14, 0x30000
	s_addc_u32 s15, s15, 0
	s_waitcnt vmcnt(62) lgkmcnt(3)
	v_cvt_pk_bf16_f32 v12, v2, v3
	v_cvt_pk_bf16_f32 v13, v4, v5
	v_lshlrev_b32_e32 v6, 16, v68
	v_and_b32_e32 v7, 0xffff0000, v68
	v_lshlrev_b32_e32 v8, 16, v69
	v_and_b32_e32 v9, 0xffff0000, v69
	v_pk_fma_f32 v[2:3], v[2:3], v[92:93], v[6:7]
	v_pk_fma_f32 v[4:5], v[4:5], v[94:95], v[8:9]
	global_store_dwordx2 v0, v[12:13], s[40:41]
	ds_read_b128 v[92:95], v1 offset:15872
	s_add_u32 s40, s40, 0x30000
	s_addc_u32 s41, s41, 0
	global_load_dwordx2 v[68:69], v0, s[14:15]
	s_add_u32 s14, s14, 0x30000
	s_addc_u32 s15, s15, 0
	s_waitcnt vmcnt(62) lgkmcnt(3)
	v_cvt_pk_bf16_f32 v10, v2, v3
	v_cvt_pk_bf16_f32 v11, v4, v5
	v_lshlrev_b32_e32 v6, 16, v70
	v_and_b32_e32 v7, 0xffff0000, v70
	v_lshlrev_b32_e32 v8, 16, v71
	v_and_b32_e32 v9, 0xffff0000, v71
	v_pk_fma_f32 v[2:3], v[2:3], v[80:81], v[6:7]
	v_pk_fma_f32 v[4:5], v[4:5], v[82:83], v[8:9]
	global_store_dwordx2 v0, v[10:11], s[40:41]
	ds_read_b128 v[80:83], v1 offset:16384
	s_add_u32 s40, s40, 0x30000
	s_addc_u32 s41, s41, 0
	global_load_dwordx2 v[70:71], v0, s[14:15]
	s_add_u32 s14, s14, 0x30000
	s_addc_u32 s15, s15, 0
	s_waitcnt vmcnt(62) lgkmcnt(3)
	v_cvt_pk_bf16_f32 v12, v2, v3
	v_cvt_pk_bf16_f32 v13, v4, v5
	v_lshlrev_b32_e32 v6, 16, v72
	v_and_b32_e32 v7, 0xffff0000, v72
	v_lshlrev_b32_e32 v8, 16, v73
	v_and_b32_e32 v9, 0xffff0000, v73
	v_pk_fma_f32 v[2:3], v[2:3], v[84:85], v[6:7]
	v_pk_fma_f32 v[4:5], v[4:5], v[86:87], v[8:9]
	global_store_dwordx2 v0, v[12:13], s[40:41]
	ds_read_b128 v[84:87], v1 offset:16896
	s_add_u32 s40, s40, 0x30000
	s_addc_u32 s41, s41, 0
	global_load_dwordx2 v[72:73], v0, s[14:15]
	s_add_u32 s14, s14, 0x30000
	s_addc_u32 s15, s15, 0
	s_waitcnt vmcnt(62) lgkmcnt(3)
	v_cvt_pk_bf16_f32 v10, v2, v3
	v_cvt_pk_bf16_f32 v11, v4, v5
	v_lshlrev_b32_e32 v6, 16, v74
	v_and_b32_e32 v7, 0xffff0000, v74
	v_lshlrev_b32_e32 v8, 16, v75
	v_and_b32_e32 v9, 0xffff0000, v75
	v_pk_fma_f32 v[2:3], v[2:3], v[88:89], v[6:7]
	v_pk_fma_f32 v[4:5], v[4:5], v[90:91], v[8:9]
	global_store_dwordx2 v0, v[10:11], s[40:41]
	ds_read_b128 v[88:91], v1 offset:17408
	s_add_u32 s40, s40, 0x30000
	s_addc_u32 s41, s41, 0
	global_load_dwordx2 v[74:75], v0, s[14:15]
	s_add_u32 s14, s14, 0x30000
	s_addc_u32 s15, s15, 0
	s_waitcnt vmcnt(62) lgkmcnt(3)
	v_cvt_pk_bf16_f32 v12, v2, v3
	v_cvt_pk_bf16_f32 v13, v4, v5
	v_lshlrev_b32_e32 v6, 16, v76
	v_and_b32_e32 v7, 0xffff0000, v76
	v_lshlrev_b32_e32 v8, 16, v77
	v_and_b32_e32 v9, 0xffff0000, v77
	v_pk_fma_f32 v[2:3], v[2:3], v[92:93], v[6:7]
	v_pk_fma_f32 v[4:5], v[4:5], v[94:95], v[8:9]
	global_store_dwordx2 v0, v[12:13], s[40:41]
	ds_read_b128 v[92:95], v1 offset:17920
	s_add_u32 s40, s40, 0x30000
	s_addc_u32 s41, s41, 0
	global_load_dwordx2 v[76:77], v0, s[14:15]
	s_add_u32 s14, s14, 0x30000
	s_addc_u32 s15, s15, 0
	v_add_u32_e32 v1, 0x4000, v1
	s_sub_u32 s8, s8, 1
	s_cmp_lg_u32 s8, 0
	s_cbranch_scc1 .Lscan_a_loop
; __device__ __forceinline__ unsigned cvt_pk_bf16(float lo, float hi) { const f32x2 f = {lo, hi}; const bf16x2_t v = __builtin_convertvector(f, bf16x2_t); return __builtin_bit_cast(unsigned, v); }
; __device__ __forceinline__ float bflo(unsigned u) { return __uint_as_float(u << 16); }
; __device__ __forceinline__ float bfhi(unsigned u) { return __uint_as_float(u & 0xffff0000u); }
; __device__ __forceinline__ void phase_scan(const Params& P, int tid) {
;     ...
;             for (int n0 = 0; n0 < 256; n0 += 16) {
;                 u32x2 d[16]; f32x4 dc[16];
; #pragma unroll
;                 for (int j = 0; j < 16; ++j) { d[j] = *(const u32x2*)(sp + (size_t)(n0 + j) * (6 * 16384)); dc[j] = *(const f32x4*)(dp + (size_t)(n0 + j) * 768); }
; #pragma unroll
;                 for (int j = 0; j < 16; ++j) { u32x2 o; o.x = cvt_pk_bf16(S[0], S[1]); o.y = cvt_pk_bf16(S[2], S[3]);
;                     S[0] = dc[j][0] * S[0] + bflo(d[j].x); S[1] = dc[j][1] * S[1] + bfhi(d[j].x); S[2] = dc[j][2] * S[2] + bflo(d[j].y); S[3] = dc[j][3] * S[3] + bfhi(d[j].y);
;                     *(u32x2*)(sp + (size_t)(n0 + j) * (6 * 16384)) = o; }
;             }
	s_waitcnt vmcnt(62) lgkmcnt(3)
	v_cvt_pk_bf16_f32 v10, v2, v3
	v_cvt_pk_bf16_f32 v11, v4, v5
	v_lshlrev_b32_e32 v6, 16, v14
	v_and_b32_e32 v7, 0xffff0000, v14
	v_lshlrev_b32_e32 v8, 16, v15
	v_and_b32_e32 v9, 0xffff0000, v15
	v_pk_fma_f32 v[2:3], v[2:3], v[80:81], v[6:7]
	v_pk_fma_f32 v[4:5], v[4:5], v[82:83], v[8:9]
	global_store_dwordx2 v0, v[10:11], s[40:41]
	ds_read_b128 v[80:83], v1 offset:2048
	s_add_u32 s40, s40, 0x30000
	s_addc_u32 s41, s41, 0
	s_waitcnt vmcnt(61) lgkmcnt(3)
	v_cvt_pk_bf16_f32 v12, v2, v3
	v_cvt_pk_bf16_f32 v13, v4, v5
	v_lshlrev_b32_e32 v6, 16, v16
	v_and_b32_e32 v7, 0xffff0000, v16
	v_lshlrev_b32_e32 v8, 16, v17
	v_and_b32_e32 v9, 0xffff0000, v17
	v_pk_fma_f32 v[2:3], v[2:3], v[84:85], v[6:7]
	v_pk_fma_f32 v[4:5], v[4:5], v[86:87], v[8:9]
	global_store_dwordx2 v0, v[12:13], s[40:41]
	ds_read_b128 v[84:87], v1 offset:2560
	s_add_u32 s40, s40, 0x30000
	s_addc_u32 s41, s41, 0
	s_waitcnt vmcnt(60) lgkmcnt(3)
	v_cvt_pk_bf16_f32 v10, v2, v3
	v_cvt_pk_bf16_f32 v11, v4, v5
	v_lshlrev_b32_e32 v6, 16, v18
	v_and_b32_e32 v7, 0xffff0000, v18
	v_lshlrev_b32_e32 v8, 16, v19
	v_and_b32_e32 v9, 0xffff0000, v19
	v_pk_fma_f32 v[2:3], v[2:3], v[88:89], v[6:7]
	v_pk_fma_f32 v[4:5], v[4:5], v[90:91], v[8:9]
	global_store_dwordx2 v0, v[10:11], s[40:41]
	ds_read_b128 v[88:91], v1 offset:3072
	s_add_u32 s40, s40, 0x30000
	s_addc_u32 s41, s41, 0
	s_waitcnt vmcnt(59) lgkmcnt(3)
	v_cvt_pk_bf16_f32 v12, v2, v3
	v_cvt_pk_bf16_f32 v13, v4, v5
	v_lshlrev_b32_e32 v6, 16, v20
	v_and_b32_e32 v7, 0xffff0000, v20
	v_lshlrev_b32_e32 v8, 16, v21
	v_and_b32_e32 v9, 0xffff0000, v21
	v_pk_fma_f32 v[2:3], v[2:3], v[92:93], v[6:7]
	v_pk_fma_f32 v[4:5], v[4:5], v[94:95], v[8:9]
	global_store_dwordx2 v0, v[12:13], s[40:41]
	ds_read_b128 v[92:95], v1 offset:3584
	s_add_u32 s40, s40, 0x30000
	s_addc_u32 s41, s41, 0
	s_waitcnt vmcnt(58) lgkmcnt(3)
	v_cvt_pk_bf16_f32 v10, v2, v3
	v_cvt_pk_bf16_f32 v11, v4, v5
	v_lshlrev_b32_e32 v6, 16, v22
	v_and_b32_e32 v7, 0xffff0000, v22
	v_lshlrev_b32_e32 v8, 16, v23
	v_and_b32_e32 v9, 0xffff0000, v23
	v_pk_fma_f32 v[2:3], v[2:3], v[80:81], v[6:7]
	v_pk_fma_f32 v[4:5], v[4:5], v[82:83], v[8:9]
	global_store_dwordx2 v0, v[10:11], s[40:41]
	ds_read_b128 v[80:83], v1 offset:4096
	s_add_u32 s40, s40, 0x30000
	s_addc_u32 s41, s41, 0
	s_waitcnt vmcnt(57) lgkmcnt(3)
	v_cvt_pk_bf16_f32 v12, v2, v3
	v_cvt_pk_bf16_f32 v13, v4, v5
	v_lshlrev_b32_e32 v6, 16, v24
	v_and_b32_e32 v7, 0xffff0000, v24
	v_lshlrev_b32_e32 v8, 16, v25
	v_and_b32_e32 v9, 0xffff0000, v25
	v_pk_fma_f32 v[2:3], v[2:3], v[84:85], v[6:7]
	v_pk_fma_f32 v[4:5], v[4:5], v[86:87], v[8:9]
	global_store_dwordx2 v0, v[12:13], s[40:41]
	ds_read_b128 v[84:87], v1 offset:4608
	s_add_u32 s40, s40, 0x30000
	s_addc_u32 s41, s41, 0
	s_waitcnt vmcnt(56) lgkmcnt(3)
	v_cvt_pk_bf16_f32 v10, v2, v3
	v_cvt_pk_bf16_f32 v11, v4, v5
	v_lshlrev_b32_e32 v6, 16, v26
	v_and_b32_e32 v7, 0xffff0000, v26
	v_lshlrev_b32_e32 v8, 16, v27
	v_and_b32_e32 v9, 0xffff0000, v27
	v_pk_fma_f32 v[2:3], v[2:3], v[88:89], v[6:7]
	v_pk_fma_f32 v[4:5], v[4:5], v[90:91], v[8:9]
	global_store_dwordx2 v0, v[10:11], s[40:41]
	ds_read_b128 v[88:91], v1 offset:5120
	s_add_u32 s40, s40, 0x30000
	s_addc_u32 s41, s41, 0
	s_waitcnt vmcnt(55) lgkmcnt(3)
	v_cvt_pk_bf16_f32 v12, v2, v3
	v_cvt_pk_bf16_f32 v13, v4, v5
	v_lshlrev_b32_e32 v6, 16, v28
	v_and_b32_e32 v7, 0xffff0000, v28
	v_lshlrev_b32_e32 v8, 16, v29
	v_and_b32_e32 v9, 0xffff0000, v29
	v_pk_fma_f32 v[2:3], v[2:3], v[92:93], v[6:7]
	v_pk_fma_f32 v[4:5], v[4:5], v[94:95], v[8:9]
	global_store_dwordx2 v0, v[12:13], s[40:41]
	ds_read_b128 v[92:95], v1 offset:5632
	s_add_u32 s40, s40, 0x30000
	s_addc_u32 s41, s41, 0
	s_waitcnt vmcnt(54) lgkmcnt(3)
	v_cvt_pk_bf16_f32 v10, v2, v3
	v_cvt_pk_bf16_f32 v11, v4, v5
	v_lshlrev_b32_e32 v6, 16, v30
	v_and_b32_e32 v7, 0xffff0000, v30
	v_lshlrev_b32_e32 v8, 16, v31
	v_and_b32_e32 v9, 0xffff0000, v31
	v_pk_fma_f32 v[2:3], v[2:3], v[80:81], v[6:7]
	v_pk_fma_f32 v[4:5], v[4:5], v[82:83], v[8:9]
	global_store_dwordx2 v0, v[10:11], s[40:41]
	ds_read_b128 v[80:83], v1 offset:6144
	s_add_u32 s40, s40, 0x30000
	s_addc_u32 s41, s41, 0
	s_waitcnt vmcnt(53) lgkmcnt(3)
	v_cvt_pk_bf16_f32 v12, v2, v3
	v_cvt_pk_bf16_f32 v13, v4, v5
	v_lshlrev_b32_e32 v6, 16, v32
	v_and_b32_e32 v7, 0xffff0000, v32
	v_lshlrev_b32_e32 v8, 16, v33
	v_and_b32_e32 v9, 0xffff0000, v33
	v_pk_fma_f32 v[2:3], v[2:3], v[84:85], v[6:7]
	v_pk_fma_f32 v[4:5], v[4:5], v[86:87], v[8:9]
	global_store_dwordx2 v0, v[12:13], s[40:41]
	ds_read_b128 v[84:87], v1 offset:6656
	s_add_u32 s40, s40, 0x30000
	s_addc_u32 s41, s41, 0
	s_waitcnt vmcnt(52) lgkmcnt(3)
	v_cvt_pk_bf16_f32 v10, v2, v3
	v_cvt_pk_bf16_f32 v11, v4, v5
	v_lshlrev_b32_e32 v6, 16, v34
	v_and_b32_e32 v7, 0xffff0000, v34
	v_lshlrev_b32_e32 v8, 16, v35
	v_and_b32_e32 v9, 0xffff0000, v35
	v_pk_fma_f32 v[2:3], v[2:3], v[88:89], v[6:7]
	v_pk_fma_f32 v[4:5], v[4:5], v[90:91], v[8:9]
	global_store_dwordx2 v0, v[10:11], s[40:41]
	ds_read_b128 v[88:91], v1 offset:7168
	s_add_u32 s40, s40, 0x30000
	s_addc_u32 s41, s41, 0
	s_waitcnt vmcnt(51) lgkmcnt(3)
	v_cvt_pk_bf16_f32 v12, v2, v3
	v_cvt_pk_bf16_f32 v13, v4, v5
	v_lshlrev_b32_e32 v6, 16, v36
	v_and_b32_e32 v7, 0xffff0000, v36
	v_lshlrev_b32_e32 v8, 16, v37
	v_and_b32_e32 v9, 0xffff0000, v37
	v_pk_fma_f32 v[2:3], v[2:3], v[92:93], v[6:7]
	v_pk_fma_f32 v[4:5], v[4:5], v[94:95], v[8:9]
	global_store_dwordx2 v0, v[12:13], s[40:41]
	ds_read_b128 v[92:95], v1 offset:7680
	s_add_u32 s40, s40, 0x30000
	s_addc_u32 s41, s41, 0
	s_waitcnt vmcnt(50) lgkmcnt(3)
; __device__ __forceinline__ unsigned cvt_pk_bf16(float lo, float hi) { const f32x2 f = {lo, hi}; const bf16x2_t v = __builtin_convertvector(f, bf16x2_t); return __builtin_bit_cast(unsigned, v); }
; __device__ __forceinline__ float bflo(unsigned u) { return __uint_as_float(u << 16); }
; __device__ __forceinline__ float bfhi(unsigned u) { return __uint_as_float(u & 0xffff0000u); }
; __device__ __forceinline__ void phase_scan(const Params& P, int tid) {
;     ...
;             for (int n0 = 0; n0 < 256; n0 += 16) {
;                 u32x2 d[16]; f32x4 dc[16];
; #pragma unroll
;                 for (int j = 0; j < 16; ++j) { d[j] = *(const u32x2*)(sp + (size_t)(n0 + j) * (6 * 16384)); dc[j] = *(const f32x4*)(dp + (size_t)(n0 + j) * 768); }
; #pragma unroll
;                 for (int j = 0; j < 16; ++j) { u32x2 o; o.x = cvt_pk_bf16(S[0], S[1]); o.y = cvt_pk_bf16(S[2], S[3]);
;                     S[0] = dc[j][0] * S[0] + bflo(d[j].x); S[1] = dc[j][1] * S[1] + bfhi(d[j].x); S[2] = dc[j][2] * S[2] + bflo(d[j].y); S[3] = dc[j][3] * S[3] + bfhi(d[j].y);
;                     *(u32x2*)(sp + (size_t)(n0 + j) * (6 * 16384)) = o; }
;             }
	v_cvt_pk_bf16_f32 v10, v2, v3
	v_cvt_pk_bf16_f32 v11, v4, v5
	v_lshlrev_b32_e32 v6, 16, v38
	v_and_b32_e32 v7, 0xffff0000, v38
	v_lshlrev_b32_e32 v8, 16, v39
	v_and_b32_e32 v9, 0xffff0000, v39
	v_pk_fma_f32 v[2:3], v[2:3], v[80:81], v[6:7]
	v_pk_fma_f32 v[4:5], v[4:5], v[82:83], v[8:9]
	global_store_dwordx2 v0, v[10:11], s[40:41]
	ds_read_b128 v[80:83], v1 offset:8192
	s_add_u32 s40, s40, 0x30000
	s_addc_u32 s41, s41, 0
	s_waitcnt vmcnt(49) lgkmcnt(3)
	v_cvt_pk_bf16_f32 v12, v2, v3
	v_cvt_pk_bf16_f32 v13, v4, v5
	v_lshlrev_b32_e32 v6, 16, v40
	v_and_b32_e32 v7, 0xffff0000, v40
	v_lshlrev_b32_e32 v8, 16, v41
	v_and_b32_e32 v9, 0xffff0000, v41
	v_pk_fma_f32 v[2:3], v[2:3], v[84:85], v[6:7]
	v_pk_fma_f32 v[4:5], v[4:5], v[86:87], v[8:9]
	global_store_dwordx2 v0, v[12:13], s[40:41]
	ds_read_b128 v[84:87], v1 offset:8704
	s_add_u32 s40, s40, 0x30000
	s_addc_u32 s41, s41, 0
	s_waitcnt vmcnt(48) lgkmcnt(3)
	v_cvt_pk_bf16_f32 v10, v2, v3
	v_cvt_pk_bf16_f32 v11, v4, v5
	v_lshlrev_b32_e32 v6, 16, v42
	v_and_b32_e32 v7, 0xffff0000, v42
	v_lshlrev_b32_e32 v8, 16, v43
	v_and_b32_e32 v9, 0xffff0000, v43
	v_pk_fma_f32 v[2:3], v[2:3], v[88:89], v[6:7]
	v_pk_fma_f32 v[4:5], v[4:5], v[90:91], v[8:9]
	global_store_dwordx2 v0, v[10:11], s[40:41]
	ds_read_b128 v[88:91], v1 offset:9216
	s_add_u32 s40, s40, 0x30000
	s_addc_u32 s41, s41, 0
	s_waitcnt vmcnt(47) lgkmcnt(3)
	v_cvt_pk_bf16_f32 v12, v2, v3
	v_cvt_pk_bf16_f32 v13, v4, v5
	v_lshlrev_b32_e32 v6, 16, v44
	v_and_b32_e32 v7, 0xffff0000, v44
	v_lshlrev_b32_e32 v8, 16, v45
	v_and_b32_e32 v9, 0xffff0000, v45
	v_pk_fma_f32 v[2:3], v[2:3], v[92:93], v[6:7]
	v_pk_fma_f32 v[4:5], v[4:5], v[94:95], v[8:9]
	global_store_dwordx2 v0, v[12:13], s[40:41]
	ds_read_b128 v[92:95], v1 offset:9728
	s_add_u32 s40, s40, 0x30000
	s_addc_u32 s41, s41, 0
	s_waitcnt vmcnt(46) lgkmcnt(3)
	v_cvt_pk_bf16_f32 v10, v2, v3
	v_cvt_pk_bf16_f32 v11, v4, v5
	v_lshlrev_b32_e32 v6, 16, v46
	v_and_b32_e32 v7, 0xffff0000, v46
	v_lshlrev_b32_e32 v8, 16, v47
	v_and_b32_e32 v9, 0xffff0000, v47
	v_pk_fma_f32 v[2:3], v[2:3], v[80:81], v[6:7]
	v_pk_fma_f32 v[4:5], v[4:5], v[82:83], v[8:9]
	global_store_dwordx2 v0, v[10:11], s[40:41]
	ds_read_b128 v[80:83], v1 offset:10240
	s_add_u32 s40, s40, 0x30000
	s_addc_u32 s41, s41, 0
	s_waitcnt vmcnt(45) lgkmcnt(3)
	v_cvt_pk_bf16_f32 v12, v2, v3
	v_cvt_pk_bf16_f32 v13, v4, v5
	v_lshlrev_b32_e32 v6, 16, v48
	v_and_b32_e32 v7, 0xffff0000, v48
	v_lshlrev_b32_e32 v8, 16, v49
	v_and_b32_e32 v9, 0xffff0000, v49
	v_pk_fma_f32 v[2:3], v[2:3], v[84:85], v[6:7]
	v_pk_fma_f32 v[4:5], v[4:5], v[86:87], v[8:9]
	global_store_dwordx2 v0, v[12:13], s[40:41]
	ds_read_b128 v[84:87], v1 offset:10752
	s_add_u32 s40, s40, 0x30000
	s_addc_u32 s41, s41, 0
	s_waitcnt vmcnt(44) lgkmcnt(3)
	v_cvt_pk_bf16_f32 v10, v2, v3
	v_cvt_pk_bf16_f32 v11, v4, v5
	v_lshlrev_b32_e32 v6, 16, v50
	v_and_b32_e32 v7, 0xffff0000, v50
	v_lshlrev_b32_e32 v8, 16, v51
	v_and_b32_e32 v9, 0xffff0000, v51
	v_pk_fma_f32 v[2:3], v[2:3], v[88:89], v[6:7]
	v_pk_fma_f32 v[4:5], v[4:5], v[90:91], v[8:9]
	global_store_dwordx2 v0, v[10:11], s[40:41]
	ds_read_b128 v[88:91], v1 offset:11264
	s_add_u32 s40, s40, 0x30000
	s_addc_u32 s41, s41, 0
	s_waitcnt vmcnt(43) lgkmcnt(3)
	v_cvt_pk_bf16_f32 v12, v2, v3
	v_cvt_pk_bf16_f32 v13, v4, v5
	v_lshlrev_b32_e32 v6, 16, v52
	v_and_b32_e32 v7, 0xffff0000, v52
	v_lshlrev_b32_e32 v8, 16, v53
	v_and_b32_e32 v9, 0xffff0000, v53
	v_pk_fma_f32 v[2:3], v[2:3], v[92:93], v[6:7]
	v_pk_fma_f32 v[4:5], v[4:5], v[94:95], v[8:9]
	global_store_dwordx2 v0, v[12:13], s[40:41]
	ds_read_b128 v[92:95], v1 offset:11776
	s_add_u32 s40, s40, 0x30000
	s_addc_u32 s41, s41, 0
	s_waitcnt vmcnt(42) lgkmcnt(3)
	v_cvt_pk_bf16_f32 v10, v2, v3
	v_cvt_pk_bf16_f32 v11, v4, v5
	v_lshlrev_b32_e32 v6, 16, v54
	v_and_b32_e32 v7, 0xffff0000, v54
	v_lshlrev_b32_e32 v8, 16, v55
	v_and_b32_e32 v9, 0xffff0000, v55
	v_pk_fma_f32 v[2:3], v[2:3], v[80:81], v[6:7]
	v_pk_fma_f32 v[4:5], v[4:5], v[82:83], v[8:9]
	global_store_dwordx2 v0, v[10:11], s[40:41]
	ds_read_b128 v[80:83], v1 offset:12288
	s_add_u32 s40, s40, 0x30000
	s_addc_u32 s41, s41, 0
	s_waitcnt vmcnt(41) lgkmcnt(3)
	v_cvt_pk_bf16_f32 v12, v2, v3
	v_cvt_pk_bf16_f32 v13, v4, v5
	v_lshlrev_b32_e32 v6, 16, v56
	v_and_b32_e32 v7, 0xffff0000, v56
	v_lshlrev_b32_e32 v8, 16, v57
	v_and_b32_e32 v9, 0xffff0000, v57
	v_pk_fma_f32 v[2:3], v[2:3], v[84:85], v[6:7]
	v_pk_fma_f32 v[4:5], v[4:5], v[86:87], v[8:9]
	global_store_dwordx2 v0, v[12:13], s[40:41]
	ds_read_b128 v[84:87], v1 offset:12800
	s_add_u32 s40, s40, 0x30000
	s_addc_u32 s41, s41, 0
	s_waitcnt vmcnt(40) lgkmcnt(3)
	v_cvt_pk_bf16_f32 v10, v2, v3
	v_cvt_pk_bf16_f32 v11, v4, v5
	v_lshlrev_b32_e32 v6, 16, v58
	v_and_b32_e32 v7, 0xffff0000, v58
	v_lshlrev_b32_e32 v8, 16, v59
	v_and_b32_e32 v9, 0xffff0000, v59
	v_pk_fma_f32 v[2:3], v[2:3], v[88:89], v[6:7]
	v_pk_fma_f32 v[4:5], v[4:5], v[90:91], v[8:9]
	global_store_dwordx2 v0, v[10:11], s[40:41]
	ds_read_b128 v[88:91], v1 offset:13312
	s_add_u32 s40, s40, 0x30000
	s_addc_u32 s41, s41, 0
	s_waitcnt vmcnt(39) lgkmcnt(3)
	v_cvt_pk_bf16_f32 v12, v2, v3
	v_cvt_pk_bf16_f32 v13, v4, v5
	v_lshlrev_b32_e32 v6, 16, v60
	v_and_b32_e32 v7, 0xffff0000, v60
	v_lshlrev_b32_e32 v8, 16, v61
	v_and_b32_e32 v9, 0xffff0000, v61
	v_pk_fma_f32 v[2:3], v[2:3], v[92:93], v[6:7]
	v_pk_fma_f32 v[4:5], v[4:5], v[94:95], v[8:9]
	global_store_dwordx2 v0, v[12:13], s[40:41]
	ds_read_b128 v[92:95], v1 offset:13824
	s_add_u32 s40, s40, 0x30000
	s_addc_u32 s41, s41, 0
	s_waitcnt vmcnt(38) lgkmcnt(3)
; __device__ __forceinline__ unsigned cvt_pk_bf16(float lo, float hi) { const f32x2 f = {lo, hi}; const bf16x2_t v = __builtin_convertvector(f, bf16x2_t); return __builtin_bit_cast(unsigned, v); }
; __device__ __forceinline__ float bflo(unsigned u) { return __uint_as_float(u << 16); }
; __device__ __forceinline__ float bfhi(unsigned u) { return __uint_as_float(u & 0xffff0000u); }
; __device__ __forceinline__ float c_gl2(int h) { return log2f(1.f - exp2f(-5.f - (float)h)); }
; __device__ __forceinline__ void phase_scan(const Params& P, int tid) {
;     ...
;             for (int n0 = 0; n0 < 256; n0 += 16) {
;                 u32x2 d[16]; f32x4 dc[16];
; #pragma unroll
;                 for (int j = 0; j < 16; ++j) { d[j] = *(const u32x2*)(sp + (size_t)(n0 + j) * (6 * 16384)); dc[j] = *(const f32x4*)(dp + (size_t)(n0 + j) * 768); }
; #pragma unroll
;                 for (int j = 0; j < 16; ++j) { u32x2 o; o.x = cvt_pk_bf16(S[0], S[1]); o.y = cvt_pk_bf16(S[2], S[3]);
;                     S[0] = dc[j][0] * S[0] + bflo(d[j].x); S[1] = dc[j][1] * S[1] + bfhi(d[j].x); S[2] = dc[j][2] * S[2] + bflo(d[j].y); S[3] = dc[j][3] * S[3] + bfhi(d[j].y);
;                     *(u32x2*)(sp + (size_t)(n0 + j) * (6 * 16384)) = o; }
;             }
;         } else {
;             const int i2 = idx - 49152, bh = i2 >> 11, e = (i2 & 2047) * 4, b = bh / 5, h = bh % 5;
;             bf16_t* sp = (bf16_t*)(P.ws + WS_STC) + (size_t)(b * 256 * 5 + h) * 8192 + e;
;             const float cd = exp2f(64.f * c_gl2(h));
;             f32x4 S = (f32x4){0.f, 0.f, 0.f, 0.f};
;             for (int n0 = 0; n0 < 256; n0 += 16) {
;                 u32x2 d[16];
; #pragma unroll
;                 for (int j = 0; j < 16; ++j) d[j] = *(const u32x2*)(sp + (size_t)(n0 + j) * (5 * 8192));
	v_cvt_pk_bf16_f32 v10, v2, v3
	v_cvt_pk_bf16_f32 v11, v4, v5
	v_lshlrev_b32_e32 v6, 16, v62
	v_and_b32_e32 v7, 0xffff0000, v62
	v_lshlrev_b32_e32 v8, 16, v63
	v_and_b32_e32 v9, 0xffff0000, v63
	v_pk_fma_f32 v[2:3], v[2:3], v[80:81], v[6:7]
	v_pk_fma_f32 v[4:5], v[4:5], v[82:83], v[8:9]
	global_store_dwordx2 v0, v[10:11], s[40:41]
	ds_read_b128 v[80:83], v1 offset:14336
	s_add_u32 s40, s40, 0x30000
	s_addc_u32 s41, s41, 0
	s_waitcnt vmcnt(37) lgkmcnt(3)
	v_cvt_pk_bf16_f32 v12, v2, v3
	v_cvt_pk_bf16_f32 v13, v4, v5
	v_lshlrev_b32_e32 v6, 16, v64
	v_and_b32_e32 v7, 0xffff0000, v64
	v_lshlrev_b32_e32 v8, 16, v65
	v_and_b32_e32 v9, 0xffff0000, v65
	v_pk_fma_f32 v[2:3], v[2:3], v[84:85], v[6:7]
	v_pk_fma_f32 v[4:5], v[4:5], v[86:87], v[8:9]
	global_store_dwordx2 v0, v[12:13], s[40:41]
	ds_read_b128 v[84:87], v1 offset:14848
	s_add_u32 s40, s40, 0x30000
	s_addc_u32 s41, s41, 0
	s_waitcnt vmcnt(36) lgkmcnt(3)
	v_cvt_pk_bf16_f32 v10, v2, v3
	v_cvt_pk_bf16_f32 v11, v4, v5
	v_lshlrev_b32_e32 v6, 16, v66
	v_and_b32_e32 v7, 0xffff0000, v66
	v_lshlrev_b32_e32 v8, 16, v67
	v_and_b32_e32 v9, 0xffff0000, v67
	v_pk_fma_f32 v[2:3], v[2:3], v[88:89], v[6:7]
	v_pk_fma_f32 v[4:5], v[4:5], v[90:91], v[8:9]
	global_store_dwordx2 v0, v[10:11], s[40:41]
	ds_read_b128 v[88:91], v1 offset:15360
	s_add_u32 s40, s40, 0x30000
	s_addc_u32 s41, s41, 0
	s_waitcnt vmcnt(35) lgkmcnt(3)
	v_cvt_pk_bf16_f32 v12, v2, v3
	v_cvt_pk_bf16_f32 v13, v4, v5
	v_lshlrev_b32_e32 v6, 16, v68
	v_and_b32_e32 v7, 0xffff0000, v68
	v_lshlrev_b32_e32 v8, 16, v69
	v_and_b32_e32 v9, 0xffff0000, v69
	v_pk_fma_f32 v[2:3], v[2:3], v[92:93], v[6:7]
	v_pk_fma_f32 v[4:5], v[4:5], v[94:95], v[8:9]
	global_store_dwordx2 v0, v[12:13], s[40:41]
	ds_read_b128 v[92:95], v1 offset:15872
	s_add_u32 s40, s40, 0x30000
	s_addc_u32 s41, s41, 0
	s_waitcnt vmcnt(34) lgkmcnt(3)
	v_cvt_pk_bf16_f32 v10, v2, v3
	v_cvt_pk_bf16_f32 v11, v4, v5
	v_lshlrev_b32_e32 v6, 16, v70
	v_and_b32_e32 v7, 0xffff0000, v70
	v_lshlrev_b32_e32 v8, 16, v71
	v_and_b32_e32 v9, 0xffff0000, v71
	v_pk_fma_f32 v[2:3], v[2:3], v[80:81], v[6:7]
	v_pk_fma_f32 v[4:5], v[4:5], v[82:83], v[8:9]
	global_store_dwordx2 v0, v[10:11], s[40:41]
	s_add_u32 s40, s40, 0x30000
	s_addc_u32 s41, s41, 0
	s_waitcnt vmcnt(33) lgkmcnt(2)
	v_cvt_pk_bf16_f32 v12, v2, v3
	v_cvt_pk_bf16_f32 v13, v4, v5
	v_lshlrev_b32_e32 v6, 16, v72
	v_and_b32_e32 v7, 0xffff0000, v72
	v_lshlrev_b32_e32 v8, 16, v73
	v_and_b32_e32 v9, 0xffff0000, v73
	v_pk_fma_f32 v[2:3], v[2:3], v[84:85], v[6:7]
	v_pk_fma_f32 v[4:5], v[4:5], v[86:87], v[8:9]
	global_store_dwordx2 v0, v[12:13], s[40:41]
	s_add_u32 s40, s40, 0x30000
	s_addc_u32 s41, s41, 0
	s_waitcnt vmcnt(32) lgkmcnt(1)
	v_cvt_pk_bf16_f32 v10, v2, v3
	v_cvt_pk_bf16_f32 v11, v4, v5
	v_lshlrev_b32_e32 v6, 16, v74
	v_and_b32_e32 v7, 0xffff0000, v74
	v_lshlrev_b32_e32 v8, 16, v75
	v_and_b32_e32 v9, 0xffff0000, v75
	v_pk_fma_f32 v[2:3], v[2:3], v[88:89], v[6:7]
	v_pk_fma_f32 v[4:5], v[4:5], v[90:91], v[8:9]
	global_store_dwordx2 v0, v[10:11], s[40:41]
	s_add_u32 s40, s40, 0x30000
	s_addc_u32 s41, s41, 0
	s_waitcnt vmcnt(31) lgkmcnt(0)
	v_cvt_pk_bf16_f32 v12, v2, v3
	v_cvt_pk_bf16_f32 v13, v4, v5
	v_lshlrev_b32_e32 v6, 16, v76
	v_and_b32_e32 v7, 0xffff0000, v76
	v_lshlrev_b32_e32 v8, 16, v77
	v_and_b32_e32 v9, 0xffff0000, v77
	v_pk_fma_f32 v[2:3], v[2:3], v[92:93], v[6:7]
	v_pk_fma_f32 v[4:5], v[4:5], v[94:95], v[8:9]
	global_store_dwordx2 v0, v[12:13], s[40:41]
	s_add_u32 s40, s40, 0x30000
	s_addc_u32 s41, s41, 0
	s_branch .Lscan_done
.Lscan_c:
	s_sub_u32 s0, s68, 0xc000
	s_lshr_b32 s1, s0, 11
	s_lshr_b32 s0, s0, 9
	s_lshr_b32 s8, s1, 1
	s_add_u32 s0, s0, s8
	s_and_b32 s0, s0, 3
	s_lshl_b32 s0, s0, 12
	s_cmp_gt_u32 s1, 4
	s_cselect_b32 s8, 5, 0
	s_cselect_b32 s18, 0x500, 0
	s_sub_u32 s1, s1, s8
	s_add_u32 s18, s18, s1
	s_lshl_b32 s18, s18, 14
	s_add_u32 s18, s18, s0
	v_readlane_b32 s0, v248, 53
	v_mov_b32_e32 v1, s1
	s_add_u32 s14, s0, s36
	v_readlane_b32 s0, v248, 54
	s_addc_u32 s15, s0, s37
	s_add_u32 s14, s14, s18
	s_addc_u32 s15, s15, 0
	s_mov_b64 s[40:41], s[14:15]
	global_load_dwordx2 v[16:17], v0, s[14:15]
	s_add_u32 s14, s14, 0x14000
	s_addc_u32 s15, s15, 0
	global_load_dwordx2 v[18:19], v0, s[14:15]
	s_add_u32 s14, s14, 0x14000
	s_addc_u32 s15, s15, 0
	global_load_dwordx2 v[20:21], v0, s[14:15]
	s_add_u32 s14, s14, 0x14000
	s_addc_u32 s15, s15, 0
	global_load_dwordx2 v[22:23], v0, s[14:15]
	s_add_u32 s14, s14, 0x14000
	s_addc_u32 s15, s15, 0
	global_load_dwordx2 v[24:25], v0, s[14:15]
	s_add_u32 s14, s14, 0x14000
	s_addc_u32 s15, s15, 0
	global_load_dwordx2 v[26:27], v0, s[14:15]
	s_add_u32 s14, s14, 0x14000
	s_addc_u32 s15, s15, 0
	global_load_dwordx2 v[28:29], v0, s[14:15]
	s_add_u32 s14, s14, 0x14000
	s_addc_u32 s15, s15, 0
	global_load_dwordx2 v[30:31], v0, s[14:15]
	s_add_u32 s14, s14, 0x14000
	s_addc_u32 s15, s15, 0
	global_load_dwordx2 v[32:33], v0, s[14:15]
	s_add_u32 s14, s14, 0x14000
	s_addc_u32 s15, s15, 0
	global_load_dwordx2 v[34:35], v0, s[14:15]
	s_add_u32 s14, s14, 0x14000
	s_addc_u32 s15, s15, 0
	global_load_dwordx2 v[36:37], v0, s[14:15]
	s_add_u32 s14, s14, 0x14000
	s_addc_u32 s15, s15, 0
	global_load_dwordx2 v[38:39], v0, s[14:15]
	s_add_u32 s14, s14, 0x14000
	s_addc_u32 s15, s15, 0
	global_load_dwordx2 v[40:41], v0, s[14:15]
	s_add_u32 s14, s14, 0x14000
	s_addc_u32 s15, s15, 0
	global_load_dwordx2 v[42:43], v0, s[14:15]
	s_add_u32 s14, s14, 0x14000
	s_addc_u32 s15, s15, 0
	global_load_dwordx2 v[44:45], v0, s[14:15]
	s_add_u32 s14, s14, 0x14000
	s_addc_u32 s15, s15, 0
	global_load_dwordx2 v[46:47], v0, s[14:15]
	s_add_u32 s14, s14, 0x14000
	s_addc_u32 s15, s15, 0
	global_load_dwordx2 v[48:49], v0, s[14:15]
; __device__ __forceinline__ unsigned cvt_pk_bf16(float lo, float hi) { const f32x2 f = {lo, hi}; const bf16x2_t v = __builtin_convertvector(f, bf16x2_t); return __builtin_bit_cast(unsigned, v); }
; __device__ __forceinline__ float bflo(unsigned u) { return __uint_as_float(u << 16); }
; __device__ __forceinline__ float bfhi(unsigned u) { return __uint_as_float(u & 0xffff0000u); }
; __device__ __forceinline__ float c_gl2(int h) { return log2f(1.f - exp2f(-5.f - (float)h)); }
; __device__ __forceinline__ void phase_scan(const Params& P, int tid) {
;     ...
;             const int i2 = idx - 49152, bh = i2 >> 11, e = (i2 & 2047) * 4, b = bh / 5, h = bh % 5;
;             bf16_t* sp = (bf16_t*)(P.ws + WS_STC) + (size_t)(b * 256 * 5 + h) * 8192 + e;
;             const float cd = exp2f(64.f * c_gl2(h));
;             f32x4 S = (f32x4){0.f, 0.f, 0.f, 0.f};
;             for (int n0 = 0; n0 < 256; n0 += 16) {
;                 u32x2 d[16];
; #pragma unroll
;                 for (int j = 0; j < 16; ++j) d[j] = *(const u32x2*)(sp + (size_t)(n0 + j) * (5 * 8192));
; #pragma unroll
;                 for (int j = 0; j < 16; ++j) { u32x2 o; o.x = cvt_pk_bf16(S[0], S[1]); o.y = cvt_pk_bf16(S[2], S[3]);
;                     S[0] = cd * S[0] + bflo(d[j].x); S[1] = cd * S[1] + bfhi(d[j].x); S[2] = cd * S[2] + bflo(d[j].y); S[3] = cd * S[3] + bfhi(d[j].y);
;                     *(u32x2*)(sp + (size_t)(n0 + j) * (5 * 8192)) = o; }
	s_add_u32 s14, s14, 0x14000
	s_addc_u32 s15, s15, 0
	global_load_dwordx2 v[50:51], v0, s[14:15]
	s_add_u32 s14, s14, 0x14000
	s_addc_u32 s15, s15, 0
	global_load_dwordx2 v[52:53], v0, s[14:15]
	s_add_u32 s14, s14, 0x14000
	s_addc_u32 s15, s15, 0
	global_load_dwordx2 v[54:55], v0, s[14:15]
	s_add_u32 s14, s14, 0x14000
	s_addc_u32 s15, s15, 0
	global_load_dwordx2 v[56:57], v0, s[14:15]
	s_add_u32 s14, s14, 0x14000
	s_addc_u32 s15, s15, 0
	global_load_dwordx2 v[58:59], v0, s[14:15]
	s_add_u32 s14, s14, 0x14000
	s_addc_u32 s15, s15, 0
	global_load_dwordx2 v[60:61], v0, s[14:15]
	s_add_u32 s14, s14, 0x14000
	s_addc_u32 s15, s15, 0
	global_load_dwordx2 v[62:63], v0, s[14:15]
	s_add_u32 s14, s14, 0x14000
	s_addc_u32 s15, s15, 0
	global_load_dwordx2 v[64:65], v0, s[14:15]
	s_add_u32 s14, s14, 0x14000
	s_addc_u32 s15, s15, 0
	global_load_dwordx2 v[66:67], v0, s[14:15]
	s_add_u32 s14, s14, 0x14000
	s_addc_u32 s15, s15, 0
	global_load_dwordx2 v[68:69], v0, s[14:15]
	s_add_u32 s14, s14, 0x14000
	s_addc_u32 s15, s15, 0
	global_load_dwordx2 v[70:71], v0, s[14:15]
	s_add_u32 s14, s14, 0x14000
	s_addc_u32 s15, s15, 0
	global_load_dwordx2 v[72:73], v0, s[14:15]
	s_add_u32 s14, s14, 0x14000
	s_addc_u32 s15, s15, 0
	global_load_dwordx2 v[74:75], v0, s[14:15]
	s_add_u32 s14, s14, 0x14000
	s_addc_u32 s15, s15, 0
	global_load_dwordx2 v[76:77], v0, s[14:15]
	s_add_u32 s14, s14, 0x14000
	s_addc_u32 s15, s15, 0
	global_load_dwordx2 v[78:79], v0, s[14:15]
	s_add_u32 s14, s14, 0x14000
	s_addc_u32 s15, s15, 0
	v_cvt_f32_i32_e32 v6, v1
	v_sub_f32_e32 v6, 0xc0a00000, v6
	v_cmp_gt_f32_e32 vcc, s95, v6
	s_nop 1
	v_cndmask_b32_e32 v7, 0, v185, vcc
	v_add_f32_e32 v6, v6, v7
	v_exp_f32_e32 v6, v6
	v_cndmask_b32_e32 v7, 0, v187, vcc
	s_nop 0
	v_ldexp_f32 v6, v6, v7
	v_sub_f32_e32 v6, 1.0, v6
	v_cmp_gt_f32_e32 vcc, s77, v6
	s_nop 1
	v_cndmask_b32_e64 v7, 0, 32, vcc
	v_ldexp_f32 v6, v6, v7
	v_log_f32_e32 v6, v6
	v_cndmask_b32_e32 v8, 0, v186, vcc
	s_nop 0
	v_sub_f32_e32 v8, v6, v8
	v_mul_f32_e32 v9, 0x42800000, v8
	v_cmp_gt_f32_e32 vcc, s95, v9
	s_nop 1
	v_cndmask_b32_e32 v9, 0, v185, vcc
	v_fmac_f32_e32 v9, 0x42800000, v8
	v_exp_f32_e32 v8, v9
	v_cndmask_b32_e32 v9, 0, v187, vcc
	s_nop 0
	v_ldexp_f32 v10, v8, v9
	s_nop 0
	v_mov_b32_e32 v11, v10
	s_waitcnt vmcnt(31)
	v_cvt_pk_bf16_f32 v12, v2, v3
	v_cvt_pk_bf16_f32 v13, v4, v5
	v_lshlrev_b32_e32 v6, 16, v16
	v_and_b32_e32 v7, 0xffff0000, v16
	v_lshlrev_b32_e32 v8, 16, v17
	v_and_b32_e32 v9, 0xffff0000, v17
	v_pk_fma_f32 v[2:3], v[10:11], v[2:3], v[6:7]
	v_pk_fma_f32 v[4:5], v[10:11], v[4:5], v[8:9]
	global_store_dwordx2 v0, v[12:13], s[40:41]
	s_add_u32 s40, s40, 0x14000
	s_addc_u32 s41, s41, 0
	global_load_dwordx2 v[16:17], v0, s[14:15]
	s_add_u32 s14, s14, 0x14000
	s_addc_u32 s15, s15, 0
	s_waitcnt vmcnt(32)
	v_cvt_pk_bf16_f32 v14, v2, v3
	v_cvt_pk_bf16_f32 v15, v4, v5
	v_lshlrev_b32_e32 v6, 16, v18
	v_and_b32_e32 v7, 0xffff0000, v18
	v_lshlrev_b32_e32 v8, 16, v19
	v_and_b32_e32 v9, 0xffff0000, v19
	v_pk_fma_f32 v[2:3], v[10:11], v[2:3], v[6:7]
	v_pk_fma_f32 v[4:5], v[10:11], v[4:5], v[8:9]
	global_store_dwordx2 v0, v[14:15], s[40:41]
	s_add_u32 s40, s40, 0x14000
	s_addc_u32 s41, s41, 0
	global_load_dwordx2 v[18:19], v0, s[14:15]
	s_add_u32 s14, s14, 0x14000
	s_addc_u32 s15, s15, 0
	s_waitcnt vmcnt(33)
	v_cvt_pk_bf16_f32 v12, v2, v3
	v_cvt_pk_bf16_f32 v13, v4, v5
	v_lshlrev_b32_e32 v6, 16, v20
	v_and_b32_e32 v7, 0xffff0000, v20
	v_lshlrev_b32_e32 v8, 16, v21
	v_and_b32_e32 v9, 0xffff0000, v21
	v_pk_fma_f32 v[2:3], v[10:11], v[2:3], v[6:7]
	v_pk_fma_f32 v[4:5], v[10:11], v[4:5], v[8:9]
	global_store_dwordx2 v0, v[12:13], s[40:41]
	s_add_u32 s40, s40, 0x14000
	s_addc_u32 s41, s41, 0
	global_load_dwordx2 v[20:21], v0, s[14:15]
	s_add_u32 s14, s14, 0x14000
	s_addc_u32 s15, s15, 0
	s_waitcnt vmcnt(34)
	v_cvt_pk_bf16_f32 v14, v2, v3
	v_cvt_pk_bf16_f32 v15, v4, v5
	v_lshlrev_b32_e32 v6, 16, v22
	v_and_b32_e32 v7, 0xffff0000, v22
	v_lshlrev_b32_e32 v8, 16, v23
	v_and_b32_e32 v9, 0xffff0000, v23
	v_pk_fma_f32 v[2:3], v[10:11], v[2:3], v[6:7]
	v_pk_fma_f32 v[4:5], v[10:11], v[4:5], v[8:9]
	global_store_dwordx2 v0, v[14:15], s[40:41]
	s_add_u32 s40, s40, 0x14000
	s_addc_u32 s41, s41, 0
	global_load_dwordx2 v[22:23], v0, s[14:15]
	s_add_u32 s14, s14, 0x14000
	s_addc_u32 s15, s15, 0
	s_waitcnt vmcnt(35)
	v_cvt_pk_bf16_f32 v12, v2, v3
	v_cvt_pk_bf16_f32 v13, v4, v5
	v_lshlrev_b32_e32 v6, 16, v24
	v_and_b32_e32 v7, 0xffff0000, v24
	v_lshlrev_b32_e32 v8, 16, v25
	v_and_b32_e32 v9, 0xffff0000, v25
	v_pk_fma_f32 v[2:3], v[10:11], v[2:3], v[6:7]
	v_pk_fma_f32 v[4:5], v[10:11], v[4:5], v[8:9]
	global_store_dwordx2 v0, v[12:13], s[40:41]
	s_add_u32 s40, s40, 0x14000
	s_addc_u32 s41, s41, 0
	global_load_dwordx2 v[24:25], v0, s[14:15]
	s_add_u32 s14, s14, 0x14000
	s_addc_u32 s15, s15, 0
	s_waitcnt vmcnt(36)
	v_cvt_pk_bf16_f32 v14, v2, v3
	v_cvt_pk_bf16_f32 v15, v4, v5
	v_lshlrev_b32_e32 v6, 16, v26
	v_and_b32_e32 v7, 0xffff0000, v26
	v_lshlrev_b32_e32 v8, 16, v27
	v_and_b32_e32 v9, 0xffff0000, v27
	v_pk_fma_f32 v[2:3], v[10:11], v[2:3], v[6:7]
	v_pk_fma_f32 v[4:5], v[10:11], v[4:5], v[8:9]
	global_store_dwordx2 v0, v[14:15], s[40:41]
	s_add_u32 s40, s40, 0x14000
	s_addc_u32 s41, s41, 0
	global_load_dwordx2 v[26:27], v0, s[14:15]
	s_add_u32 s14, s14, 0x14000
	s_addc_u32 s15, s15, 0
	s_waitcnt vmcnt(37)
	v_cvt_pk_bf16_f32 v12, v2, v3
	v_cvt_pk_bf16_f32 v13, v4, v5
	v_lshlrev_b32_e32 v6, 16, v28
	v_and_b32_e32 v7, 0xffff0000, v28
	v_lshlrev_b32_e32 v8, 16, v29
	v_and_b32_e32 v9, 0xffff0000, v29
	v_pk_fma_f32 v[2:3], v[10:11], v[2:3], v[6:7]
	v_pk_fma_f32 v[4:5], v[10:11], v[4:5], v[8:9]
	global_store_dwordx2 v0, v[12:13], s[40:41]
	s_add_u32 s40, s40, 0x14000
	s_addc_u32 s41, s41, 0
	global_load_dwordx2 v[28:29], v0, s[14:15]
	s_add_u32 s14, s14, 0x14000
	s_addc_u32 s15, s15, 0
	s_waitcnt vmcnt(38)
; __device__ __forceinline__ unsigned cvt_pk_bf16(float lo, float hi) { const f32x2 f = {lo, hi}; const bf16x2_t v = __builtin_convertvector(f, bf16x2_t); return __builtin_bit_cast(unsigned, v); }
; __device__ __forceinline__ float bflo(unsigned u) { return __uint_as_float(u << 16); }
; __device__ __forceinline__ float bfhi(unsigned u) { return __uint_as_float(u & 0xffff0000u); }
; __device__ __forceinline__ void phase_scan(const Params& P, int tid) {
;     ...
;             for (int n0 = 0; n0 < 256; n0 += 16) {
;                 u32x2 d[16];
; #pragma unroll
;                 for (int j = 0; j < 16; ++j) d[j] = *(const u32x2*)(sp + (size_t)(n0 + j) * (5 * 8192));
; #pragma unroll
;                 for (int j = 0; j < 16; ++j) { u32x2 o; o.x = cvt_pk_bf16(S[0], S[1]); o.y = cvt_pk_bf16(S[2], S[3]);
;                     S[0] = cd * S[0] + bflo(d[j].x); S[1] = cd * S[1] + bfhi(d[j].x); S[2] = cd * S[2] + bflo(d[j].y); S[3] = cd * S[3] + bfhi(d[j].y);
;                     *(u32x2*)(sp + (size_t)(n0 + j) * (5 * 8192)) = o; }
;             }
	v_cvt_pk_bf16_f32 v14, v2, v3
	v_cvt_pk_bf16_f32 v15, v4, v5
	v_lshlrev_b32_e32 v6, 16, v30
	v_and_b32_e32 v7, 0xffff0000, v30
	v_lshlrev_b32_e32 v8, 16, v31
	v_and_b32_e32 v9, 0xffff0000, v31
	v_pk_fma_f32 v[2:3], v[10:11], v[2:3], v[6:7]
	v_pk_fma_f32 v[4:5], v[10:11], v[4:5], v[8:9]
	global_store_dwordx2 v0, v[14:15], s[40:41]
	s_add_u32 s40, s40, 0x14000
	s_addc_u32 s41, s41, 0
	global_load_dwordx2 v[30:31], v0, s[14:15]
	s_add_u32 s14, s14, 0x14000
	s_addc_u32 s15, s15, 0
	s_waitcnt vmcnt(39)
	v_cvt_pk_bf16_f32 v12, v2, v3
	v_cvt_pk_bf16_f32 v13, v4, v5
	v_lshlrev_b32_e32 v6, 16, v32
	v_and_b32_e32 v7, 0xffff0000, v32
	v_lshlrev_b32_e32 v8, 16, v33
	v_and_b32_e32 v9, 0xffff0000, v33
	v_pk_fma_f32 v[2:3], v[10:11], v[2:3], v[6:7]
	v_pk_fma_f32 v[4:5], v[10:11], v[4:5], v[8:9]
	global_store_dwordx2 v0, v[12:13], s[40:41]
	s_add_u32 s40, s40, 0x14000
	s_addc_u32 s41, s41, 0
	global_load_dwordx2 v[32:33], v0, s[14:15]
	s_add_u32 s14, s14, 0x14000
	s_addc_u32 s15, s15, 0
	s_waitcnt vmcnt(40)
	v_cvt_pk_bf16_f32 v14, v2, v3
	v_cvt_pk_bf16_f32 v15, v4, v5
	v_lshlrev_b32_e32 v6, 16, v34
	v_and_b32_e32 v7, 0xffff0000, v34
	v_lshlrev_b32_e32 v8, 16, v35
	v_and_b32_e32 v9, 0xffff0000, v35
	v_pk_fma_f32 v[2:3], v[10:11], v[2:3], v[6:7]
	v_pk_fma_f32 v[4:5], v[10:11], v[4:5], v[8:9]
	global_store_dwordx2 v0, v[14:15], s[40:41]
	s_add_u32 s40, s40, 0x14000
	s_addc_u32 s41, s41, 0
	global_load_dwordx2 v[34:35], v0, s[14:15]
	s_add_u32 s14, s14, 0x14000
	s_addc_u32 s15, s15, 0
	s_waitcnt vmcnt(41)
	v_cvt_pk_bf16_f32 v12, v2, v3
	v_cvt_pk_bf16_f32 v13, v4, v5
	v_lshlrev_b32_e32 v6, 16, v36
	v_and_b32_e32 v7, 0xffff0000, v36
	v_lshlrev_b32_e32 v8, 16, v37
	v_and_b32_e32 v9, 0xffff0000, v37
	v_pk_fma_f32 v[2:3], v[10:11], v[2:3], v[6:7]
	v_pk_fma_f32 v[4:5], v[10:11], v[4:5], v[8:9]
	global_store_dwordx2 v0, v[12:13], s[40:41]
	s_add_u32 s40, s40, 0x14000
	s_addc_u32 s41, s41, 0
	global_load_dwordx2 v[36:37], v0, s[14:15]
	s_add_u32 s14, s14, 0x14000
	s_addc_u32 s15, s15, 0
	s_waitcnt vmcnt(42)
	v_cvt_pk_bf16_f32 v14, v2, v3
	v_cvt_pk_bf16_f32 v15, v4, v5
	v_lshlrev_b32_e32 v6, 16, v38
	v_and_b32_e32 v7, 0xffff0000, v38
	v_lshlrev_b32_e32 v8, 16, v39
	v_and_b32_e32 v9, 0xffff0000, v39
	v_pk_fma_f32 v[2:3], v[10:11], v[2:3], v[6:7]
	v_pk_fma_f32 v[4:5], v[10:11], v[4:5], v[8:9]
	global_store_dwordx2 v0, v[14:15], s[40:41]
	s_add_u32 s40, s40, 0x14000
	s_addc_u32 s41, s41, 0
	global_load_dwordx2 v[38:39], v0, s[14:15]
	s_add_u32 s14, s14, 0x14000
	s_addc_u32 s15, s15, 0
	s_waitcnt vmcnt(43)
	v_cvt_pk_bf16_f32 v12, v2, v3
	v_cvt_pk_bf16_f32 v13, v4, v5
	v_lshlrev_b32_e32 v6, 16, v40
	v_and_b32_e32 v7, 0xffff0000, v40
	v_lshlrev_b32_e32 v8, 16, v41
	v_and_b32_e32 v9, 0xffff0000, v41
	v_pk_fma_f32 v[2:3], v[10:11], v[2:3], v[6:7]
	v_pk_fma_f32 v[4:5], v[10:11], v[4:5], v[8:9]
	global_store_dwordx2 v0, v[12:13], s[40:41]
	s_add_u32 s40, s40, 0x14000
	s_addc_u32 s41, s41, 0
	global_load_dwordx2 v[40:41], v0, s[14:15]
	s_add_u32 s14, s14, 0x14000
	s_addc_u32 s15, s15, 0
	s_waitcnt vmcnt(44)
	v_cvt_pk_bf16_f32 v14, v2, v3
	v_cvt_pk_bf16_f32 v15, v4, v5
	v_lshlrev_b32_e32 v6, 16, v42
	v_and_b32_e32 v7, 0xffff0000, v42
	v_lshlrev_b32_e32 v8, 16, v43
	v_and_b32_e32 v9, 0xffff0000, v43
	v_pk_fma_f32 v[2:3], v[10:11], v[2:3], v[6:7]
	v_pk_fma_f32 v[4:5], v[10:11], v[4:5], v[8:9]
	global_store_dwordx2 v0, v[14:15], s[40:41]
	s_add_u32 s40, s40, 0x14000
	s_addc_u32 s41, s41, 0
	global_load_dwordx2 v[42:43], v0, s[14:15]
	s_add_u32 s14, s14, 0x14000
	s_addc_u32 s15, s15, 0
	s_waitcnt vmcnt(45)
	v_cvt_pk_bf16_f32 v12, v2, v3
	v_cvt_pk_bf16_f32 v13, v4, v5
	v_lshlrev_b32_e32 v6, 16, v44
	v_and_b32_e32 v7, 0xffff0000, v44
	v_lshlrev_b32_e32 v8, 16, v45
	v_and_b32_e32 v9, 0xffff0000, v45
	v_pk_fma_f32 v[2:3], v[10:11], v[2:3], v[6:7]
	v_pk_fma_f32 v[4:5], v[10:11], v[4:5], v[8:9]
	global_store_dwordx2 v0, v[12:13], s[40:41]
	s_add_u32 s40, s40, 0x14000
	s_addc_u32 s41, s41, 0
	global_load_dwordx2 v[44:45], v0, s[14:15]
	s_add_u32 s14, s14, 0x14000
	s_addc_u32 s15, s15, 0
	s_waitcnt vmcnt(46)
	v_cvt_pk_bf16_f32 v14, v2, v3
	v_cvt_pk_bf16_f32 v15, v4, v5
	v_lshlrev_b32_e32 v6, 16, v46
	v_and_b32_e32 v7, 0xffff0000, v46
	v_lshlrev_b32_e32 v8, 16, v47
	v_and_b32_e32 v9, 0xffff0000, v47
	v_pk_fma_f32 v[2:3], v[10:11], v[2:3], v[6:7]
	v_pk_fma_f32 v[4:5], v[10:11], v[4:5], v[8:9]
	global_store_dwordx2 v0, v[14:15], s[40:41]
	s_add_u32 s40, s40, 0x14000
	s_addc_u32 s41, s41, 0
	global_load_dwordx2 v[46:47], v0, s[14:15]
	s_add_u32 s14, s14, 0x14000
	s_addc_u32 s15, s15, 0
	s_waitcnt vmcnt(47)
	v_cvt_pk_bf16_f32 v12, v2, v3
	v_cvt_pk_bf16_f32 v13, v4, v5
	v_lshlrev_b32_e32 v6, 16, v48
	v_and_b32_e32 v7, 0xffff0000, v48
	v_lshlrev_b32_e32 v8, 16, v49
	v_and_b32_e32 v9, 0xffff0000, v49
	v_pk_fma_f32 v[2:3], v[10:11], v[2:3], v[6:7]
	v_pk_fma_f32 v[4:5], v[10:11], v[4:5], v[8:9]
	global_store_dwordx2 v0, v[12:13], s[40:41]
	s_add_u32 s40, s40, 0x14000
	s_addc_u32 s41, s41, 0
	global_load_dwordx2 v[48:49], v0, s[14:15]
	s_add_u32 s14, s14, 0x14000
	s_addc_u32 s15, s15, 0
	s_waitcnt vmcnt(48)
	v_cvt_pk_bf16_f32 v14, v2, v3
	v_cvt_pk_bf16_f32 v15, v4, v5
	v_lshlrev_b32_e32 v6, 16, v50
	v_and_b32_e32 v7, 0xffff0000, v50
	v_lshlrev_b32_e32 v8, 16, v51
	v_and_b32_e32 v9, 0xffff0000, v51
	v_pk_fma_f32 v[2:3], v[10:11], v[2:3], v[6:7]
	v_pk_fma_f32 v[4:5], v[10:11], v[4:5], v[8:9]
	global_store_dwordx2 v0, v[14:15], s[40:41]
	s_add_u32 s40, s40, 0x14000
	s_addc_u32 s41, s41, 0
	global_load_dwordx2 v[50:51], v0, s[14:15]
	s_add_u32 s14, s14, 0x14000
	s_addc_u32 s15, s15, 0
	s_waitcnt vmcnt(49)
; __device__ __forceinline__ unsigned cvt_pk_bf16(float lo, float hi) { const f32x2 f = {lo, hi}; const bf16x2_t v = __builtin_convertvector(f, bf16x2_t); return __builtin_bit_cast(unsigned, v); }
; __device__ __forceinline__ float bflo(unsigned u) { return __uint_as_float(u << 16); }
; __device__ __forceinline__ float bfhi(unsigned u) { return __uint_as_float(u & 0xffff0000u); }
; __device__ __forceinline__ void phase_scan(const Params& P, int tid) {
;     ...
;             for (int n0 = 0; n0 < 256; n0 += 16) {
;                 u32x2 d[16];
; #pragma unroll
;                 for (int j = 0; j < 16; ++j) d[j] = *(const u32x2*)(sp + (size_t)(n0 + j) * (5 * 8192));
; #pragma unroll
;                 for (int j = 0; j < 16; ++j) { u32x2 o; o.x = cvt_pk_bf16(S[0], S[1]); o.y = cvt_pk_bf16(S[2], S[3]);
;                     S[0] = cd * S[0] + bflo(d[j].x); S[1] = cd * S[1] + bfhi(d[j].x); S[2] = cd * S[2] + bflo(d[j].y); S[3] = cd * S[3] + bfhi(d[j].y);
;                     *(u32x2*)(sp + (size_t)(n0 + j) * (5 * 8192)) = o; }
;             }
	v_cvt_pk_bf16_f32 v12, v2, v3
	v_cvt_pk_bf16_f32 v13, v4, v5
	v_lshlrev_b32_e32 v6, 16, v52
	v_and_b32_e32 v7, 0xffff0000, v52
	v_lshlrev_b32_e32 v8, 16, v53
	v_and_b32_e32 v9, 0xffff0000, v53
	v_pk_fma_f32 v[2:3], v[10:11], v[2:3], v[6:7]
	v_pk_fma_f32 v[4:5], v[10:11], v[4:5], v[8:9]
	global_store_dwordx2 v0, v[12:13], s[40:41]
	s_add_u32 s40, s40, 0x14000
	s_addc_u32 s41, s41, 0
	global_load_dwordx2 v[52:53], v0, s[14:15]
	s_add_u32 s14, s14, 0x14000
	s_addc_u32 s15, s15, 0
	s_waitcnt vmcnt(50)
	v_cvt_pk_bf16_f32 v14, v2, v3
	v_cvt_pk_bf16_f32 v15, v4, v5
	v_lshlrev_b32_e32 v6, 16, v54
	v_and_b32_e32 v7, 0xffff0000, v54
	v_lshlrev_b32_e32 v8, 16, v55
	v_and_b32_e32 v9, 0xffff0000, v55
	v_pk_fma_f32 v[2:3], v[10:11], v[2:3], v[6:7]
	v_pk_fma_f32 v[4:5], v[10:11], v[4:5], v[8:9]
	global_store_dwordx2 v0, v[14:15], s[40:41]
	s_add_u32 s40, s40, 0x14000
	s_addc_u32 s41, s41, 0
	global_load_dwordx2 v[54:55], v0, s[14:15]
	s_add_u32 s14, s14, 0x14000
	s_addc_u32 s15, s15, 0
	s_waitcnt vmcnt(51)
	v_cvt_pk_bf16_f32 v12, v2, v3
	v_cvt_pk_bf16_f32 v13, v4, v5
	v_lshlrev_b32_e32 v6, 16, v56
	v_and_b32_e32 v7, 0xffff0000, v56
	v_lshlrev_b32_e32 v8, 16, v57
	v_and_b32_e32 v9, 0xffff0000, v57
	v_pk_fma_f32 v[2:3], v[10:11], v[2:3], v[6:7]
	v_pk_fma_f32 v[4:5], v[10:11], v[4:5], v[8:9]
	global_store_dwordx2 v0, v[12:13], s[40:41]
	s_add_u32 s40, s40, 0x14000
	s_addc_u32 s41, s41, 0
	global_load_dwordx2 v[56:57], v0, s[14:15]
	s_add_u32 s14, s14, 0x14000
	s_addc_u32 s15, s15, 0
	s_waitcnt vmcnt(52)
	v_cvt_pk_bf16_f32 v14, v2, v3
	v_cvt_pk_bf16_f32 v15, v4, v5
	v_lshlrev_b32_e32 v6, 16, v58
	v_and_b32_e32 v7, 0xffff0000, v58
	v_lshlrev_b32_e32 v8, 16, v59
	v_and_b32_e32 v9, 0xffff0000, v59
	v_pk_fma_f32 v[2:3], v[10:11], v[2:3], v[6:7]
	v_pk_fma_f32 v[4:5], v[10:11], v[4:5], v[8:9]
	global_store_dwordx2 v0, v[14:15], s[40:41]
	s_add_u32 s40, s40, 0x14000
	s_addc_u32 s41, s41, 0
	global_load_dwordx2 v[58:59], v0, s[14:15]
	s_add_u32 s14, s14, 0x14000
	s_addc_u32 s15, s15, 0
	s_waitcnt vmcnt(53)
	v_cvt_pk_bf16_f32 v12, v2, v3
	v_cvt_pk_bf16_f32 v13, v4, v5
	v_lshlrev_b32_e32 v6, 16, v60
	v_and_b32_e32 v7, 0xffff0000, v60
	v_lshlrev_b32_e32 v8, 16, v61
	v_and_b32_e32 v9, 0xffff0000, v61
	v_pk_fma_f32 v[2:3], v[10:11], v[2:3], v[6:7]
	v_pk_fma_f32 v[4:5], v[10:11], v[4:5], v[8:9]
	global_store_dwordx2 v0, v[12:13], s[40:41]
	s_add_u32 s40, s40, 0x14000
	s_addc_u32 s41, s41, 0
	global_load_dwordx2 v[60:61], v0, s[14:15]
	s_add_u32 s14, s14, 0x14000
	s_addc_u32 s15, s15, 0
	s_waitcnt vmcnt(54)
	v_cvt_pk_bf16_f32 v14, v2, v3
	v_cvt_pk_bf16_f32 v15, v4, v5
	v_lshlrev_b32_e32 v6, 16, v62
	v_and_b32_e32 v7, 0xffff0000, v62
	v_lshlrev_b32_e32 v8, 16, v63
	v_and_b32_e32 v9, 0xffff0000, v63
	v_pk_fma_f32 v[2:3], v[10:11], v[2:3], v[6:7]
	v_pk_fma_f32 v[4:5], v[10:11], v[4:5], v[8:9]
	global_store_dwordx2 v0, v[14:15], s[40:41]
	s_add_u32 s40, s40, 0x14000
	s_addc_u32 s41, s41, 0
	global_load_dwordx2 v[62:63], v0, s[14:15]
	s_add_u32 s14, s14, 0x14000
	s_addc_u32 s15, s15, 0
	s_waitcnt vmcnt(55)
	v_cvt_pk_bf16_f32 v12, v2, v3
	v_cvt_pk_bf16_f32 v13, v4, v5
	v_lshlrev_b32_e32 v6, 16, v64
	v_and_b32_e32 v7, 0xffff0000, v64
	v_lshlrev_b32_e32 v8, 16, v65
	v_and_b32_e32 v9, 0xffff0000, v65
	v_pk_fma_f32 v[2:3], v[10:11], v[2:3], v[6:7]
	v_pk_fma_f32 v[4:5], v[10:11], v[4:5], v[8:9]
	global_store_dwordx2 v0, v[12:13], s[40:41]
	s_add_u32 s40, s40, 0x14000
	s_addc_u32 s41, s41, 0
	global_load_dwordx2 v[64:65], v0, s[14:15]
	s_add_u32 s14, s14, 0x14000
	s_addc_u32 s15, s15, 0
	s_waitcnt vmcnt(56)
	v_cvt_pk_bf16_f32 v14, v2, v3
	v_cvt_pk_bf16_f32 v15, v4, v5
	v_lshlrev_b32_e32 v6, 16, v66
	v_and_b32_e32 v7, 0xffff0000, v66
	v_lshlrev_b32_e32 v8, 16, v67
	v_and_b32_e32 v9, 0xffff0000, v67
	v_pk_fma_f32 v[2:3], v[10:11], v[2:3], v[6:7]
	v_pk_fma_f32 v[4:5], v[10:11], v[4:5], v[8:9]
	global_store_dwordx2 v0, v[14:15], s[40:41]
	s_add_u32 s40, s40, 0x14000
	s_addc_u32 s41, s41, 0
	global_load_dwordx2 v[66:67], v0, s[14:15]
	s_add_u32 s14, s14, 0x14000
	s_addc_u32 s15, s15, 0
	s_waitcnt vmcnt(57)
	v_cvt_pk_bf16_f32 v12, v2, v3
	v_cvt_pk_bf16_f32 v13, v4, v5
	v_lshlrev_b32_e32 v6, 16, v68
	v_and_b32_e32 v7, 0xffff0000, v68
	v_lshlrev_b32_e32 v8, 16, v69
	v_and_b32_e32 v9, 0xffff0000, v69
	v_pk_fma_f32 v[2:3], v[10:11], v[2:3], v[6:7]
	v_pk_fma_f32 v[4:5], v[10:11], v[4:5], v[8:9]
	global_store_dwordx2 v0, v[12:13], s[40:41]
	s_add_u32 s40, s40, 0x14000
	s_addc_u32 s41, s41, 0
	global_load_dwordx2 v[68:69], v0, s[14:15]
	s_add_u32 s14, s14, 0x14000
	s_addc_u32 s15, s15, 0
	s_waitcnt vmcnt(58)
	v_cvt_pk_bf16_f32 v14, v2, v3
	v_cvt_pk_bf16_f32 v15, v4, v5
	v_lshlrev_b32_e32 v6, 16, v70
	v_and_b32_e32 v7, 0xffff0000, v70
	v_lshlrev_b32_e32 v8, 16, v71
	v_and_b32_e32 v9, 0xffff0000, v71
	v_pk_fma_f32 v[2:3], v[10:11], v[2:3], v[6:7]
	v_pk_fma_f32 v[4:5], v[10:11], v[4:5], v[8:9]
	global_store_dwordx2 v0, v[14:15], s[40:41]
	s_add_u32 s40, s40, 0x14000
	s_addc_u32 s41, s41, 0
	global_load_dwordx2 v[70:71], v0, s[14:15]
	s_add_u32 s14, s14, 0x14000
	s_addc_u32 s15, s15, 0
	s_waitcnt vmcnt(59)
	v_cvt_pk_bf16_f32 v12, v2, v3
	v_cvt_pk_bf16_f32 v13, v4, v5
	v_lshlrev_b32_e32 v6, 16, v72
	v_and_b32_e32 v7, 0xffff0000, v72
	v_lshlrev_b32_e32 v8, 16, v73
	v_and_b32_e32 v9, 0xffff0000, v73
	v_pk_fma_f32 v[2:3], v[10:11], v[2:3], v[6:7]
	v_pk_fma_f32 v[4:5], v[10:11], v[4:5], v[8:9]
	global_store_dwordx2 v0, v[12:13], s[40:41]
	s_add_u32 s40, s40, 0x14000
	s_addc_u32 s41, s41, 0
	global_load_dwordx2 v[72:73], v0, s[14:15]
	s_add_u32 s14, s14, 0x14000
	s_addc_u32 s15, s15, 0
	s_waitcnt vmcnt(60)
; __device__ __forceinline__ unsigned cvt_pk_bf16(float lo, float hi) { const f32x2 f = {lo, hi}; const bf16x2_t v = __builtin_convertvector(f, bf16x2_t); return __builtin_bit_cast(unsigned, v); }
; __device__ __forceinline__ float bflo(unsigned u) { return __uint_as_float(u << 16); }
; __device__ __forceinline__ float bfhi(unsigned u) { return __uint_as_float(u & 0xffff0000u); }
; __device__ __forceinline__ void phase_scan(const Params& P, int tid) {
;     ...
;             for (int n0 = 0; n0 < 256; n0 += 16) {
;                 u32x2 d[16];
; #pragma unroll
;                 for (int j = 0; j < 16; ++j) d[j] = *(const u32x2*)(sp + (size_t)(n0 + j) * (5 * 8192));
; #pragma unroll
;                 for (int j = 0; j < 16; ++j) { u32x2 o; o.x = cvt_pk_bf16(S[0], S[1]); o.y = cvt_pk_bf16(S[2], S[3]);
;                     S[0] = cd * S[0] + bflo(d[j].x); S[1] = cd * S[1] + bfhi(d[j].x); S[2] = cd * S[2] + bflo(d[j].y); S[3] = cd * S[3] + bfhi(d[j].y);
;                     *(u32x2*)(sp + (size_t)(n0 + j) * (5 * 8192)) = o; }
;             }
	v_cvt_pk_bf16_f32 v14, v2, v3
	v_cvt_pk_bf16_f32 v15, v4, v5
	v_lshlrev_b32_e32 v6, 16, v74
	v_and_b32_e32 v7, 0xffff0000, v74
	v_lshlrev_b32_e32 v8, 16, v75
	v_and_b32_e32 v9, 0xffff0000, v75
	v_pk_fma_f32 v[2:3], v[10:11], v[2:3], v[6:7]
	v_pk_fma_f32 v[4:5], v[10:11], v[4:5], v[8:9]
	global_store_dwordx2 v0, v[14:15], s[40:41]
	s_add_u32 s40, s40, 0x14000
	s_addc_u32 s41, s41, 0
	global_load_dwordx2 v[74:75], v0, s[14:15]
	s_add_u32 s14, s14, 0x14000
	s_addc_u32 s15, s15, 0
	s_waitcnt vmcnt(61)
	v_cvt_pk_bf16_f32 v12, v2, v3
	v_cvt_pk_bf16_f32 v13, v4, v5
	v_lshlrev_b32_e32 v6, 16, v76
	v_and_b32_e32 v7, 0xffff0000, v76
	v_lshlrev_b32_e32 v8, 16, v77
	v_and_b32_e32 v9, 0xffff0000, v77
	v_pk_fma_f32 v[2:3], v[10:11], v[2:3], v[6:7]
	v_pk_fma_f32 v[4:5], v[10:11], v[4:5], v[8:9]
	global_store_dwordx2 v0, v[12:13], s[40:41]
	s_add_u32 s40, s40, 0x14000
	s_addc_u32 s41, s41, 0
	global_load_dwordx2 v[76:77], v0, s[14:15]
	s_add_u32 s14, s14, 0x14000
	s_addc_u32 s15, s15, 0
	s_waitcnt vmcnt(62)
	v_cvt_pk_bf16_f32 v14, v2, v3
	v_cvt_pk_bf16_f32 v15, v4, v5
	v_lshlrev_b32_e32 v6, 16, v78
	v_and_b32_e32 v7, 0xffff0000, v78
	v_lshlrev_b32_e32 v8, 16, v79
	v_and_b32_e32 v9, 0xffff0000, v79
	v_pk_fma_f32 v[2:3], v[10:11], v[2:3], v[6:7]
	v_pk_fma_f32 v[4:5], v[10:11], v[4:5], v[8:9]
	global_store_dwordx2 v0, v[14:15], s[40:41]
	s_add_u32 s40, s40, 0x14000
	s_addc_u32 s41, s41, 0
	global_load_dwordx2 v[78:79], v0, s[14:15]
	s_add_u32 s14, s14, 0x14000
	s_addc_u32 s15, s15, 0
	s_mov_b32 s8, 6
.Lscan_c_loop:
	s_waitcnt vmcnt(62)
	v_cvt_pk_bf16_f32 v12, v2, v3
	v_cvt_pk_bf16_f32 v13, v4, v5
	v_lshlrev_b32_e32 v6, 16, v16
	v_and_b32_e32 v7, 0xffff0000, v16
	v_lshlrev_b32_e32 v8, 16, v17
	v_and_b32_e32 v9, 0xffff0000, v17
	v_pk_fma_f32 v[2:3], v[10:11], v[2:3], v[6:7]
	v_pk_fma_f32 v[4:5], v[10:11], v[4:5], v[8:9]
	global_store_dwordx2 v0, v[12:13], s[40:41]
	s_add_u32 s40, s40, 0x14000
	s_addc_u32 s41, s41, 0
	global_load_dwordx2 v[16:17], v0, s[14:15]
	s_add_u32 s14, s14, 0x14000
	s_addc_u32 s15, s15, 0
	s_waitcnt vmcnt(62)
	v_cvt_pk_bf16_f32 v14, v2, v3
	v_cvt_pk_bf16_f32 v15, v4, v5
	v_lshlrev_b32_e32 v6, 16, v18
	v_and_b32_e32 v7, 0xffff0000, v18
	v_lshlrev_b32_e32 v8, 16, v19
	v_and_b32_e32 v9, 0xffff0000, v19
	v_pk_fma_f32 v[2:3], v[10:11], v[2:3], v[6:7]
	v_pk_fma_f32 v[4:5], v[10:11], v[4:5], v[8:9]
	global_store_dwordx2 v0, v[14:15], s[40:41]
	s_add_u32 s40, s40, 0x14000
	s_addc_u32 s41, s41, 0
	global_load_dwordx2 v[18:19], v0, s[14:15]
	s_add_u32 s14, s14, 0x14000
	s_addc_u32 s15, s15, 0
	s_waitcnt vmcnt(62)
	v_cvt_pk_bf16_f32 v12, v2, v3
	v_cvt_pk_bf16_f32 v13, v4, v5
	v_lshlrev_b32_e32 v6, 16, v20
	v_and_b32_e32 v7, 0xffff0000, v20
	v_lshlrev_b32_e32 v8, 16, v21
	v_and_b32_e32 v9, 0xffff0000, v21
	v_pk_fma_f32 v[2:3], v[10:11], v[2:3], v[6:7]
	v_pk_fma_f32 v[4:5], v[10:11], v[4:5], v[8:9]
	global_store_dwordx2 v0, v[12:13], s[40:41]
	s_add_u32 s40, s40, 0x14000
	s_addc_u32 s41, s41, 0
	global_load_dwordx2 v[20:21], v0, s[14:15]
	s_add_u32 s14, s14, 0x14000
	s_addc_u32 s15, s15, 0
	s_waitcnt vmcnt(62)
	v_cvt_pk_bf16_f32 v14, v2, v3
	v_cvt_pk_bf16_f32 v15, v4, v5
	v_lshlrev_b32_e32 v6, 16, v22
	v_and_b32_e32 v7, 0xffff0000, v22
	v_lshlrev_b32_e32 v8, 16, v23
	v_and_b32_e32 v9, 0xffff0000, v23
	v_pk_fma_f32 v[2:3], v[10:11], v[2:3], v[6:7]
	v_pk_fma_f32 v[4:5], v[10:11], v[4:5], v[8:9]
	global_store_dwordx2 v0, v[14:15], s[40:41]
	s_add_u32 s40, s40, 0x14000
	s_addc_u32 s41, s41, 0
	global_load_dwordx2 v[22:23], v0, s[14:15]
	s_add_u32 s14, s14, 0x14000
	s_addc_u32 s15, s15, 0
	s_waitcnt vmcnt(62)
	v_cvt_pk_bf16_f32 v12, v2, v3
	v_cvt_pk_bf16_f32 v13, v4, v5
	v_lshlrev_b32_e32 v6, 16, v24
	v_and_b32_e32 v7, 0xffff0000, v24
	v_lshlrev_b32_e32 v8, 16, v25
	v_and_b32_e32 v9, 0xffff0000, v25
	v_pk_fma_f32 v[2:3], v[10:11], v[2:3], v[6:7]
	v_pk_fma_f32 v[4:5], v[10:11], v[4:5], v[8:9]
	global_store_dwordx2 v0, v[12:13], s[40:41]
	s_add_u32 s40, s40, 0x14000
	s_addc_u32 s41, s41, 0
	global_load_dwordx2 v[24:25], v0, s[14:15]
	s_add_u32 s14, s14, 0x14000
	s_addc_u32 s15, s15, 0
	s_waitcnt vmcnt(62)
	v_cvt_pk_bf16_f32 v14, v2, v3
	v_cvt_pk_bf16_f32 v15, v4, v5
	v_lshlrev_b32_e32 v6, 16, v26
	v_and_b32_e32 v7, 0xffff0000, v26
	v_lshlrev_b32_e32 v8, 16, v27
	v_and_b32_e32 v9, 0xffff0000, v27
	v_pk_fma_f32 v[2:3], v[10:11], v[2:3], v[6:7]
	v_pk_fma_f32 v[4:5], v[10:11], v[4:5], v[8:9]
	global_store_dwordx2 v0, v[14:15], s[40:41]
	s_add_u32 s40, s40, 0x14000
	s_addc_u32 s41, s41, 0
	global_load_dwordx2 v[26:27], v0, s[14:15]
	s_add_u32 s14, s14, 0x14000
	s_addc_u32 s15, s15, 0
	s_waitcnt vmcnt(62)
	v_cvt_pk_bf16_f32 v12, v2, v3
	v_cvt_pk_bf16_f32 v13, v4, v5
	v_lshlrev_b32_e32 v6, 16, v28
	v_and_b32_e32 v7, 0xffff0000, v28
	v_lshlrev_b32_e32 v8, 16, v29
	v_and_b32_e32 v9, 0xffff0000, v29
	v_pk_fma_f32 v[2:3], v[10:11], v[2:3], v[6:7]
	v_pk_fma_f32 v[4:5], v[10:11], v[4:5], v[8:9]
	global_store_dwordx2 v0, v[12:13], s[40:41]
	s_add_u32 s40, s40, 0x14000
	s_addc_u32 s41, s41, 0
	global_load_dwordx2 v[28:29], v0, s[14:15]
	s_add_u32 s14, s14, 0x14000
	s_addc_u32 s15, s15, 0
	s_waitcnt vmcnt(62)
	v_cvt_pk_bf16_f32 v14, v2, v3
	v_cvt_pk_bf16_f32 v15, v4, v5
	v_lshlrev_b32_e32 v6, 16, v30
	v_and_b32_e32 v7, 0xffff0000, v30
	v_lshlrev_b32_e32 v8, 16, v31
	v_and_b32_e32 v9, 0xffff0000, v31
	v_pk_fma_f32 v[2:3], v[10:11], v[2:3], v[6:7]
	v_pk_fma_f32 v[4:5], v[10:11], v[4:5], v[8:9]
	global_store_dwordx2 v0, v[14:15], s[40:41]
	s_add_u32 s40, s40, 0x14000
	s_addc_u32 s41, s41, 0
	global_load_dwordx2 v[30:31], v0, s[14:15]
	s_add_u32 s14, s14, 0x14000
	s_addc_u32 s15, s15, 0
	s_waitcnt vmcnt(62)
; __device__ __forceinline__ unsigned cvt_pk_bf16(float lo, float hi) { const f32x2 f = {lo, hi}; const bf16x2_t v = __builtin_convertvector(f, bf16x2_t); return __builtin_bit_cast(unsigned, v); }
; __device__ __forceinline__ float bflo(unsigned u) { return __uint_as_float(u << 16); }
; __device__ __forceinline__ float bfhi(unsigned u) { return __uint_as_float(u & 0xffff0000u); }
; __device__ __forceinline__ void phase_scan(const Params& P, int tid) {
;     ...
;             for (int n0 = 0; n0 < 256; n0 += 16) {
;                 u32x2 d[16];
; #pragma unroll
;                 for (int j = 0; j < 16; ++j) d[j] = *(const u32x2*)(sp + (size_t)(n0 + j) * (5 * 8192));
; #pragma unroll
;                 for (int j = 0; j < 16; ++j) { u32x2 o; o.x = cvt_pk_bf16(S[0], S[1]); o.y = cvt_pk_bf16(S[2], S[3]);
;                     S[0] = cd * S[0] + bflo(d[j].x); S[1] = cd * S[1] + bfhi(d[j].x); S[2] = cd * S[2] + bflo(d[j].y); S[3] = cd * S[3] + bfhi(d[j].y);
;                     *(u32x2*)(sp + (size_t)(n0 + j) * (5 * 8192)) = o; }
;             }
	v_cvt_pk_bf16_f32 v12, v2, v3
	v_cvt_pk_bf16_f32 v13, v4, v5
	v_lshlrev_b32_e32 v6, 16, v32
	v_and_b32_e32 v7, 0xffff0000, v32
	v_lshlrev_b32_e32 v8, 16, v33
	v_and_b32_e32 v9, 0xffff0000, v33
	v_pk_fma_f32 v[2:3], v[10:11], v[2:3], v[6:7]
	v_pk_fma_f32 v[4:5], v[10:11], v[4:5], v[8:9]
	global_store_dwordx2 v0, v[12:13], s[40:41]
	s_add_u32 s40, s40, 0x14000
	s_addc_u32 s41, s41, 0
	global_load_dwordx2 v[32:33], v0, s[14:15]
	s_add_u32 s14, s14, 0x14000
	s_addc_u32 s15, s15, 0
	s_waitcnt vmcnt(62)
	v_cvt_pk_bf16_f32 v14, v2, v3
	v_cvt_pk_bf16_f32 v15, v4, v5
	v_lshlrev_b32_e32 v6, 16, v34
	v_and_b32_e32 v7, 0xffff0000, v34
	v_lshlrev_b32_e32 v8, 16, v35
	v_and_b32_e32 v9, 0xffff0000, v35
	v_pk_fma_f32 v[2:3], v[10:11], v[2:3], v[6:7]
	v_pk_fma_f32 v[4:5], v[10:11], v[4:5], v[8:9]
	global_store_dwordx2 v0, v[14:15], s[40:41]
	s_add_u32 s40, s40, 0x14000
	s_addc_u32 s41, s41, 0
	global_load_dwordx2 v[34:35], v0, s[14:15]
	s_add_u32 s14, s14, 0x14000
	s_addc_u32 s15, s15, 0
	s_waitcnt vmcnt(62)
	v_cvt_pk_bf16_f32 v12, v2, v3
	v_cvt_pk_bf16_f32 v13, v4, v5
	v_lshlrev_b32_e32 v6, 16, v36
	v_and_b32_e32 v7, 0xffff0000, v36
	v_lshlrev_b32_e32 v8, 16, v37
	v_and_b32_e32 v9, 0xffff0000, v37
	v_pk_fma_f32 v[2:3], v[10:11], v[2:3], v[6:7]
	v_pk_fma_f32 v[4:5], v[10:11], v[4:5], v[8:9]
	global_store_dwordx2 v0, v[12:13], s[40:41]
	s_add_u32 s40, s40, 0x14000
	s_addc_u32 s41, s41, 0
	global_load_dwordx2 v[36:37], v0, s[14:15]
	s_add_u32 s14, s14, 0x14000
	s_addc_u32 s15, s15, 0
	s_waitcnt vmcnt(62)
	v_cvt_pk_bf16_f32 v14, v2, v3
	v_cvt_pk_bf16_f32 v15, v4, v5
	v_lshlrev_b32_e32 v6, 16, v38
	v_and_b32_e32 v7, 0xffff0000, v38
	v_lshlrev_b32_e32 v8, 16, v39
	v_and_b32_e32 v9, 0xffff0000, v39
	v_pk_fma_f32 v[2:3], v[10:11], v[2:3], v[6:7]
	v_pk_fma_f32 v[4:5], v[10:11], v[4:5], v[8:9]
	global_store_dwordx2 v0, v[14:15], s[40:41]
	s_add_u32 s40, s40, 0x14000
	s_addc_u32 s41, s41, 0
	global_load_dwordx2 v[38:39], v0, s[14:15]
	s_add_u32 s14, s14, 0x14000
	s_addc_u32 s15, s15, 0
	s_waitcnt vmcnt(62)
	v_cvt_pk_bf16_f32 v12, v2, v3
	v_cvt_pk_bf16_f32 v13, v4, v5
	v_lshlrev_b32_e32 v6, 16, v40
	v_and_b32_e32 v7, 0xffff0000, v40
	v_lshlrev_b32_e32 v8, 16, v41
	v_and_b32_e32 v9, 0xffff0000, v41
	v_pk_fma_f32 v[2:3], v[10:11], v[2:3], v[6:7]
	v_pk_fma_f32 v[4:5], v[10:11], v[4:5], v[8:9]
	global_store_dwordx2 v0, v[12:13], s[40:41]
	s_add_u32 s40, s40, 0x14000
	s_addc_u32 s41, s41, 0
	global_load_dwordx2 v[40:41], v0, s[14:15]
	s_add_u32 s14, s14, 0x14000
	s_addc_u32 s15, s15, 0
	s_waitcnt vmcnt(62)
	v_cvt_pk_bf16_f32 v14, v2, v3
	v_cvt_pk_bf16_f32 v15, v4, v5
	v_lshlrev_b32_e32 v6, 16, v42
	v_and_b32_e32 v7, 0xffff0000, v42
	v_lshlrev_b32_e32 v8, 16, v43
	v_and_b32_e32 v9, 0xffff0000, v43
	v_pk_fma_f32 v[2:3], v[10:11], v[2:3], v[6:7]
	v_pk_fma_f32 v[4:5], v[10:11], v[4:5], v[8:9]
	global_store_dwordx2 v0, v[14:15], s[40:41]
	s_add_u32 s40, s40, 0x14000
	s_addc_u32 s41, s41, 0
	global_load_dwordx2 v[42:43], v0, s[14:15]
	s_add_u32 s14, s14, 0x14000
	s_addc_u32 s15, s15, 0
	s_waitcnt vmcnt(62)
	v_cvt_pk_bf16_f32 v12, v2, v3
	v_cvt_pk_bf16_f32 v13, v4, v5
	v_lshlrev_b32_e32 v6, 16, v44
	v_and_b32_e32 v7, 0xffff0000, v44
	v_lshlrev_b32_e32 v8, 16, v45
	v_and_b32_e32 v9, 0xffff0000, v45
	v_pk_fma_f32 v[2:3], v[10:11], v[2:3], v[6:7]
	v_pk_fma_f32 v[4:5], v[10:11], v[4:5], v[8:9]
	global_store_dwordx2 v0, v[12:13], s[40:41]
	s_add_u32 s40, s40, 0x14000
	s_addc_u32 s41, s41, 0
	global_load_dwordx2 v[44:45], v0, s[14:15]
	s_add_u32 s14, s14, 0x14000
	s_addc_u32 s15, s15, 0
	s_waitcnt vmcnt(62)
	v_cvt_pk_bf16_f32 v14, v2, v3
	v_cvt_pk_bf16_f32 v15, v4, v5
	v_lshlrev_b32_e32 v6, 16, v46
	v_and_b32_e32 v7, 0xffff0000, v46
	v_lshlrev_b32_e32 v8, 16, v47
	v_and_b32_e32 v9, 0xffff0000, v47
	v_pk_fma_f32 v[2:3], v[10:11], v[2:3], v[6:7]
	v_pk_fma_f32 v[4:5], v[10:11], v[4:5], v[8:9]
	global_store_dwordx2 v0, v[14:15], s[40:41]
	s_add_u32 s40, s40, 0x14000
	s_addc_u32 s41, s41, 0
	global_load_dwordx2 v[46:47], v0, s[14:15]
	s_add_u32 s14, s14, 0x14000
	s_addc_u32 s15, s15, 0
	s_waitcnt vmcnt(62)
	v_cvt_pk_bf16_f32 v12, v2, v3
	v_cvt_pk_bf16_f32 v13, v4, v5
	v_lshlrev_b32_e32 v6, 16, v48
	v_and_b32_e32 v7, 0xffff0000, v48
	v_lshlrev_b32_e32 v8, 16, v49
	v_and_b32_e32 v9, 0xffff0000, v49
	v_pk_fma_f32 v[2:3], v[10:11], v[2:3], v[6:7]
	v_pk_fma_f32 v[4:5], v[10:11], v[4:5], v[8:9]
	global_store_dwordx2 v0, v[12:13], s[40:41]
	s_add_u32 s40, s40, 0x14000
	s_addc_u32 s41, s41, 0
	global_load_dwordx2 v[48:49], v0, s[14:15]
	s_add_u32 s14, s14, 0x14000
	s_addc_u32 s15, s15, 0
	s_waitcnt vmcnt(62)
	v_cvt_pk_bf16_f32 v14, v2, v3
	v_cvt_pk_bf16_f32 v15, v4, v5
	v_lshlrev_b32_e32 v6, 16, v50
	v_and_b32_e32 v7, 0xffff0000, v50
	v_lshlrev_b32_e32 v8, 16, v51
	v_and_b32_e32 v9, 0xffff0000, v51
	v_pk_fma_f32 v[2:3], v[10:11], v[2:3], v[6:7]
	v_pk_fma_f32 v[4:5], v[10:11], v[4:5], v[8:9]
	global_store_dwordx2 v0, v[14:15], s[40:41]
	s_add_u32 s40, s40, 0x14000
	s_addc_u32 s41, s41, 0
	global_load_dwordx2 v[50:51], v0, s[14:15]
	s_add_u32 s14, s14, 0x14000
	s_addc_u32 s15, s15, 0
	s_waitcnt vmcnt(62)
	v_cvt_pk_bf16_f32 v12, v2, v3
	v_cvt_pk_bf16_f32 v13, v4, v5
	v_lshlrev_b32_e32 v6, 16, v52
	v_and_b32_e32 v7, 0xffff0000, v52
	v_lshlrev_b32_e32 v8, 16, v53
	v_and_b32_e32 v9, 0xffff0000, v53
	v_pk_fma_f32 v[2:3], v[10:11], v[2:3], v[6:7]
	v_pk_fma_f32 v[4:5], v[10:11], v[4:5], v[8:9]
	global_store_dwordx2 v0, v[12:13], s[40:41]
	s_add_u32 s40, s40, 0x14000
	s_addc_u32 s41, s41, 0
	global_load_dwordx2 v[52:53], v0, s[14:15]
	s_add_u32 s14, s14, 0x14000
	s_addc_u32 s15, s15, 0
	s_waitcnt vmcnt(62)
; __device__ __forceinline__ unsigned cvt_pk_bf16(float lo, float hi) { const f32x2 f = {lo, hi}; const bf16x2_t v = __builtin_convertvector(f, bf16x2_t); return __builtin_bit_cast(unsigned, v); }
; __device__ __forceinline__ float bflo(unsigned u) { return __uint_as_float(u << 16); }
; __device__ __forceinline__ float bfhi(unsigned u) { return __uint_as_float(u & 0xffff0000u); }
; __device__ __forceinline__ void phase_scan(const Params& P, int tid) {
;     ...
;             for (int n0 = 0; n0 < 256; n0 += 16) {
;                 u32x2 d[16];
; #pragma unroll
;                 for (int j = 0; j < 16; ++j) d[j] = *(const u32x2*)(sp + (size_t)(n0 + j) * (5 * 8192));
; #pragma unroll
;                 for (int j = 0; j < 16; ++j) { u32x2 o; o.x = cvt_pk_bf16(S[0], S[1]); o.y = cvt_pk_bf16(S[2], S[3]);
;                     S[0] = cd * S[0] + bflo(d[j].x); S[1] = cd * S[1] + bfhi(d[j].x); S[2] = cd * S[2] + bflo(d[j].y); S[3] = cd * S[3] + bfhi(d[j].y);
;                     *(u32x2*)(sp + (size_t)(n0 + j) * (5 * 8192)) = o; }
;             }
	v_cvt_pk_bf16_f32 v14, v2, v3
	v_cvt_pk_bf16_f32 v15, v4, v5
	v_lshlrev_b32_e32 v6, 16, v54
	v_and_b32_e32 v7, 0xffff0000, v54
	v_lshlrev_b32_e32 v8, 16, v55
	v_and_b32_e32 v9, 0xffff0000, v55
	v_pk_fma_f32 v[2:3], v[10:11], v[2:3], v[6:7]
	v_pk_fma_f32 v[4:5], v[10:11], v[4:5], v[8:9]
	global_store_dwordx2 v0, v[14:15], s[40:41]
	s_add_u32 s40, s40, 0x14000
	s_addc_u32 s41, s41, 0
	global_load_dwordx2 v[54:55], v0, s[14:15]
	s_add_u32 s14, s14, 0x14000
	s_addc_u32 s15, s15, 0
	s_waitcnt vmcnt(62)
	v_cvt_pk_bf16_f32 v12, v2, v3
	v_cvt_pk_bf16_f32 v13, v4, v5
	v_lshlrev_b32_e32 v6, 16, v56
	v_and_b32_e32 v7, 0xffff0000, v56
	v_lshlrev_b32_e32 v8, 16, v57
	v_and_b32_e32 v9, 0xffff0000, v57
	v_pk_fma_f32 v[2:3], v[10:11], v[2:3], v[6:7]
	v_pk_fma_f32 v[4:5], v[10:11], v[4:5], v[8:9]
	global_store_dwordx2 v0, v[12:13], s[40:41]
	s_add_u32 s40, s40, 0x14000
	s_addc_u32 s41, s41, 0
	global_load_dwordx2 v[56:57], v0, s[14:15]
	s_add_u32 s14, s14, 0x14000
	s_addc_u32 s15, s15, 0
	s_waitcnt vmcnt(62)
	v_cvt_pk_bf16_f32 v14, v2, v3
	v_cvt_pk_bf16_f32 v15, v4, v5
	v_lshlrev_b32_e32 v6, 16, v58
	v_and_b32_e32 v7, 0xffff0000, v58
	v_lshlrev_b32_e32 v8, 16, v59
	v_and_b32_e32 v9, 0xffff0000, v59
	v_pk_fma_f32 v[2:3], v[10:11], v[2:3], v[6:7]
	v_pk_fma_f32 v[4:5], v[10:11], v[4:5], v[8:9]
	global_store_dwordx2 v0, v[14:15], s[40:41]
	s_add_u32 s40, s40, 0x14000
	s_addc_u32 s41, s41, 0
	global_load_dwordx2 v[58:59], v0, s[14:15]
	s_add_u32 s14, s14, 0x14000
	s_addc_u32 s15, s15, 0
	s_waitcnt vmcnt(62)
	v_cvt_pk_bf16_f32 v12, v2, v3
	v_cvt_pk_bf16_f32 v13, v4, v5
	v_lshlrev_b32_e32 v6, 16, v60
	v_and_b32_e32 v7, 0xffff0000, v60
	v_lshlrev_b32_e32 v8, 16, v61
	v_and_b32_e32 v9, 0xffff0000, v61
	v_pk_fma_f32 v[2:3], v[10:11], v[2:3], v[6:7]
	v_pk_fma_f32 v[4:5], v[10:11], v[4:5], v[8:9]
	global_store_dwordx2 v0, v[12:13], s[40:41]
	s_add_u32 s40, s40, 0x14000
	s_addc_u32 s41, s41, 0
	global_load_dwordx2 v[60:61], v0, s[14:15]
	s_add_u32 s14, s14, 0x14000
	s_addc_u32 s15, s15, 0
	s_waitcnt vmcnt(62)
	v_cvt_pk_bf16_f32 v14, v2, v3
	v_cvt_pk_bf16_f32 v15, v4, v5
	v_lshlrev_b32_e32 v6, 16, v62
	v_and_b32_e32 v7, 0xffff0000, v62
	v_lshlrev_b32_e32 v8, 16, v63
	v_and_b32_e32 v9, 0xffff0000, v63
	v_pk_fma_f32 v[2:3], v[10:11], v[2:3], v[6:7]
	v_pk_fma_f32 v[4:5], v[10:11], v[4:5], v[8:9]
	global_store_dwordx2 v0, v[14:15], s[40:41]
	s_add_u32 s40, s40, 0x14000
	s_addc_u32 s41, s41, 0
	global_load_dwordx2 v[62:63], v0, s[14:15]
	s_add_u32 s14, s14, 0x14000
	s_addc_u32 s15, s15, 0
	s_waitcnt vmcnt(62)
	v_cvt_pk_bf16_f32 v12, v2, v3
	v_cvt_pk_bf16_f32 v13, v4, v5
	v_lshlrev_b32_e32 v6, 16, v64
	v_and_b32_e32 v7, 0xffff0000, v64
	v_lshlrev_b32_e32 v8, 16, v65
	v_and_b32_e32 v9, 0xffff0000, v65
	v_pk_fma_f32 v[2:3], v[10:11], v[2:3], v[6:7]
	v_pk_fma_f32 v[4:5], v[10:11], v[4:5], v[8:9]
	global_store_dwordx2 v0, v[12:13], s[40:41]
	s_add_u32 s40, s40, 0x14000
	s_addc_u32 s41, s41, 0
	global_load_dwordx2 v[64:65], v0, s[14:15]
	s_add_u32 s14, s14, 0x14000
	s_addc_u32 s15, s15, 0
	s_waitcnt vmcnt(62)
	v_cvt_pk_bf16_f32 v14, v2, v3
	v_cvt_pk_bf16_f32 v15, v4, v5
	v_lshlrev_b32_e32 v6, 16, v66
	v_and_b32_e32 v7, 0xffff0000, v66
	v_lshlrev_b32_e32 v8, 16, v67
	v_and_b32_e32 v9, 0xffff0000, v67
	v_pk_fma_f32 v[2:3], v[10:11], v[2:3], v[6:7]
	v_pk_fma_f32 v[4:5], v[10:11], v[4:5], v[8:9]
	global_store_dwordx2 v0, v[14:15], s[40:41]
	s_add_u32 s40, s40, 0x14000
	s_addc_u32 s41, s41, 0
	global_load_dwordx2 v[66:67], v0, s[14:15]
	s_add_u32 s14, s14, 0x14000
	s_addc_u32 s15, s15, 0
	s_waitcnt vmcnt(62)
	v_cvt_pk_bf16_f32 v12, v2, v3
	v_cvt_pk_bf16_f32 v13, v4, v5
	v_lshlrev_b32_e32 v6, 16, v68
	v_and_b32_e32 v7, 0xffff0000, v68
	v_lshlrev_b32_e32 v8, 16, v69
	v_and_b32_e32 v9, 0xffff0000, v69
	v_pk_fma_f32 v[2:3], v[10:11], v[2:3], v[6:7]
	v_pk_fma_f32 v[4:5], v[10:11], v[4:5], v[8:9]
	global_store_dwordx2 v0, v[12:13], s[40:41]
	s_add_u32 s40, s40, 0x14000
	s_addc_u32 s41, s41, 0
	global_load_dwordx2 v[68:69], v0, s[14:15]
	s_add_u32 s14, s14, 0x14000
	s_addc_u32 s15, s15, 0
	s_waitcnt vmcnt(62)
	v_cvt_pk_bf16_f32 v14, v2, v3
	v_cvt_pk_bf16_f32 v15, v4, v5
	v_lshlrev_b32_e32 v6, 16, v70
	v_and_b32_e32 v7, 0xffff0000, v70
	v_lshlrev_b32_e32 v8, 16, v71
	v_and_b32_e32 v9, 0xffff0000, v71
	v_pk_fma_f32 v[2:3], v[10:11], v[2:3], v[6:7]
	v_pk_fma_f32 v[4:5], v[10:11], v[4:5], v[8:9]
	global_store_dwordx2 v0, v[14:15], s[40:41]
	s_add_u32 s40, s40, 0x14000
	s_addc_u32 s41, s41, 0
	global_load_dwordx2 v[70:71], v0, s[14:15]
	s_add_u32 s14, s14, 0x14000
	s_addc_u32 s15, s15, 0
	s_waitcnt vmcnt(62)
	v_cvt_pk_bf16_f32 v12, v2, v3
	v_cvt_pk_bf16_f32 v13, v4, v5
	v_lshlrev_b32_e32 v6, 16, v72
	v_and_b32_e32 v7, 0xffff0000, v72
	v_lshlrev_b32_e32 v8, 16, v73
	v_and_b32_e32 v9, 0xffff0000, v73
	v_pk_fma_f32 v[2:3], v[10:11], v[2:3], v[6:7]
	v_pk_fma_f32 v[4:5], v[10:11], v[4:5], v[8:9]
	global_store_dwordx2 v0, v[12:13], s[40:41]
	s_add_u32 s40, s40, 0x14000
	s_addc_u32 s41, s41, 0
	global_load_dwordx2 v[72:73], v0, s[14:15]
	s_add_u32 s14, s14, 0x14000
	s_addc_u32 s15, s15, 0
	s_waitcnt vmcnt(62)
	v_cvt_pk_bf16_f32 v14, v2, v3
	v_cvt_pk_bf16_f32 v15, v4, v5
	v_lshlrev_b32_e32 v6, 16, v74
	v_and_b32_e32 v7, 0xffff0000, v74
	v_lshlrev_b32_e32 v8, 16, v75
	v_and_b32_e32 v9, 0xffff0000, v75
	v_pk_fma_f32 v[2:3], v[10:11], v[2:3], v[6:7]
	v_pk_fma_f32 v[4:5], v[10:11], v[4:5], v[8:9]
	global_store_dwordx2 v0, v[14:15], s[40:41]
	s_add_u32 s40, s40, 0x14000
	s_addc_u32 s41, s41, 0
	global_load_dwordx2 v[74:75], v0, s[14:15]
	s_add_u32 s14, s14, 0x14000
	s_addc_u32 s15, s15, 0
	s_waitcnt vmcnt(62)
	v_cvt_pk_bf16_f32 v12, v2, v3
	v_cvt_pk_bf16_f32 v13, v4, v5
	v_lshlrev_b32_e32 v6, 16, v76
	v_and_b32_e32 v7, 0xffff0000, v76
	v_lshlrev_b32_e32 v8, 16, v77
	v_and_b32_e32 v9, 0xffff0000, v77
	v_pk_fma_f32 v[2:3], v[10:11], v[2:3], v[6:7]
	v_pk_fma_f32 v[4:5], v[10:11], v[4:5], v[8:9]
	global_store_dwordx2 v0, v[12:13], s[40:41]
	s_add_u32 s40, s40, 0x14000
	s_addc_u32 s41, s41, 0
	global_load_dwordx2 v[76:77], v0, s[14:15]
	s_add_u32 s14, s14, 0x14000
	s_addc_u32 s15, s15, 0
	s_waitcnt vmcnt(62)
	v_cvt_pk_bf16_f32 v14, v2, v3
	v_cvt_pk_bf16_f32 v15, v4, v5
	v_lshlrev_b32_e32 v6, 16, v78
	v_and_b32_e32 v7, 0xffff0000, v78
	v_lshlrev_b32_e32 v8, 16, v79
	v_and_b32_e32 v9, 0xffff0000, v79
	v_pk_fma_f32 v[2:3], v[10:11], v[2:3], v[6:7]
	v_pk_fma_f32 v[4:5], v[10:11], v[4:5], v[8:9]
	global_store_dwordx2 v0, v[14:15], s[40:41]
	s_add_u32 s40, s40, 0x14000
	s_addc_u32 s41, s41, 0
	global_load_dwordx2 v[78:79], v0, s[14:15]
	s_add_u32 s14, s14, 0x14000
	s_addc_u32 s15, s15, 0
	s_sub_u32 s8, s8, 1
	s_cmp_lg_u32 s8, 0
	s_cbranch_scc1 .Lscan_c_loop
; __device__ __forceinline__ unsigned cvt_pk_bf16(float lo, float hi) { const f32x2 f = {lo, hi}; const bf16x2_t v = __builtin_convertvector(f, bf16x2_t); return __builtin_bit_cast(unsigned, v); }
; __device__ __forceinline__ float bflo(unsigned u) { return __uint_as_float(u << 16); }
; __device__ __forceinline__ float bfhi(unsigned u) { return __uint_as_float(u & 0xffff0000u); }
; __device__ __forceinline__ void phase_scan(const Params& P, int tid) {
;     ...
;             for (int n0 = 0; n0 < 256; n0 += 16) {
;                 u32x2 d[16];
; #pragma unroll
;                 for (int j = 0; j < 16; ++j) d[j] = *(const u32x2*)(sp + (size_t)(n0 + j) * (5 * 8192));
; #pragma unroll
;                 for (int j = 0; j < 16; ++j) { u32x2 o; o.x = cvt_pk_bf16(S[0], S[1]); o.y = cvt_pk_bf16(S[2], S[3]);
;                     S[0] = cd * S[0] + bflo(d[j].x); S[1] = cd * S[1] + bfhi(d[j].x); S[2] = cd * S[2] + bflo(d[j].y); S[3] = cd * S[3] + bfhi(d[j].y);
;                     *(u32x2*)(sp + (size_t)(n0 + j) * (5 * 8192)) = o; }
;             }
	s_waitcnt vmcnt(62)
	v_cvt_pk_bf16_f32 v12, v2, v3
	v_cvt_pk_bf16_f32 v13, v4, v5
	v_lshlrev_b32_e32 v6, 16, v16
	v_and_b32_e32 v7, 0xffff0000, v16
	v_lshlrev_b32_e32 v8, 16, v17
	v_and_b32_e32 v9, 0xffff0000, v17
	v_pk_fma_f32 v[2:3], v[10:11], v[2:3], v[6:7]
	v_pk_fma_f32 v[4:5], v[10:11], v[4:5], v[8:9]
	global_store_dwordx2 v0, v[12:13], s[40:41]
	s_add_u32 s40, s40, 0x14000
	s_addc_u32 s41, s41, 0
	s_waitcnt vmcnt(61)
	v_cvt_pk_bf16_f32 v14, v2, v3
	v_cvt_pk_bf16_f32 v15, v4, v5
	v_lshlrev_b32_e32 v6, 16, v18
	v_and_b32_e32 v7, 0xffff0000, v18
	v_lshlrev_b32_e32 v8, 16, v19
	v_and_b32_e32 v9, 0xffff0000, v19
	v_pk_fma_f32 v[2:3], v[10:11], v[2:3], v[6:7]
	v_pk_fma_f32 v[4:5], v[10:11], v[4:5], v[8:9]
	global_store_dwordx2 v0, v[14:15], s[40:41]
	s_add_u32 s40, s40, 0x14000
	s_addc_u32 s41, s41, 0
	s_waitcnt vmcnt(60)
	v_cvt_pk_bf16_f32 v12, v2, v3
	v_cvt_pk_bf16_f32 v13, v4, v5
	v_lshlrev_b32_e32 v6, 16, v20
	v_and_b32_e32 v7, 0xffff0000, v20
	v_lshlrev_b32_e32 v8, 16, v21
	v_and_b32_e32 v9, 0xffff0000, v21
	v_pk_fma_f32 v[2:3], v[10:11], v[2:3], v[6:7]
	v_pk_fma_f32 v[4:5], v[10:11], v[4:5], v[8:9]
	global_store_dwordx2 v0, v[12:13], s[40:41]
	s_add_u32 s40, s40, 0x14000
	s_addc_u32 s41, s41, 0
	s_waitcnt vmcnt(59)
	v_cvt_pk_bf16_f32 v14, v2, v3
	v_cvt_pk_bf16_f32 v15, v4, v5
	v_lshlrev_b32_e32 v6, 16, v22
	v_and_b32_e32 v7, 0xffff0000, v22
	v_lshlrev_b32_e32 v8, 16, v23
	v_and_b32_e32 v9, 0xffff0000, v23
	v_pk_fma_f32 v[2:3], v[10:11], v[2:3], v[6:7]
	v_pk_fma_f32 v[4:5], v[10:11], v[4:5], v[8:9]
	global_store_dwordx2 v0, v[14:15], s[40:41]
	s_add_u32 s40, s40, 0x14000
	s_addc_u32 s41, s41, 0
	s_waitcnt vmcnt(58)
	v_cvt_pk_bf16_f32 v12, v2, v3
	v_cvt_pk_bf16_f32 v13, v4, v5
	v_lshlrev_b32_e32 v6, 16, v24
	v_and_b32_e32 v7, 0xffff0000, v24
	v_lshlrev_b32_e32 v8, 16, v25
	v_and_b32_e32 v9, 0xffff0000, v25
	v_pk_fma_f32 v[2:3], v[10:11], v[2:3], v[6:7]
	v_pk_fma_f32 v[4:5], v[10:11], v[4:5], v[8:9]
	global_store_dwordx2 v0, v[12:13], s[40:41]
	s_add_u32 s40, s40, 0x14000
	s_addc_u32 s41, s41, 0
	s_waitcnt vmcnt(57)
	v_cvt_pk_bf16_f32 v14, v2, v3
	v_cvt_pk_bf16_f32 v15, v4, v5
	v_lshlrev_b32_e32 v6, 16, v26
	v_and_b32_e32 v7, 0xffff0000, v26
	v_lshlrev_b32_e32 v8, 16, v27
	v_and_b32_e32 v9, 0xffff0000, v27
	v_pk_fma_f32 v[2:3], v[10:11], v[2:3], v[6:7]
	v_pk_fma_f32 v[4:5], v[10:11], v[4:5], v[8:9]
	global_store_dwordx2 v0, v[14:15], s[40:41]
	s_add_u32 s40, s40, 0x14000
	s_addc_u32 s41, s41, 0
	s_waitcnt vmcnt(56)
	v_cvt_pk_bf16_f32 v12, v2, v3
	v_cvt_pk_bf16_f32 v13, v4, v5
	v_lshlrev_b32_e32 v6, 16, v28
	v_and_b32_e32 v7, 0xffff0000, v28
	v_lshlrev_b32_e32 v8, 16, v29
	v_and_b32_e32 v9, 0xffff0000, v29
	v_pk_fma_f32 v[2:3], v[10:11], v[2:3], v[6:7]
	v_pk_fma_f32 v[4:5], v[10:11], v[4:5], v[8:9]
	global_store_dwordx2 v0, v[12:13], s[40:41]
	s_add_u32 s40, s40, 0x14000
	s_addc_u32 s41, s41, 0
	s_waitcnt vmcnt(55)
	v_cvt_pk_bf16_f32 v14, v2, v3
	v_cvt_pk_bf16_f32 v15, v4, v5
	v_lshlrev_b32_e32 v6, 16, v30
	v_and_b32_e32 v7, 0xffff0000, v30
	v_lshlrev_b32_e32 v8, 16, v31
	v_and_b32_e32 v9, 0xffff0000, v31
	v_pk_fma_f32 v[2:3], v[10:11], v[2:3], v[6:7]
	v_pk_fma_f32 v[4:5], v[10:11], v[4:5], v[8:9]
	global_store_dwordx2 v0, v[14:15], s[40:41]
	s_add_u32 s40, s40, 0x14000
	s_addc_u32 s41, s41, 0
	s_waitcnt vmcnt(54)
	v_cvt_pk_bf16_f32 v12, v2, v3
	v_cvt_pk_bf16_f32 v13, v4, v5
	v_lshlrev_b32_e32 v6, 16, v32
	v_and_b32_e32 v7, 0xffff0000, v32
	v_lshlrev_b32_e32 v8, 16, v33
	v_and_b32_e32 v9, 0xffff0000, v33
	v_pk_fma_f32 v[2:3], v[10:11], v[2:3], v[6:7]
	v_pk_fma_f32 v[4:5], v[10:11], v[4:5], v[8:9]
	global_store_dwordx2 v0, v[12:13], s[40:41]
	s_add_u32 s40, s40, 0x14000
	s_addc_u32 s41, s41, 0
	s_waitcnt vmcnt(53)
	v_cvt_pk_bf16_f32 v14, v2, v3
	v_cvt_pk_bf16_f32 v15, v4, v5
	v_lshlrev_b32_e32 v6, 16, v34
	v_and_b32_e32 v7, 0xffff0000, v34
	v_lshlrev_b32_e32 v8, 16, v35
	v_and_b32_e32 v9, 0xffff0000, v35
	v_pk_fma_f32 v[2:3], v[10:11], v[2:3], v[6:7]
	v_pk_fma_f32 v[4:5], v[10:11], v[4:5], v[8:9]
	global_store_dwordx2 v0, v[14:15], s[40:41]
	s_add_u32 s40, s40, 0x14000
	s_addc_u32 s41, s41, 0
	s_waitcnt vmcnt(52)
	v_cvt_pk_bf16_f32 v12, v2, v3
	v_cvt_pk_bf16_f32 v13, v4, v5
	v_lshlrev_b32_e32 v6, 16, v36
	v_and_b32_e32 v7, 0xffff0000, v36
	v_lshlrev_b32_e32 v8, 16, v37
	v_and_b32_e32 v9, 0xffff0000, v37
	v_pk_fma_f32 v[2:3], v[10:11], v[2:3], v[6:7]
	v_pk_fma_f32 v[4:5], v[10:11], v[4:5], v[8:9]
	global_store_dwordx2 v0, v[12:13], s[40:41]
	s_add_u32 s40, s40, 0x14000
	s_addc_u32 s41, s41, 0
	s_waitcnt vmcnt(51)
	v_cvt_pk_bf16_f32 v14, v2, v3
	v_cvt_pk_bf16_f32 v15, v4, v5
	v_lshlrev_b32_e32 v6, 16, v38
	v_and_b32_e32 v7, 0xffff0000, v38
	v_lshlrev_b32_e32 v8, 16, v39
	v_and_b32_e32 v9, 0xffff0000, v39
	v_pk_fma_f32 v[2:3], v[10:11], v[2:3], v[6:7]
	v_pk_fma_f32 v[4:5], v[10:11], v[4:5], v[8:9]
	global_store_dwordx2 v0, v[14:15], s[40:41]
	s_add_u32 s40, s40, 0x14000
	s_addc_u32 s41, s41, 0
	s_waitcnt vmcnt(50)
	v_cvt_pk_bf16_f32 v12, v2, v3
	v_cvt_pk_bf16_f32 v13, v4, v5
	v_lshlrev_b32_e32 v6, 16, v40
	v_and_b32_e32 v7, 0xffff0000, v40
	v_lshlrev_b32_e32 v8, 16, v41
	v_and_b32_e32 v9, 0xffff0000, v41
	v_pk_fma_f32 v[2:3], v[10:11], v[2:3], v[6:7]
	v_pk_fma_f32 v[4:5], v[10:11], v[4:5], v[8:9]
	global_store_dwordx2 v0, v[12:13], s[40:41]
	s_add_u32 s40, s40, 0x14000
	s_addc_u32 s41, s41, 0
	s_waitcnt vmcnt(49)
	v_cvt_pk_bf16_f32 v14, v2, v3
	v_cvt_pk_bf16_f32 v15, v4, v5
	v_lshlrev_b32_e32 v6, 16, v42
	v_and_b32_e32 v7, 0xffff0000, v42
	v_lshlrev_b32_e32 v8, 16, v43
	v_and_b32_e32 v9, 0xffff0000, v43
	v_pk_fma_f32 v[2:3], v[10:11], v[2:3], v[6:7]
	v_pk_fma_f32 v[4:5], v[10:11], v[4:5], v[8:9]
	global_store_dwordx2 v0, v[14:15], s[40:41]
	s_add_u32 s40, s40, 0x14000
	s_addc_u32 s41, s41, 0
	s_waitcnt vmcnt(48)
; __device__ __forceinline__ unsigned cvt_pk_bf16(float lo, float hi) { const f32x2 f = {lo, hi}; const bf16x2_t v = __builtin_convertvector(f, bf16x2_t); return __builtin_bit_cast(unsigned, v); }
; __device__ __forceinline__ float bflo(unsigned u) { return __uint_as_float(u << 16); }
; __device__ __forceinline__ float bfhi(unsigned u) { return __uint_as_float(u & 0xffff0000u); }
; __device__ __forceinline__ void phase_scan(const Params& P, int tid) {
;     ...
;             for (int n0 = 0; n0 < 256; n0 += 16) {
;                 u32x2 d[16];
; #pragma unroll
;                 for (int j = 0; j < 16; ++j) d[j] = *(const u32x2*)(sp + (size_t)(n0 + j) * (5 * 8192));
; #pragma unroll
;                 for (int j = 0; j < 16; ++j) { u32x2 o; o.x = cvt_pk_bf16(S[0], S[1]); o.y = cvt_pk_bf16(S[2], S[3]);
;                     S[0] = cd * S[0] + bflo(d[j].x); S[1] = cd * S[1] + bfhi(d[j].x); S[2] = cd * S[2] + bflo(d[j].y); S[3] = cd * S[3] + bfhi(d[j].y);
;                     *(u32x2*)(sp + (size_t)(n0 + j) * (5 * 8192)) = o; }
;             }
	v_cvt_pk_bf16_f32 v12, v2, v3
	v_cvt_pk_bf16_f32 v13, v4, v5
	v_lshlrev_b32_e32 v6, 16, v44
	v_and_b32_e32 v7, 0xffff0000, v44
	v_lshlrev_b32_e32 v8, 16, v45
	v_and_b32_e32 v9, 0xffff0000, v45
	v_pk_fma_f32 v[2:3], v[10:11], v[2:3], v[6:7]
	v_pk_fma_f32 v[4:5], v[10:11], v[4:5], v[8:9]
	global_store_dwordx2 v0, v[12:13], s[40:41]
	s_add_u32 s40, s40, 0x14000
	s_addc_u32 s41, s41, 0
	s_waitcnt vmcnt(47)
	v_cvt_pk_bf16_f32 v14, v2, v3
	v_cvt_pk_bf16_f32 v15, v4, v5
	v_lshlrev_b32_e32 v6, 16, v46
	v_and_b32_e32 v7, 0xffff0000, v46
	v_lshlrev_b32_e32 v8, 16, v47
	v_and_b32_e32 v9, 0xffff0000, v47
	v_pk_fma_f32 v[2:3], v[10:11], v[2:3], v[6:7]
	v_pk_fma_f32 v[4:5], v[10:11], v[4:5], v[8:9]
	global_store_dwordx2 v0, v[14:15], s[40:41]
	s_add_u32 s40, s40, 0x14000
	s_addc_u32 s41, s41, 0
	s_waitcnt vmcnt(46)
	v_cvt_pk_bf16_f32 v12, v2, v3
	v_cvt_pk_bf16_f32 v13, v4, v5
	v_lshlrev_b32_e32 v6, 16, v48
	v_and_b32_e32 v7, 0xffff0000, v48
	v_lshlrev_b32_e32 v8, 16, v49
	v_and_b32_e32 v9, 0xffff0000, v49
	v_pk_fma_f32 v[2:3], v[10:11], v[2:3], v[6:7]
	v_pk_fma_f32 v[4:5], v[10:11], v[4:5], v[8:9]
	global_store_dwordx2 v0, v[12:13], s[40:41]
	s_add_u32 s40, s40, 0x14000
	s_addc_u32 s41, s41, 0
	s_waitcnt vmcnt(45)
	v_cvt_pk_bf16_f32 v14, v2, v3
	v_cvt_pk_bf16_f32 v15, v4, v5
	v_lshlrev_b32_e32 v6, 16, v50
	v_and_b32_e32 v7, 0xffff0000, v50
	v_lshlrev_b32_e32 v8, 16, v51
	v_and_b32_e32 v9, 0xffff0000, v51
	v_pk_fma_f32 v[2:3], v[10:11], v[2:3], v[6:7]
	v_pk_fma_f32 v[4:5], v[10:11], v[4:5], v[8:9]
	global_store_dwordx2 v0, v[14:15], s[40:41]
	s_add_u32 s40, s40, 0x14000
	s_addc_u32 s41, s41, 0
	s_waitcnt vmcnt(44)
	v_cvt_pk_bf16_f32 v12, v2, v3
	v_cvt_pk_bf16_f32 v13, v4, v5
	v_lshlrev_b32_e32 v6, 16, v52
	v_and_b32_e32 v7, 0xffff0000, v52
	v_lshlrev_b32_e32 v8, 16, v53
	v_and_b32_e32 v9, 0xffff0000, v53
	v_pk_fma_f32 v[2:3], v[10:11], v[2:3], v[6:7]
	v_pk_fma_f32 v[4:5], v[10:11], v[4:5], v[8:9]
	global_store_dwordx2 v0, v[12:13], s[40:41]
	s_add_u32 s40, s40, 0x14000
	s_addc_u32 s41, s41, 0
	s_waitcnt vmcnt(43)
	v_cvt_pk_bf16_f32 v14, v2, v3
	v_cvt_pk_bf16_f32 v15, v4, v5
	v_lshlrev_b32_e32 v6, 16, v54
	v_and_b32_e32 v7, 0xffff0000, v54
	v_lshlrev_b32_e32 v8, 16, v55
	v_and_b32_e32 v9, 0xffff0000, v55
	v_pk_fma_f32 v[2:3], v[10:11], v[2:3], v[6:7]
	v_pk_fma_f32 v[4:5], v[10:11], v[4:5], v[8:9]
	global_store_dwordx2 v0, v[14:15], s[40:41]
	s_add_u32 s40, s40, 0x14000
	s_addc_u32 s41, s41, 0
	s_waitcnt vmcnt(42)
	v_cvt_pk_bf16_f32 v12, v2, v3
	v_cvt_pk_bf16_f32 v13, v4, v5
	v_lshlrev_b32_e32 v6, 16, v56
	v_and_b32_e32 v7, 0xffff0000, v56
	v_lshlrev_b32_e32 v8, 16, v57
	v_and_b32_e32 v9, 0xffff0000, v57
	v_pk_fma_f32 v[2:3], v[10:11], v[2:3], v[6:7]
	v_pk_fma_f32 v[4:5], v[10:11], v[4:5], v[8:9]
	global_store_dwordx2 v0, v[12:13], s[40:41]
	s_add_u32 s40, s40, 0x14000
	s_addc_u32 s41, s41, 0
	s_waitcnt vmcnt(41)
	v_cvt_pk_bf16_f32 v14, v2, v3
	v_cvt_pk_bf16_f32 v15, v4, v5
	v_lshlrev_b32_e32 v6, 16, v58
	v_and_b32_e32 v7, 0xffff0000, v58
	v_lshlrev_b32_e32 v8, 16, v59
	v_and_b32_e32 v9, 0xffff0000, v59
	v_pk_fma_f32 v[2:3], v[10:11], v[2:3], v[6:7]
	v_pk_fma_f32 v[4:5], v[10:11], v[4:5], v[8:9]
	global_store_dwordx2 v0, v[14:15], s[40:41]
	s_add_u32 s40, s40, 0x14000
	s_addc_u32 s41, s41, 0
	s_waitcnt vmcnt(40)
	v_cvt_pk_bf16_f32 v12, v2, v3
	v_cvt_pk_bf16_f32 v13, v4, v5
	v_lshlrev_b32_e32 v6, 16, v60
	v_and_b32_e32 v7, 0xffff0000, v60
	v_lshlrev_b32_e32 v8, 16, v61
	v_and_b32_e32 v9, 0xffff0000, v61
	v_pk_fma_f32 v[2:3], v[10:11], v[2:3], v[6:7]
	v_pk_fma_f32 v[4:5], v[10:11], v[4:5], v[8:9]
	global_store_dwordx2 v0, v[12:13], s[40:41]
	s_add_u32 s40, s40, 0x14000
	s_addc_u32 s41, s41, 0
	s_waitcnt vmcnt(39)
	v_cvt_pk_bf16_f32 v14, v2, v3
	v_cvt_pk_bf16_f32 v15, v4, v5
	v_lshlrev_b32_e32 v6, 16, v62
	v_and_b32_e32 v7, 0xffff0000, v62
	v_lshlrev_b32_e32 v8, 16, v63
	v_and_b32_e32 v9, 0xffff0000, v63
	v_pk_fma_f32 v[2:3], v[10:11], v[2:3], v[6:7]
	v_pk_fma_f32 v[4:5], v[10:11], v[4:5], v[8:9]
	global_store_dwordx2 v0, v[14:15], s[40:41]
	s_add_u32 s40, s40, 0x14000
	s_addc_u32 s41, s41, 0
	s_waitcnt vmcnt(38)
	v_cvt_pk_bf16_f32 v12, v2, v3
	v_cvt_pk_bf16_f32 v13, v4, v5
	v_lshlrev_b32_e32 v6, 16, v64
	v_and_b32_e32 v7, 0xffff0000, v64
	v_lshlrev_b32_e32 v8, 16, v65
	v_and_b32_e32 v9, 0xffff0000, v65
	v_pk_fma_f32 v[2:3], v[10:11], v[2:3], v[6:7]
	v_pk_fma_f32 v[4:5], v[10:11], v[4:5], v[8:9]
	global_store_dwordx2 v0, v[12:13], s[40:41]
	s_add_u32 s40, s40, 0x14000
	s_addc_u32 s41, s41, 0
	s_waitcnt vmcnt(37)
	v_cvt_pk_bf16_f32 v14, v2, v3
	v_cvt_pk_bf16_f32 v15, v4, v5
	v_lshlrev_b32_e32 v6, 16, v66
	v_and_b32_e32 v7, 0xffff0000, v66
	v_lshlrev_b32_e32 v8, 16, v67
	v_and_b32_e32 v9, 0xffff0000, v67
	v_pk_fma_f32 v[2:3], v[10:11], v[2:3], v[6:7]
	v_pk_fma_f32 v[4:5], v[10:11], v[4:5], v[8:9]
	global_store_dwordx2 v0, v[14:15], s[40:41]
	s_add_u32 s40, s40, 0x14000
	s_addc_u32 s41, s41, 0
	s_waitcnt vmcnt(36)
	v_cvt_pk_bf16_f32 v12, v2, v3
	v_cvt_pk_bf16_f32 v13, v4, v5
	v_lshlrev_b32_e32 v6, 16, v68
	v_and_b32_e32 v7, 0xffff0000, v68
	v_lshlrev_b32_e32 v8, 16, v69
	v_and_b32_e32 v9, 0xffff0000, v69
	v_pk_fma_f32 v[2:3], v[10:11], v[2:3], v[6:7]
	v_pk_fma_f32 v[4:5], v[10:11], v[4:5], v[8:9]
	global_store_dwordx2 v0, v[12:13], s[40:41]
	s_add_u32 s40, s40, 0x14000
	s_addc_u32 s41, s41, 0
	s_waitcnt vmcnt(35)
	v_cvt_pk_bf16_f32 v14, v2, v3
	v_cvt_pk_bf16_f32 v15, v4, v5
	v_lshlrev_b32_e32 v6, 16, v70
	v_and_b32_e32 v7, 0xffff0000, v70
	v_lshlrev_b32_e32 v8, 16, v71
	v_and_b32_e32 v9, 0xffff0000, v71
	v_pk_fma_f32 v[2:3], v[10:11], v[2:3], v[6:7]
	v_pk_fma_f32 v[4:5], v[10:11], v[4:5], v[8:9]
	global_store_dwordx2 v0, v[14:15], s[40:41]
	s_add_u32 s40, s40, 0x14000
	s_addc_u32 s41, s41, 0
	s_waitcnt vmcnt(34)
; #define LAS __attribute__((address_space(3)))
; __device__ __forceinline__ unsigned cvt_pk_bf16(float lo, float hi) { const f32x2 f = {lo, hi}; const bf16x2_t v = __builtin_convertvector(f, bf16x2_t); return __builtin_bit_cast(unsigned, v); }
; __device__ __forceinline__ float bflo(unsigned u) { return __uint_as_float(u << 16); }
; __device__ __forceinline__ float bfhi(unsigned u) { return __uint_as_float(u & 0xffff0000u); }
; template <int ROWS, int CH>
; __device__ __forceinline__ void tile_load(LAS unsigned char* tile, const bf16_t* src, int ld, int tid) {
; #pragma unroll
;     for (int u = 0; u < ROWS * CH / 512; ++u) { const int i = tid + 512 * u, row = i / CH, ch = i % CH;
;         *(LAS u32x4*)(tile + off_b((unsigned)row, (unsigned)ch)) = *(const u32x4*)(src + (size_t)row * ld + ch * 8); }
; }
; __device__ __forceinline__ void phase_scan(const Params& P, int tid) {
;     ...
;                 for (int j = 0; j < 16; ++j) { u32x2 o; o.x = cvt_pk_bf16(S[0], S[1]); o.y = cvt_pk_bf16(S[2], S[3]);
;                     S[0] = cd * S[0] + bflo(d[j].x); S[1] = cd * S[1] + bfhi(d[j].x); S[2] = cd * S[2] + bflo(d[j].y); S[3] = cd * S[3] + bfhi(d[j].y);
;                     *(u32x2*)(sp + (size_t)(n0 + j) * (5 * 8192)) = o; }
;             }
	v_cvt_pk_bf16_f32 v12, v2, v3
	v_cvt_pk_bf16_f32 v13, v4, v5
	v_lshlrev_b32_e32 v6, 16, v72
	v_and_b32_e32 v7, 0xffff0000, v72
	v_lshlrev_b32_e32 v8, 16, v73
	v_and_b32_e32 v9, 0xffff0000, v73
	v_pk_fma_f32 v[2:3], v[10:11], v[2:3], v[6:7]
	v_pk_fma_f32 v[4:5], v[10:11], v[4:5], v[8:9]
	global_store_dwordx2 v0, v[12:13], s[40:41]
	s_add_u32 s40, s40, 0x14000
	s_addc_u32 s41, s41, 0
	s_waitcnt vmcnt(33)
	v_cvt_pk_bf16_f32 v14, v2, v3
	v_cvt_pk_bf16_f32 v15, v4, v5
	v_lshlrev_b32_e32 v6, 16, v74
	v_and_b32_e32 v7, 0xffff0000, v74
	v_lshlrev_b32_e32 v8, 16, v75
	v_and_b32_e32 v9, 0xffff0000, v75
	v_pk_fma_f32 v[2:3], v[10:11], v[2:3], v[6:7]
	v_pk_fma_f32 v[4:5], v[10:11], v[4:5], v[8:9]
	global_store_dwordx2 v0, v[14:15], s[40:41]
	s_add_u32 s40, s40, 0x14000
	s_addc_u32 s41, s41, 0
	s_waitcnt vmcnt(32)
	v_cvt_pk_bf16_f32 v12, v2, v3
	v_cvt_pk_bf16_f32 v13, v4, v5
	v_lshlrev_b32_e32 v6, 16, v76
	v_and_b32_e32 v7, 0xffff0000, v76
	v_lshlrev_b32_e32 v8, 16, v77
	v_and_b32_e32 v9, 0xffff0000, v77
	v_pk_fma_f32 v[2:3], v[10:11], v[2:3], v[6:7]
	v_pk_fma_f32 v[4:5], v[10:11], v[4:5], v[8:9]
	global_store_dwordx2 v0, v[12:13], s[40:41]
	s_add_u32 s40, s40, 0x14000
	s_addc_u32 s41, s41, 0
	s_waitcnt vmcnt(31)
	v_cvt_pk_bf16_f32 v14, v2, v3
	v_cvt_pk_bf16_f32 v15, v4, v5
	v_lshlrev_b32_e32 v6, 16, v78
	v_and_b32_e32 v7, 0xffff0000, v78
	v_lshlrev_b32_e32 v8, 16, v79
	v_and_b32_e32 v9, 0xffff0000, v79
	v_pk_fma_f32 v[2:3], v[10:11], v[2:3], v[6:7]
	v_pk_fma_f32 v[4:5], v[10:11], v[4:5], v[8:9]
	global_store_dwordx2 v0, v[14:15], s[40:41]
	s_add_u32 s40, s40, 0x14000
	s_addc_u32 s41, s41, 0
.Lscan_done:
.LBB0_139:
	s_or_b64 exec, exec, s[12:13]
	s_waitcnt vmcnt(0)
	v_ashrrev_i32_e32 v0, 31, v150
	v_lshrrev_b32_e32 v0, 28, v0
	v_add_u32_e32 v1, v150, v0
	v_ashrrev_i32_e32 v0, 4, v1
	v_and_b32_e32 v1, -16, v1
	v_sub_u32_e32 v2, v150, v1
	v_ashrrev_i32_e32 v1, 31, v0
	v_lshlrev_b64 v[96:97], 8, v[0:1]
	v_lshlrev_b32_e32 v1, 2, v0
	v_lshlrev_b32_e32 v9, 8, v0
	v_and_b32_e32 v1, 12, v1
	v_bfe_u32 v0, v0, 2, 2
	v_bitop3_b32 v0, v1, v2, v0 bitop3:0x36
	v_add_u32_e32 v151, 0x200, v150
	v_lshl_add_u32 v10, v0, 4, 0
	v_ashrrev_i32_e32 v0, 31, v151
	v_lshrrev_b32_e32 v0, 28, v0
	v_add_u32_e32 v1, v151, v0
	v_ashrrev_i32_e32 v0, 4, v1
	v_and_b32_e32 v1, -16, v1
	v_lshlrev_b32_e32 v98, 3, v2
	v_sub_u32_e32 v2, v151, v1
	v_ashrrev_i32_e32 v1, 31, v0
	v_lshlrev_b64 v[100:101], 8, v[0:1]
	v_lshlrev_b32_e32 v1, 2, v0
	v_lshlrev_b32_e32 v11, 8, v0
	v_and_b32_e32 v1, 12, v1
	v_bfe_u32 v0, v0, 2, 2
	v_bitop3_b32 v0, v1, v2, v0 bitop3:0x36
	v_add_u32_e32 v1, 0x400, v150
	v_lshl_add_u32 v12, v0, 4, 0
	v_ashrrev_i32_e32 v0, 31, v1
	v_lshrrev_b32_e32 v0, 28, v0
	v_lshlrev_b32_e32 v102, 3, v2
	v_add_u32_e32 v2, v1, v0
	v_ashrrev_i32_e32 v0, 4, v2
	v_and_b32_e32 v2, -16, v2
	v_sub_u32_e32 v2, v1, v2
	v_ashrrev_i32_e32 v1, 31, v0
	v_lshlrev_b64 v[104:105], 8, v[0:1]
	v_lshlrev_b32_e32 v1, 2, v0
	v_lshlrev_b32_e32 v13, 8, v0
	v_and_b32_e32 v1, 12, v1
	v_bfe_u32 v0, v0, 2, 2
	v_bitop3_b32 v0, v1, v2, v0 bitop3:0x36
	v_add_u32_e32 v1, 0x600, v150
	v_lshl_add_u32 v14, v0, 4, 0
	v_ashrrev_i32_e32 v0, 31, v1
	v_lshrrev_b32_e32 v0, 28, v0
	v_lshlrev_b32_e32 v106, 3, v2
	v_add_u32_e32 v2, v1, v0
	v_ashrrev_i32_e32 v0, 4, v2
	v_and_b32_e32 v2, -16, v2
	v_sub_u32_e32 v2, v1, v2
	v_ashrrev_i32_e32 v1, 31, v0
	v_lshlrev_b64 v[108:109], 8, v[0:1]
	v_lshlrev_b32_e32 v1, 2, v0
	v_lshlrev_b32_e32 v15, 8, v0
	v_and_b32_e32 v1, 12, v1
	v_bfe_u32 v0, v0, 2, 2
	v_bitop3_b32 v0, v1, v2, v0 bitop3:0x36
	v_add_u32_e32 v1, 0x800, v150
	v_lshl_add_u32 v16, v0, 4, 0
	v_ashrrev_i32_e32 v0, 31, v1
	v_lshrrev_b32_e32 v0, 28, v0
	v_lshlrev_b32_e32 v110, 3, v2
	v_add_u32_e32 v2, v1, v0
	v_ashrrev_i32_e32 v0, 4, v2
	v_and_b32_e32 v2, -16, v2
	v_sub_u32_e32 v2, v1, v2
	v_ashrrev_i32_e32 v1, 31, v0
	v_lshlrev_b64 v[112:113], 8, v[0:1]
	v_lshlrev_b32_e32 v1, 2, v0
	v_lshlrev_b32_e32 v17, 8, v0
	v_and_b32_e32 v1, 12, v1
	v_bfe_u32 v0, v0, 2, 2
	v_bitop3_b32 v0, v1, v2, v0 bitop3:0x36
	v_add_u32_e32 v1, 0xa00, v150
	v_lshl_add_u32 v18, v0, 4, 0
	v_ashrrev_i32_e32 v0, 31, v1
	v_lshrrev_b32_e32 v0, 28, v0
	v_lshlrev_b32_e32 v114, 3, v2
	v_add_u32_e32 v2, v1, v0
	v_ashrrev_i32_e32 v0, 4, v2
	v_and_b32_e32 v2, -16, v2
	v_sub_u32_e32 v2, v1, v2
	v_ashrrev_i32_e32 v1, 31, v0
	v_lshlrev_b64 v[116:117], 8, v[0:1]
	v_lshlrev_b32_e32 v1, 2, v0
	v_lshlrev_b32_e32 v19, 8, v0
	v_and_b32_e32 v1, 12, v1
	v_bfe_u32 v0, v0, 2, 2
	v_bitop3_b32 v0, v1, v2, v0 bitop3:0x36
	v_add_u32_e32 v1, 0xc00, v150
	v_lshl_add_u32 v20, v0, 4, 0
	v_ashrrev_i32_e32 v0, 31, v1
	v_lshrrev_b32_e32 v0, 28, v0
	v_lshlrev_b32_e32 v118, 3, v2
	v_add_u32_e32 v2, v1, v0
	v_ashrrev_i32_e32 v0, 4, v2
	v_and_b32_e32 v2, -16, v2
	v_sub_u32_e32 v2, v1, v2
	v_ashrrev_i32_e32 v1, 31, v0
	v_lshlrev_b64 v[120:121], 8, v[0:1]
	v_lshlrev_b32_e32 v1, 2, v0
	v_lshlrev_b32_e32 v21, 8, v0
	v_and_b32_e32 v1, 12, v1
	v_bfe_u32 v0, v0, 2, 2
	v_lshlrev_b32_e32 v7, 2, v150
	v_bfe_u32 v8, v150, 4, 2
	v_and_b32_e32 v192, 15, v150
	v_bitop3_b32 v0, v1, v2, v0 bitop3:0x36
	v_add_u32_e32 v1, 0xe00, v150
; #define LAS __attribute__((address_space(3)))
; __device__ __forceinline__ unsigned row_addr(int lane, int s) { return off_b((unsigned)(lane & 15), (unsigned)(4 * s + (lane >> 4))); }
; __device__ __forceinline__ void b_item(const Params& P, int layer, LAS unsigned char* lds, int item, int tid) {
;     const int b = item / 320, rem = item % 320, h = rem / 64, m = rem % 64, w = tid >> 6, lane = tid & 63;
;     const int qc = w >> 1, th = w & 1, g = lane >> 4, c15 = lane & 15;
;     const bf16_t* proj = (const bf16_t*)(P.ws + WS_PROJ);
;     const size_t tok0 = (size_t)b * SEQ + (size_t)m * 256;
;     LAS unsigned char* Qt = lds + 0; LAS unsigned char* KV = lds + 65536; LAS float* bias = (LAS float*)(lds + 131072);
;     tile_load<256, 16>(Qt, pjp(proj, BQ, 128, h, tok0), 128, tid);
;     for (int i = tid; i < 257; i += 512) bias[i] = P.rel_bias[(size_t)(layer * 5 + h) * 257 + i];
;     const int jst = (8 - 4 * m) > 0 ? (8 - 4 * m) : 0;
;     const long krow = (long)b * SEQ + (long)(4 * m - 8) * 64;
;     const bf16_t* kbase = pjp(proj, BKC, 128, h, 0) + krow * 128; const bf16_t* vbase = pjp(proj, BV, 128, h, 0) + krow * 128;
;     unsigned soff[2];
; #pragma unroll
;     for (int u = 0; u < 2; ++u) { const unsigned i = tid + 512 * u, row = i >> 4, ch = (i & 15) ^ (((row & 3u) << 2) | ((row >> 2) & 3u)); soff[u] = row * 128 + ch * 8; }
;     const unsigned ldsw = (unsigned)__builtin_amdgcn_readfirstlane(w) * 1024u;
;     ...
;     B_DMA(jst, 0);
;     __syncthreads();
;     LAS unsigned char* Qw = Qt + 4096 * (qc * 4 + th * 2);
;     float mrun[2] = {-1e30f, -1e30f}, lrun[2] = {0.f, 0.f}; const float bfar = bias[256];
;     unsigned kaddr[4], vaddr[8];
; #pragma unroll
;     for (int kk = 0; kk < 4; ++kk) kaddr[kk] = row_addr(lane, kk);
; #pragma unroll
;     for (int vb = 0; vb < 8; ++vb) vaddr[vb] = tr_addr<true>(lane, vb);
	v_and_b32_e32 v7, 12, v7
	v_bfe_u32 v25, v150, 2, 2
	v_lshl_add_u32 v22, v0, 4, 0
	v_ashrrev_i32_e32 v0, 31, v1
	v_lshlrev_b32_e32 v6, 8, v192
	v_bitop3_b32 v26, v7, v8, v25 bitop3:0x36
	v_lshrrev_b32_e32 v0, 28, v0
	v_lshl_or_b32 v193, v26, 4, v6
	v_or_b32_e32 v26, 4, v8
	v_lshlrev_b32_e32 v122, 3, v2
	v_add_u32_e32 v2, v1, v0
	v_bitop3_b32 v26, v7, v26, v25 bitop3:0x36
	v_ashrrev_i32_e32 v0, 4, v2
	v_and_b32_e32 v2, -16, v2
	v_lshl_or_b32 v194, v26, 4, v6
	v_or_b32_e32 v26, 8, v8
	v_readlane_b32 s40, v247, 14
	v_sub_u32_e32 v2, v1, v2
	v_ashrrev_i32_e32 v1, 31, v0
	v_bitop3_b32 v26, v7, v26, v25 bitop3:0x36
	v_readlane_b32 s50, v247, 24
	v_readlane_b32 s0, v247, 48
	v_lshlrev_b64 v[124:125], 8, v[0:1]
	v_lshlrev_b32_e32 v1, 2, v0
	v_lshl_or_b32 v195, v26, 4, v6
	v_or_b32_e32 v26, 12, v8
	v_readlane_b32 s51, v247, 25
	v_readlane_b32 s1, v247, 49
	s_add_u32 s8, s50, s0
	v_lshlrev_b32_e32 v23, 8, v0
	v_and_b32_e32 v1, 12, v1
	v_bfe_u32 v0, v0, 2, 2
	v_lshlrev_b32_e32 v4, 3, v150
	v_bitop3_b32 v7, v7, v26, v25 bitop3:0x36
	s_addc_u32 s9, s51, s1
	s_ashr_i32 s85, s84, 31
	v_lshlrev_b32_e32 v126, 3, v2
	v_bitop3_b32 v0, v1, v2, v0 bitop3:0x36
	v_and_b32_e32 v2, 0xffffff80, v4
	v_lshl_or_b32 v196, v7, 4, v6
	v_bfe_u32 v6, v150, 1, 1
	v_lshlrev_b32_e32 v7, 6, v150
	v_and_b32_e32 v25, 12, v150
	v_and_b32_e32 v4, 8, v4
	s_lshl_b64 s[0:1], s[84:85], 2
	v_or_b32_e32 v26, v8, v25
	v_and_or_b32 v197, v7, s92, v4
	v_bitop3_b32 v4, v8, v6, v25 bitop3:0x36
	s_add_u32 s0, s4, s0
	v_lshlrev_b32_e32 v198, 4, v4
	v_bitop3_b32 v4, v6, v26, 2 bitop3:0x36
	v_readlane_b32 s48, v247, 22
	s_addc_u32 s1, s5, s1
	v_lshlrev_b32_e32 v199, 4, v4
	v_bitop3_b32 v4, v6, v26, 4 bitop3:0x36
	v_readlane_b32 s49, v247, 23
	s_add_u32 s48, s0, 0x33983800
	v_lshlrev_b32_e32 v200, 4, v4
	v_bitop3_b32 v4, v6, v26, 6 bitop3:0x36
	s_addc_u32 s49, s1, 0
	v_lshlrev_b32_e32 v201, 4, v4
	v_bitop3_b32 v4, v6, v26, 8 bitop3:0x36
	v_ashrrev_i32_e32 v190, 6, v150
	s_add_u32 s60, s4, 0x18c00000
	v_lshlrev_b32_e32 v202, 4, v4
	v_bitop3_b32 v4, v6, v26, 10 bitop3:0x36
	v_ashrrev_i32_e32 v191, 7, v150
	v_and_b32_e32 v5, 1, v190
	s_addc_u32 s61, s5, 0
	v_lshlrev_b32_e32 v203, 4, v4
	v_bitop3_b32 v4, v6, v26, 12 bitop3:0x36
	s_add_u32 s39, s4, 0x1dc00000
	v_lshlrev_b32_e32 v204, 4, v4
	v_bitop3_b32 v4, v6, v26, 14 bitop3:0x36
	v_lshlrev_b32_e32 v25, 5, v5
	v_lshlrev_b32_e32 v6, 14, v191
	v_lshlrev_b32_e32 v5, 13, v5
	v_lshl_add_u32 v24, v0, 4, 0
	s_addc_u32 s62, s5, 0
	v_lshrrev_b32_e32 v0, 2, v150
	v_add3_u32 v206, 0, v6, v5
	v_max_i32_e32 v5, 0xffffff01, v150
	v_readlane_b32 s42, v247, 16
	v_readlane_b32 s43, v247, 17
	s_movk_i32 s0, 0x101
	v_bfe_u32 v1, v150, 6, 2
	v_and_b32_e32 v0, 12, v0
	s_add_u32 s63, s4, 0x1b400000
	v_sub_u32_e32 v5, v5, v150
	v_cmp_gt_i32_e64 s[42:43], s0, v150
	v_bitop3_b32 v0, v0, v192, v1 bitop3:0x36
	s_addc_u32 s64, s5, 0
	s_add_i32 s0, s94, 4
	v_add_u32_e32 v5, 0x1ff, v5
	v_lshl_or_b32 v0, v0, 3, v2
	v_lshrrev_b32_e32 v2, 2, v151
	s_cmp_lt_u32 s0, 11
	v_lshrrev_b32_e32 v6, 9, v5
	v_and_b32_e32 v2, 12, v2
	s_cselect_b32 s0, s93, 0x33984000
	v_add_u32_e32 v6, 1, v6
	v_readlane_b32 s44, v247, 18
	v_readlane_b32 s45, v247, 19
	v_readlane_b32 s46, v247, 20
	v_readlane_b32 s47, v247, 21
	v_bitop3_b32 v1, v2, v192, v1 bitop3:0x36
	v_lshlrev_b32_e32 v2, 3, v151
	s_add_u32 s18, s4, s0
	s_movk_i32 s0, 0x1ff
	v_and_b32_e32 v208, 0xfffffe, v6
	v_lshlrev_b32_e32 v136, 3, v8
	v_and_b32_e32 v2, 0xffffff80, v2
	v_lshlrev_b32_e32 v152, 6, v191
	v_cmp_lt_u32_e64 s[44:45], s0, v5
	v_cmp_ne_u32_e64 s[46:47], v6, v208
	v_lshl_add_u64 v[6:7], s[4:5], 0, v[136:137]
	s_mov_b64 s[0:1], 0x20400000
	v_readlane_b32 s41, v247, 15
	v_lshl_or_b32 v2, v1, 3, v2
	v_mov_b32_e32 v1, v137
	v_mov_b32_e32 v3, v137
	v_lshlrev_b32_e32 v205, 4, v4
	v_lshlrev_b32_e32 v4, 2, v8
	v_lshl_add_u64 v[156:157], v[6:7], 0, s[0:1]
	v_readlane_b32 s0, v247, 7
	v_or_b32_e32 v5, v152, v25
	v_cmp_eq_u32_e64 s[40:41], 0, v150
	v_ashrrev_i32_e32 v99, 31, v98
	v_ashrrev_i32_e32 v103, 31, v102
	v_ashrrev_i32_e32 v107, 31, v106
	v_ashrrev_i32_e32 v111, 31, v110
	v_ashrrev_i32_e32 v115, 31, v114
	v_ashrrev_i32_e32 v119, 31, v118
	v_ashrrev_i32_e32 v123, 31, v122
	v_ashrrev_i32_e32 v127, 31, v126
	v_add_u32_e32 v207, 8, v191
	v_ashrrev_i32_e32 v153, 31, v152
	s_addc_u32 s19, s5, 0
	v_or_b32_e32 v154, v25, v192
	v_lshl_add_u32 v209, v208, 9, v150
	v_add_u32_e32 v210, s0, v189
	v_sub_u32_e32 v211, v5, v4
	v_mad_i32_i24 v212, v8, -4, v5
	v_add_u32_e32 v213, v10, v9
	v_add_u32_e32 v214, v12, v11
	v_add_u32_e32 v215, v14, v13
	v_add_u32_e32 v216, v16, v15
	v_add_u32_e32 v217, v18, v17
	v_add_u32_e32 v218, v20, v19
	v_add_u32_e32 v219, v22, v21
	v_add_u32_e32 v220, v24, v23
	v_lshlrev_b32_e32 v136, 1, v4
	v_lshlrev_b64 v[158:159], 1, v[0:1]
	v_lshlrev_b64 v[160:161], 1, v[2:3]
	v_readlane_b32 s52, v247, 26
	v_readlane_b32 s53, v247, 27
	v_readlane_b32 s54, v247, 28
	v_readlane_b32 s55, v247, 29
	s_and_saveexec_b64 s[0:1], s[40:41]
	s_cbranch_execz .Lbq_pre_skip
	v_mov_b32_e32 v246, 1
	global_atomic_add v246, v137, v246, s[48:49] sc0
	s_waitcnt vmcnt(0)

; #define LAS __attribute__((address_space(3)))
; __device__ __forceinline__ void swz_put(LAS unsigned char* reg, int i, u32x4 v) { *(LAS u32x4*)(reg + off_b((unsigned)(i >> 4), (unsigned)(i & 15))) = v; }
; __device__ __forceinline__ float c_gl2(int h) { return log2f(1.f - exp2f(-5.f - (float)h)); }
; __device__ __forceinline__ void c1_phase(const Params& P, LAS unsigned char* lds, int tid) {
;     const int w = tid >> 6, lane = tid & 63, ip = tid & 15, i0 = 2 * ip, r0 = tid >> 4, G = gridDim.x;
;     C1Regs R; int it = blockIdx.x; if (it < 2560) c1_load(R, P, it, tid);
;     for (; it < 2560; it += G) {
;         const int cidx = it / 5, h = it % 5; const float gl2 = c_gl2(h);
;         *(LAS u32x4*)(lds + R_Q + (tid >> 3) * 256 + (tid & 7) * 16) = R.kq;
; #pragma unroll
;         for (int u = 0; u < 2; ++u) swz_put(lds + R_V, tid + 512 * u, R.v[u]);
;         f32x4 cs[2];
; #pragma unroll
;         for (int u = 0; u < 2; ++u) cs[u] = R.cs[u];
;         __syncthreads();
;         if (it + G < 2560) c1_load(R, P, it + G, tid);
.LBB0_219:
	s_mul_hi_i32 s0, s12, 0x66666667
	s_lshr_b32 s1, s0, 31
	s_ashr_i32 s0, s0, 1
	s_add_i32 s0, s0, s1
	s_mul_i32 s0, s0, 5
	s_sub_i32 s0, s12, s0
	v_cvt_f32_i32_e32 v65, s0
	ds_write_b128 v47, v[0:3] offset:16384
	ds_write_b128 v48, v[4:7] offset:49152
	ds_write_b128 v51, v[8:11] offset:49152
	v_sub_f32_e32 v65, 0xc0a00000, v65
	v_cmp_gt_f32_e32 vcc, s95, v65
	s_and_b64 s[0:1], vcc, exec
	s_cselect_b32 s0, 0xffffffc0, 0
	v_cndmask_b32_e32 v66, 0, v185, vcc
	v_add_f32_e32 v65, v65, v66
	v_exp_f32_e32 v65, v65
	s_waitcnt lgkmcnt(0)
	s_barrier
	v_ldexp_f32 v65, v65, s0
	v_sub_f32_e32 v65, 1.0, v65
	v_cmp_gt_f32_e64 s[0:1], s77, v65
	s_and_b64 s[8:9], s[0:1], exec
	s_cselect_b32 s9, 32, 0
	v_readlane_b32 s10, v248, 59
	s_and_b32 s11, s12, 0xff
	s_cmp_ge_u32 s10, 0x88
	s_cbranch_scc1 .Lc1_bblk
	s_cmp_ge_u32 s11, 0x88
	s_cbranch_scc1 .Lc1_extra
	s_add_i32 s8, s12, 0x100
	s_cmpk_gt_i32 s8, 0x9ff
	s_cbranch_scc0 .Lc1_nx_done
	s_mov_b32 s13, s10
	s_branch .Lc1_mk
.Lc1_extra:
	s_lshr_b32 s13, s12, 8
	s_sub_u32 s13, s13, 6
	s_mul_i32 s13, s13, 0x78
	s_add_u32 s13, s13, s11
.Lc1_mk:
	s_cmp_ge_u32 s13, 0x1e0
	s_cbranch_scc1 .Lc1_nx_done
	s_mul_i32 s8, s13, 0x223
	s_lshr_b32 s8, s8, 16
	s_mul_i32 s11, s8, 0x78
	s_sub_u32 s11, s13, s11
	s_add_u32 s8, s8, 6
	s_lshl_b32 s8, s8, 8
	s_add_u32 s8, s8, s11
	s_add_u32 s8, s8, 0x88
	s_cmp_eq_u32 s8, 0
	s_branch .Lc1_nx_done
.Lc1_bblk:
	s_add_i32 s8, s12, 0x100
	s_cmp_ge_u32 s8, 0x688
.Lc1_nx_done:
	s_cselect_b64 s[14:15], -1, 0
	s_and_b64 vcc, exec, s[14:15]
	s_cbranch_vccnz .LBB0_218
	s_mul_hi_i32 s10, s8, 0x66666667
	s_lshr_b32 s11, s10, 31
	s_ashr_i32 s10, s10, 1
	s_add_i32 s11, s10, s11
	s_mul_i32 s10, s11, -5
	s_add_i32 s10, s8, s10
	s_lshl_b32 s13, s11, 6
	v_add_u32_e32 v0, s13, v49
	s_ashr_i32 s11, s10, 31
	v_add_u32_e32 v2, s13, v50
	v_add_u32_e32 v8, s13, v44
	v_ashrrev_i32_e32 v1, 31, v0
	s_lshl_b64 s[10:11], s[10:11], 15
	v_ashrrev_i32_e32 v3, 31, v2
	v_ashrrev_i32_e32 v9, 31, v8
	v_lshl_add_u64 v[0:1], s[10:11], 0, v[0:1]
	v_lshl_add_u64 v[2:3], s[10:11], 0, v[2:3]
	v_lshl_add_u64 v[8:9], s[10:11], 0, v[8:9]
	s_and_b32 s10, s13, 0x3fc0
	v_add_u32_e32 v10, s10, v50
	v_ashrrev_i32_e32 v11, 31, v10
	v_lshlrev_b64 v[0:1], 7, v[0:1]
	v_lshlrev_b64 v[2:3], 8, v[2:3]
	v_lshlrev_b64 v[8:9], 8, v[8:9]
	v_lshlrev_b64 v[10:11], 8, v[10:11]
	v_lshl_add_u64 v[0:1], v[40:41], 0, v[0:1]
	v_lshl_add_u64 v[4:5], v[28:29], 0, v[2:3]
	v_lshl_add_u64 v[8:9], v[28:29], 0, v[8:9]
	v_lshl_add_u64 v[16:17], v[30:31], 0, v[10:11]
	global_load_dwordx4 v[0:3], v[0:1], off
	s_nop 0
	global_load_dwordx4 v[4:7], v[4:5], off
	s_nop 0
	global_load_dwordx4 v[8:11], v[8:9], off
	s_nop 0
	global_load_dwordx4 v[12:15], v[16:17], off
	v_add_co_u32_e32 v16, vcc, 0x2000, v16
	s_nop 1
	v_addc_co_u32_e32 v17, vcc, 0, v17, vcc
	global_load_dwordx4 v[16:19], v[16:17], off
	s_branch .LBB0_218
